# GEMM k-tiles 1..15 via direct HBM->LDS loads into an unpadded XOR-swizzled LDS image (no staging registers or ds_write in the k-loop); attention A/D softmax: scalar fma/add instead of packed
# speedup vs baseline: 1.0289x; 1.0289x over previous
.LBB0_31:
	s_andn2_b64 vcc, exec, s[0:1]
	s_cbranch_vccnz .LBB0_45
	s_load_dword s6, s[46:47], 0x0
	v_readlane_b32 s1, v254, 12
	s_ashr_i32 s3, s1, 3
	s_waitcnt lgkmcnt(0)
	s_and_b32 s0, s6, -8
	s_cmp_ge_i32 s1, s0
	s_cselect_b64 s[0:1], -1, 0
	s_cmpk_gt_i32 s3, 0xbf
	s_cselect_b64 s[4:5], -1, 0
	s_or_b64 s[0:1], s[4:5], s[0:1]
	s_and_b64 vcc, exec, s[0:1]
	s_cbranch_vccnz .LBB0_45
	s_add_u32 s0, s62, 0x14f5000
	v_ashrrev_i32_e32 v105, 1, v146
	s_addc_u32 s1, s63, 0
	v_and_b32_e32 v3, 31, v146
	v_bfe_u32 v4, v146, 5, 1
	s_waitcnt vmcnt(0)
	v_lshlrev_b32_e32 v0, 2, v146
	v_and_b32_e32 v6, 0xffffffc0, v105
	s_add_u32 s4, s62, 0xd00000
	v_readlane_b32 s7, v254, 12
	v_bfe_u32 v2, v146, 6, 1
	v_and_b32_e32 v5, 4, v0
	s_movk_i32 s8, 0x90
	v_or_b32_e32 v7, v6, v3
	v_lshlrev_b32_e32 v0, 4, v4
	s_addc_u32 s5, s63, 0
	s_and_b32 s14, s7, 7
	s_lshr_b32 s15, s6, 3
	v_lshl_or_b32 v8, v2, 6, v3
	v_mad_u64_u32 v[98:99], s[6:7], v7, s8, v[0:1]
	v_mad_u32_u24 v99, v8, s8, v0
	v_lshlrev_b32_e32 v0, 2, v3
	v_ashrrev_i32_e32 v105, 3, v146
	v_lshlrev_b32_e32 v110, 7, v105
	v_lshl_or_b32 v0, v2, 8, v0
	v_lshl_or_b32 v2, v4, 2, v6
	s_movk_i32 s8, 0x210
	v_mad_u64_u32 v[100:101], s[6:7], v2, s8, v[0:1]
	v_lshlrev_b32_e32 v0, 3, v146
	v_and_b32_e32 v0, 0x78, v0
	v_lshlrev_b32_e32 v4, 2, v0
	v_lshlrev_b32_e32 v0, 1, v0
	v_lshl_add_u64 v[2:3], s[62:63], 0, v[0:1]
	s_mov_b64 s[6:7], 0x44f5000
	v_lshl_add_u64 v[102:103], v[2:3], 0, s[6:7]
	v_add_u32_e32 v2, 0x100, v146
	v_add_u32_e32 v3, 0x200, v146
	v_add_u32_e32 v6, 0x300, v146
	v_add_u32_e32 v7, 0x400, v146
	v_add_u32_e32 v8, 0x500, v146
	v_add_u32_e32 v9, 0x600, v146
	v_add_u32_e32 v10, 0x700, v146
	v_and_b32_e32 v111, 7, v146
	v_lshlrev_b32_e32 v111, 4, v111
	v_ashrrev_i32_e32 v101, 4, v146
	v_ashrrev_i32_e32 v112, 4, v2
	v_ashrrev_i32_e32 v113, 4, v3
	v_ashrrev_i32_e32 v114, 4, v6
	v_ashrrev_i32_e32 v115, 4, v7
	v_ashrrev_i32_e32 v116, 4, v8
	v_ashrrev_i32_e32 v117, 4, v9
	v_ashrrev_i32_e32 v118, 4, v10
	v_mul_lo_u32 v0, v101, s8
	v_mul_lo_u32 v2, v112, s8
	v_mul_lo_u32 v3, v113, s8
	v_mul_lo_u32 v6, v114, s8
	v_mul_lo_u32 v7, v115, s8
	v_mul_lo_u32 v8, v116, s8
	v_mul_lo_u32 v9, v117, s8
	v_mul_lo_u32 v10, v118, s8
	v_bfe_u32 v104, v146, 4, 3
	v_lshlrev_b32_e32 v104, 4, v104
	v_xor_b32_e32 v104, v104, v111
	v_lshrrev_b32_e32 v104, 1, v104
	v_add_u32_e32 v5, 0x1000, v111
	v_add_u32_e32 v11, 0x2000, v111
	v_add_u32_e32 v12, 0x3000, v111
	s_mov_b64 s[8:9], 0
	s_mov_b32 s16, -1
	s_mov_b32 s17, 0
	v_add_u32_e32 v119, v110, v5
	v_add_u32_e32 v120, v110, v11
	v_add_u32_e32 v121, v110, v12
	v_add_u32_e32 v122, v4, v0
	v_add_u32_e32 v123, v4, v2
	v_add_u32_e32 v124, v4, v3
	v_add_u32_e32 v125, v4, v6
	v_add_u32_e32 v126, v4, v7
	v_add_u32_e32 v127, v4, v8
	v_add_u32_e32 v128, v4, v9
	v_add_u32_e32 v129, v4, v10
	s_branch .LBB0_35

.LBB0_39:
	s_lshl_b32 s18, s12, 7
	v_add_u32_e32 v2, s18, v105
	s_xor_b64 s[20:21], s[8:9], -1
	s_lshl_b32 s8, s13, 7
	v_ashrrev_i32_e32 v3, 31, v2
	v_lshlrev_b64 v[2:3], 11, v[2:3]
	v_add_u32_e32 v38, s8, v105
	s_lshl_b32 s98, s18, 11
	s_add_u32 s98, s0, s98
	s_addc_u32 s99, s1, 0
	s_lshl_b32 s100, s8, 11
	s_add_u32 s100, s4, s100
	s_addc_u32 s101, s5, 0
	s_mov_b64 s[12:13], -1
	s_andn2_b64 vcc, exec, s[20:21]
	v_lshl_add_u64 v[34:35], s[0:1], 0, v[2:3]
	v_ashrrev_i32_e32 v39, 31, v38
	v_lshlrev_b32_e32 v0, 1, v104
	s_cbranch_vccnz .LBB0_41
	v_lshlrev_b64 v[36:37], 11, v[38:39]
	v_lshl_add_u64 v[2:3], s[4:5], 0, v[36:37]
	v_lshl_add_u64 v[30:31], v[34:35], 0, v[0:1]
	v_lshl_add_u64 v[14:15], v[2:3], 0, v[0:1]
	v_lshl_add_u64 v[238:239], v[14:15], 0, s[56:57]
	v_lshl_add_u64 v[240:241], v[238:239], 0, s[56:57]
	v_lshl_add_u64 v[242:243], v[240:241], 0, s[56:57]
	v_lshl_add_u64 v[232:233], v[30:31], 0, s[56:57]
	v_lshl_add_u64 v[234:235], v[232:233], 0, s[56:57]
	v_lshl_add_u64 v[236:237], v[234:235], 0, s[56:57]
	global_load_dwordx4 v[2:5], v[242:243], off
	global_load_dwordx4 v[6:9], v[240:241], off
	global_load_dwordx4 v[10:13], v[238:239], off
	s_nop 0
	global_load_dwordx4 v[14:17], v[14:15], off
	s_nop 0
	global_load_dwordx4 v[18:21], v[236:237], off
	global_load_dwordx4 v[22:25], v[234:235], off
	global_load_dwordx4 v[26:29], v[232:233], off
	s_nop 0
	global_load_dwordx4 v[30:33], v[30:31], off
	s_mov_b64 s[12:13], 0

.LBB0_43:
	v_add_u32_e32 v130, v110, v111
	v_lshrrev_b32_e32 v148, 6, v146
	v_lshlrev_b32_e32 v148, 10, v148
	v_lshl_add_u32 v140, v105, 11, v0
	v_readfirstlane_b32 s32, v148
	v_add_u32_e32 v141, 0x10000, v140
	v_add_u32_e32 v142, 0x20000, v140
	v_add_u32_e32 v143, 0x30000, v140
	v_bfe_u32 v148, v146, 1, 3
	v_bfe_u32 v149, v146, 5, 1
	v_xor_b32_e32 v148, v148, v149
	v_lshlrev_b32_e32 v148, 4, v148
	v_and_b32_e32 v149, 31, v146
	v_lshrrev_b32_e32 v150, 7, v146
	v_lshl_add_u32 v150, v150, 6, v149
	v_lshl_add_u32 v132, v150, 7, v148
	v_bfe_u32 v150, v146, 6, 1
	v_lshl_add_u32 v150, v150, 6, v149
	v_lshl_add_u32 v136, v150, 7, v148
	v_xor_b32_e32 v133, 32, v132
	v_xor_b32_e32 v137, 32, v136
	v_xor_b32_e32 v134, 64, v132
	v_xor_b32_e32 v138, 64, v136
	v_xor_b32_e32 v135, 96, v132
	v_xor_b32_e32 v139, 96, v136
	s_add_u32 s98, s98, 0x80
	s_addc_u32 s99, s99, 0
	s_add_u32 s100, s100, 0x80
	s_addc_u32 s101, s101, 0
	s_add_u32 m0, s32, 0x8000
	s_nop 0
	global_load_lds_dwordx4 v140, s[98:99]
	s_add_u32 m0, s32, 0x9000
	s_nop 0
	global_load_lds_dwordx4 v141, s[98:99]
	s_add_u32 m0, s32, 0xa000
	s_nop 0
	global_load_lds_dwordx4 v142, s[98:99]
	s_add_u32 m0, s32, 0xb000
	s_nop 0
	global_load_lds_dwordx4 v143, s[98:99]
	s_add_u32 m0, s32, 0xc000
	s_nop 0
	global_load_lds_dwordx4 v140, s[100:101]
	s_add_u32 m0, s32, 0xd000
	s_nop 0
	global_load_lds_dwordx4 v141, s[100:101]
	s_add_u32 m0, s32, 0xe000
	s_nop 0
	global_load_lds_dwordx4 v142, s[100:101]
	s_add_u32 m0, s32, 0xf000
	s_nop 0
	global_load_lds_dwordx4 v143, s[100:101]
	s_add_u32 s98, s98, 0x80
	s_addc_u32 s99, s99, 0
	s_add_u32 s100, s100, 0x80
	s_addc_u32 s101, s101, 0
	s_waitcnt vmcnt(8)
	ds_write_b128 v130, v[30:33]
	ds_write_b128 v130, v[14:17] offset:16384
	ds_write_b128 v119, v[26:29]
	ds_write_b128 v119, v[10:13] offset:16384
	ds_write_b128 v120, v[22:25]
	ds_write_b128 v120, v[6:9] offset:16384
	ds_write_b128 v121, v[18:21]
	ds_write_b128 v121, v[2:5] offset:16384
	s_lshl_b32 s9, s16, 7
	s_and_b64 s[10:11], s[10:11], exec
	s_cselect_b32 s9, s9, -1
	s_waitcnt lgkmcnt(0)
	s_barrier
	ds_read_b128 v[168:171], v132
	ds_read_b128 v[172:175], v132 offset:4096
	ds_read_b128 v[176:179], v136 offset:16384
	ds_read_b128 v[180:183], v136 offset:20480
	ds_read_b128 v[184:187], v133
	ds_read_b128 v[188:191], v133 offset:4096
	ds_read_b128 v[192:195], v137 offset:16384
	ds_read_b128 v[196:199], v137 offset:20480
	s_waitcnt lgkmcnt(5)
	v_mfma_f32_32x32x16_bf16 v[34:49], v[168:171], v[176:179], 0
	s_waitcnt lgkmcnt(4)
	v_mfma_f32_32x32x16_bf16 v[50:65], v[168:171], v[180:183], 0
	v_mfma_f32_32x32x16_bf16 v[2:17], v[172:175], v[176:179], 0
	v_mfma_f32_32x32x16_bf16 v[18:33], v[172:175], v[180:183], 0
	ds_read_b128 v[168:171], v134
	ds_read_b128 v[172:175], v134 offset:4096
	ds_read_b128 v[176:179], v138 offset:16384
	ds_read_b128 v[180:183], v138 offset:20480
	s_waitcnt lgkmcnt(5)
	v_mfma_f32_32x32x16_bf16 v[34:49], v[184:187], v[192:195], v[34:49]
	s_waitcnt lgkmcnt(4)
	v_mfma_f32_32x32x16_bf16 v[50:65], v[184:187], v[196:199], v[50:65]
	v_mfma_f32_32x32x16_bf16 v[2:17], v[188:191], v[192:195], v[2:17]
	v_mfma_f32_32x32x16_bf16 v[18:33], v[188:191], v[196:199], v[18:33]
	ds_read_b128 v[184:187], v135
	ds_read_b128 v[188:191], v135 offset:4096
	ds_read_b128 v[192:195], v139 offset:16384
	ds_read_b128 v[196:199], v139 offset:20480
	s_waitcnt lgkmcnt(5)
	v_mfma_f32_32x32x16_bf16 v[34:49], v[168:171], v[176:179], v[34:49]
	s_waitcnt lgkmcnt(4)
	v_mfma_f32_32x32x16_bf16 v[50:65], v[168:171], v[180:183], v[50:65]
	v_mfma_f32_32x32x16_bf16 v[2:17], v[172:175], v[176:179], v[2:17]
	v_mfma_f32_32x32x16_bf16 v[18:33], v[172:175], v[180:183], v[18:33]
	s_waitcnt lgkmcnt(1)
	v_mfma_f32_32x32x16_bf16 v[34:49], v[184:187], v[192:195], v[34:49]
	s_waitcnt lgkmcnt(0)
	v_mfma_f32_32x32x16_bf16 v[50:65], v[184:187], v[196:199], v[50:65]
	v_mfma_f32_32x32x16_bf16 v[2:17], v[188:191], v[192:195], v[2:17]
	v_mfma_f32_32x32x16_bf16 v[18:33], v[188:191], v[196:199], v[18:33]
	s_waitcnt vmcnt(0) lgkmcnt(0)
	s_barrier
	ds_read_b128 v[168:171], v132 offset:32768
	ds_read_b128 v[172:175], v132 offset:36864
	ds_read_b128 v[176:179], v136 offset:49152
	ds_read_b128 v[180:183], v136 offset:53248
	ds_read_b128 v[184:187], v133 offset:32768
	ds_read_b128 v[188:191], v133 offset:36864
	ds_read_b128 v[192:195], v137 offset:49152
	ds_read_b128 v[196:199], v137 offset:53248
	s_mov_b32 m0, s32
	s_waitcnt lgkmcnt(5)
	v_mfma_f32_32x32x16_bf16 v[34:49], v[168:171], v[176:179], v[34:49]
	global_load_lds_dwordx4 v140, s[98:99]
	s_waitcnt lgkmcnt(4)
	v_mfma_f32_32x32x16_bf16 v[50:65], v[168:171], v[180:183], v[50:65]
	s_add_u32 m0, s32, 0x1000
	v_mfma_f32_32x32x16_bf16 v[2:17], v[172:175], v[176:179], v[2:17]
	global_load_lds_dwordx4 v141, s[98:99]
	v_mfma_f32_32x32x16_bf16 v[18:33], v[172:175], v[180:183], v[18:33]
	ds_read_b128 v[168:171], v134 offset:32768
	ds_read_b128 v[172:175], v134 offset:36864
	ds_read_b128 v[176:179], v138 offset:49152
	ds_read_b128 v[180:183], v138 offset:53248
	s_add_u32 m0, s32, 0x2000
	s_waitcnt lgkmcnt(5)
	v_mfma_f32_32x32x16_bf16 v[34:49], v[184:187], v[192:195], v[34:49]
	global_load_lds_dwordx4 v142, s[98:99]
	s_waitcnt lgkmcnt(4)
	v_mfma_f32_32x32x16_bf16 v[50:65], v[184:187], v[196:199], v[50:65]
	s_add_u32 m0, s32, 0x3000
	v_mfma_f32_32x32x16_bf16 v[2:17], v[188:191], v[192:195], v[2:17]
	global_load_lds_dwordx4 v143, s[98:99]
	v_mfma_f32_32x32x16_bf16 v[18:33], v[188:191], v[196:199], v[18:33]
	ds_read_b128 v[184:187], v135 offset:32768
	ds_read_b128 v[188:191], v135 offset:36864
	ds_read_b128 v[192:195], v139 offset:49152
	ds_read_b128 v[196:199], v139 offset:53248
	s_add_u32 m0, s32, 0x4000
	s_waitcnt lgkmcnt(5)
	v_mfma_f32_32x32x16_bf16 v[34:49], v[168:171], v[176:179], v[34:49]
	global_load_lds_dwordx4 v140, s[100:101]
	s_waitcnt lgkmcnt(4)
	v_mfma_f32_32x32x16_bf16 v[50:65], v[168:171], v[180:183], v[50:65]
	s_add_u32 m0, s32, 0x5000
	v_mfma_f32_32x32x16_bf16 v[2:17], v[172:175], v[176:179], v[2:17]
	global_load_lds_dwordx4 v141, s[100:101]
	v_mfma_f32_32x32x16_bf16 v[18:33], v[172:175], v[180:183], v[18:33]
	s_add_u32 m0, s32, 0x6000
	s_waitcnt lgkmcnt(1)
	v_mfma_f32_32x32x16_bf16 v[34:49], v[184:187], v[192:195], v[34:49]
	global_load_lds_dwordx4 v142, s[100:101]
	s_waitcnt lgkmcnt(0)
	v_mfma_f32_32x32x16_bf16 v[50:65], v[184:187], v[196:199], v[50:65]
	s_add_u32 m0, s32, 0x7000
	v_mfma_f32_32x32x16_bf16 v[2:17], v[188:191], v[192:195], v[2:17]
	global_load_lds_dwordx4 v143, s[100:101]
	v_mfma_f32_32x32x16_bf16 v[18:33], v[188:191], v[196:199], v[18:33]
	s_add_u32 s98, s98, 0x80
	s_addc_u32 s99, s99, 0
	s_add_u32 s100, s100, 0x80
	s_addc_u32 s101, s101, 0
	s_waitcnt vmcnt(0) lgkmcnt(0)
	s_barrier
	ds_read_b128 v[168:171], v132
	ds_read_b128 v[172:175], v132 offset:4096
	ds_read_b128 v[176:179], v136 offset:16384
	ds_read_b128 v[180:183], v136 offset:20480
	ds_read_b128 v[184:187], v133
	ds_read_b128 v[188:191], v133 offset:4096
	ds_read_b128 v[192:195], v137 offset:16384
	ds_read_b128 v[196:199], v137 offset:20480
	s_add_u32 m0, s32, 0x8000
	s_waitcnt lgkmcnt(5)
	v_mfma_f32_32x32x16_bf16 v[34:49], v[168:171], v[176:179], v[34:49]
	global_load_lds_dwordx4 v140, s[98:99]
	s_waitcnt lgkmcnt(4)
	v_mfma_f32_32x32x16_bf16 v[50:65], v[168:171], v[180:183], v[50:65]
	s_add_u32 m0, s32, 0x9000
	v_mfma_f32_32x32x16_bf16 v[2:17], v[172:175], v[176:179], v[2:17]
	global_load_lds_dwordx4 v141, s[98:99]
	v_mfma_f32_32x32x16_bf16 v[18:33], v[172:175], v[180:183], v[18:33]
	ds_read_b128 v[168:171], v134
	ds_read_b128 v[172:175], v134 offset:4096
	ds_read_b128 v[176:179], v138 offset:16384
	ds_read_b128 v[180:183], v138 offset:20480
	s_add_u32 m0, s32, 0xa000
	s_waitcnt lgkmcnt(5)
	v_mfma_f32_32x32x16_bf16 v[34:49], v[184:187], v[192:195], v[34:49]
	global_load_lds_dwordx4 v142, s[98:99]
	s_waitcnt lgkmcnt(4)
	v_mfma_f32_32x32x16_bf16 v[50:65], v[184:187], v[196:199], v[50:65]
	s_add_u32 m0, s32, 0xb000
	v_mfma_f32_32x32x16_bf16 v[2:17], v[188:191], v[192:195], v[2:17]
	global_load_lds_dwordx4 v143, s[98:99]
	v_mfma_f32_32x32x16_bf16 v[18:33], v[188:191], v[196:199], v[18:33]
	ds_read_b128 v[184:187], v135
	ds_read_b128 v[188:191], v135 offset:4096
	ds_read_b128 v[192:195], v139 offset:16384
	ds_read_b128 v[196:199], v139 offset:20480
	s_add_u32 m0, s32, 0xc000
	s_waitcnt lgkmcnt(5)
	v_mfma_f32_32x32x16_bf16 v[34:49], v[168:171], v[176:179], v[34:49]
	global_load_lds_dwordx4 v140, s[100:101]
	s_waitcnt lgkmcnt(4)
	v_mfma_f32_32x32x16_bf16 v[50:65], v[168:171], v[180:183], v[50:65]
	s_add_u32 m0, s32, 0xd000
	v_mfma_f32_32x32x16_bf16 v[2:17], v[172:175], v[176:179], v[2:17]
	global_load_lds_dwordx4 v141, s[100:101]
	v_mfma_f32_32x32x16_bf16 v[18:33], v[172:175], v[180:183], v[18:33]
	s_add_u32 m0, s32, 0xe000
	s_waitcnt lgkmcnt(1)
	v_mfma_f32_32x32x16_bf16 v[34:49], v[184:187], v[192:195], v[34:49]
	global_load_lds_dwordx4 v142, s[100:101]
	s_waitcnt lgkmcnt(0)
	v_mfma_f32_32x32x16_bf16 v[50:65], v[184:187], v[196:199], v[50:65]
	s_add_u32 m0, s32, 0xf000
	v_mfma_f32_32x32x16_bf16 v[2:17], v[188:191], v[192:195], v[2:17]
	global_load_lds_dwordx4 v143, s[100:101]
	v_mfma_f32_32x32x16_bf16 v[18:33], v[188:191], v[196:199], v[18:33]
	s_add_u32 s98, s98, 0x80
	s_addc_u32 s99, s99, 0
	s_add_u32 s100, s100, 0x80
	s_addc_u32 s101, s101, 0
	s_waitcnt vmcnt(0) lgkmcnt(0)
	s_barrier
	ds_read_b128 v[168:171], v132 offset:32768
	ds_read_b128 v[172:175], v132 offset:36864
	ds_read_b128 v[176:179], v136 offset:49152
	ds_read_b128 v[180:183], v136 offset:53248
	ds_read_b128 v[184:187], v133 offset:32768
	ds_read_b128 v[188:191], v133 offset:36864
	ds_read_b128 v[192:195], v137 offset:49152
	ds_read_b128 v[196:199], v137 offset:53248
	s_mov_b32 m0, s32
	s_waitcnt lgkmcnt(5)
	v_mfma_f32_32x32x16_bf16 v[34:49], v[168:171], v[176:179], v[34:49]
	global_load_lds_dwordx4 v140, s[98:99]
	s_waitcnt lgkmcnt(4)
	v_mfma_f32_32x32x16_bf16 v[50:65], v[168:171], v[180:183], v[50:65]
	s_add_u32 m0, s32, 0x1000
	v_mfma_f32_32x32x16_bf16 v[2:17], v[172:175], v[176:179], v[2:17]
	global_load_lds_dwordx4 v141, s[98:99]
	v_mfma_f32_32x32x16_bf16 v[18:33], v[172:175], v[180:183], v[18:33]
	ds_read_b128 v[168:171], v134 offset:32768
	ds_read_b128 v[172:175], v134 offset:36864
	ds_read_b128 v[176:179], v138 offset:49152
	ds_read_b128 v[180:183], v138 offset:53248
	s_add_u32 m0, s32, 0x2000
	s_waitcnt lgkmcnt(5)
	v_mfma_f32_32x32x16_bf16 v[34:49], v[184:187], v[192:195], v[34:49]
	global_load_lds_dwordx4 v142, s[98:99]
	s_waitcnt lgkmcnt(4)
	v_mfma_f32_32x32x16_bf16 v[50:65], v[184:187], v[196:199], v[50:65]
	s_add_u32 m0, s32, 0x3000
	v_mfma_f32_32x32x16_bf16 v[2:17], v[188:191], v[192:195], v[2:17]
	global_load_lds_dwordx4 v143, s[98:99]
	v_mfma_f32_32x32x16_bf16 v[18:33], v[188:191], v[196:199], v[18:33]
	ds_read_b128 v[184:187], v135 offset:32768
	ds_read_b128 v[188:191], v135 offset:36864
	ds_read_b128 v[192:195], v139 offset:49152
	ds_read_b128 v[196:199], v139 offset:53248
	s_add_u32 m0, s32, 0x4000
	s_waitcnt lgkmcnt(5)
	v_mfma_f32_32x32x16_bf16 v[34:49], v[168:171], v[176:179], v[34:49]
	global_load_lds_dwordx4 v140, s[100:101]
	s_waitcnt lgkmcnt(4)
	v_mfma_f32_32x32x16_bf16 v[50:65], v[168:171], v[180:183], v[50:65]
	s_add_u32 m0, s32, 0x5000
	v_mfma_f32_32x32x16_bf16 v[2:17], v[172:175], v[176:179], v[2:17]
	global_load_lds_dwordx4 v141, s[100:101]
	v_mfma_f32_32x32x16_bf16 v[18:33], v[172:175], v[180:183], v[18:33]
	s_add_u32 m0, s32, 0x6000
	s_waitcnt lgkmcnt(1)
	v_mfma_f32_32x32x16_bf16 v[34:49], v[184:187], v[192:195], v[34:49]
	global_load_lds_dwordx4 v142, s[100:101]
	s_waitcnt lgkmcnt(0)
	v_mfma_f32_32x32x16_bf16 v[50:65], v[184:187], v[196:199], v[50:65]
	s_add_u32 m0, s32, 0x7000
	v_mfma_f32_32x32x16_bf16 v[2:17], v[188:191], v[192:195], v[2:17]
	global_load_lds_dwordx4 v143, s[100:101]
	v_mfma_f32_32x32x16_bf16 v[18:33], v[188:191], v[196:199], v[18:33]
	s_add_u32 s98, s98, 0x80
	s_addc_u32 s99, s99, 0
	s_add_u32 s100, s100, 0x80
	s_addc_u32 s101, s101, 0
	s_waitcnt vmcnt(0) lgkmcnt(0)
	s_barrier
	ds_read_b128 v[168:171], v132
	ds_read_b128 v[172:175], v132 offset:4096
	ds_read_b128 v[176:179], v136 offset:16384
	ds_read_b128 v[180:183], v136 offset:20480
	ds_read_b128 v[184:187], v133
	ds_read_b128 v[188:191], v133 offset:4096
	ds_read_b128 v[192:195], v137 offset:16384
	ds_read_b128 v[196:199], v137 offset:20480
	s_add_u32 m0, s32, 0x8000
	s_waitcnt lgkmcnt(5)
	v_mfma_f32_32x32x16_bf16 v[34:49], v[168:171], v[176:179], v[34:49]
	global_load_lds_dwordx4 v140, s[98:99]
	s_waitcnt lgkmcnt(4)
	v_mfma_f32_32x32x16_bf16 v[50:65], v[168:171], v[180:183], v[50:65]
	s_add_u32 m0, s32, 0x9000
	v_mfma_f32_32x32x16_bf16 v[2:17], v[172:175], v[176:179], v[2:17]
	global_load_lds_dwordx4 v141, s[98:99]
	v_mfma_f32_32x32x16_bf16 v[18:33], v[172:175], v[180:183], v[18:33]
	ds_read_b128 v[168:171], v134
	ds_read_b128 v[172:175], v134 offset:4096
	ds_read_b128 v[176:179], v138 offset:16384
	ds_read_b128 v[180:183], v138 offset:20480
	s_add_u32 m0, s32, 0xa000
	s_waitcnt lgkmcnt(5)
	v_mfma_f32_32x32x16_bf16 v[34:49], v[184:187], v[192:195], v[34:49]
	global_load_lds_dwordx4 v142, s[98:99]
	s_waitcnt lgkmcnt(4)
	v_mfma_f32_32x32x16_bf16 v[50:65], v[184:187], v[196:199], v[50:65]
	s_add_u32 m0, s32, 0xb000
	v_mfma_f32_32x32x16_bf16 v[2:17], v[188:191], v[192:195], v[2:17]
	global_load_lds_dwordx4 v143, s[98:99]
	v_mfma_f32_32x32x16_bf16 v[18:33], v[188:191], v[196:199], v[18:33]
	ds_read_b128 v[184:187], v135
	ds_read_b128 v[188:191], v135 offset:4096
	ds_read_b128 v[192:195], v139 offset:16384
	ds_read_b128 v[196:199], v139 offset:20480
	s_add_u32 m0, s32, 0xc000
	s_waitcnt lgkmcnt(5)
	v_mfma_f32_32x32x16_bf16 v[34:49], v[168:171], v[176:179], v[34:49]
	global_load_lds_dwordx4 v140, s[100:101]
	s_waitcnt lgkmcnt(4)
	v_mfma_f32_32x32x16_bf16 v[50:65], v[168:171], v[180:183], v[50:65]
	s_add_u32 m0, s32, 0xd000
	v_mfma_f32_32x32x16_bf16 v[2:17], v[172:175], v[176:179], v[2:17]
	global_load_lds_dwordx4 v141, s[100:101]
	v_mfma_f32_32x32x16_bf16 v[18:33], v[172:175], v[180:183], v[18:33]
	s_add_u32 m0, s32, 0xe000
	s_waitcnt lgkmcnt(1)
	v_mfma_f32_32x32x16_bf16 v[34:49], v[184:187], v[192:195], v[34:49]
	global_load_lds_dwordx4 v142, s[100:101]
	s_waitcnt lgkmcnt(0)
	v_mfma_f32_32x32x16_bf16 v[50:65], v[184:187], v[196:199], v[50:65]
	s_add_u32 m0, s32, 0xf000
	v_mfma_f32_32x32x16_bf16 v[2:17], v[188:191], v[192:195], v[2:17]
	global_load_lds_dwordx4 v143, s[100:101]
	v_mfma_f32_32x32x16_bf16 v[18:33], v[188:191], v[196:199], v[18:33]
	s_add_u32 s98, s98, 0x80
	s_addc_u32 s99, s99, 0
	s_add_u32 s100, s100, 0x80
	s_addc_u32 s101, s101, 0
	s_waitcnt vmcnt(0) lgkmcnt(0)
	s_barrier
	ds_read_b128 v[168:171], v132 offset:32768
	ds_read_b128 v[172:175], v132 offset:36864
	ds_read_b128 v[176:179], v136 offset:49152
	ds_read_b128 v[180:183], v136 offset:53248
	ds_read_b128 v[184:187], v133 offset:32768
	ds_read_b128 v[188:191], v133 offset:36864
	ds_read_b128 v[192:195], v137 offset:49152
	ds_read_b128 v[196:199], v137 offset:53248
	s_mov_b32 m0, s32
	s_waitcnt lgkmcnt(5)
	v_mfma_f32_32x32x16_bf16 v[34:49], v[168:171], v[176:179], v[34:49]
	global_load_lds_dwordx4 v140, s[98:99]
	s_waitcnt lgkmcnt(4)
	v_mfma_f32_32x32x16_bf16 v[50:65], v[168:171], v[180:183], v[50:65]
	s_add_u32 m0, s32, 0x1000
	v_mfma_f32_32x32x16_bf16 v[2:17], v[172:175], v[176:179], v[2:17]
	global_load_lds_dwordx4 v141, s[98:99]
	v_mfma_f32_32x32x16_bf16 v[18:33], v[172:175], v[180:183], v[18:33]
	ds_read_b128 v[168:171], v134 offset:32768
	ds_read_b128 v[172:175], v134 offset:36864
	ds_read_b128 v[176:179], v138 offset:49152
	ds_read_b128 v[180:183], v138 offset:53248
	s_add_u32 m0, s32, 0x2000
	s_waitcnt lgkmcnt(5)
	v_mfma_f32_32x32x16_bf16 v[34:49], v[184:187], v[192:195], v[34:49]
	global_load_lds_dwordx4 v142, s[98:99]
	s_waitcnt lgkmcnt(4)
	v_mfma_f32_32x32x16_bf16 v[50:65], v[184:187], v[196:199], v[50:65]
	s_add_u32 m0, s32, 0x3000
	v_mfma_f32_32x32x16_bf16 v[2:17], v[188:191], v[192:195], v[2:17]
	global_load_lds_dwordx4 v143, s[98:99]
	v_mfma_f32_32x32x16_bf16 v[18:33], v[188:191], v[196:199], v[18:33]
	ds_read_b128 v[184:187], v135 offset:32768
	ds_read_b128 v[188:191], v135 offset:36864
	ds_read_b128 v[192:195], v139 offset:49152
	ds_read_b128 v[196:199], v139 offset:53248
	s_add_u32 m0, s32, 0x4000
	s_waitcnt lgkmcnt(5)
	v_mfma_f32_32x32x16_bf16 v[34:49], v[168:171], v[176:179], v[34:49]
	global_load_lds_dwordx4 v140, s[100:101]
	s_waitcnt lgkmcnt(4)
	v_mfma_f32_32x32x16_bf16 v[50:65], v[168:171], v[180:183], v[50:65]
	s_add_u32 m0, s32, 0x5000
	v_mfma_f32_32x32x16_bf16 v[2:17], v[172:175], v[176:179], v[2:17]
	global_load_lds_dwordx4 v141, s[100:101]
	v_mfma_f32_32x32x16_bf16 v[18:33], v[172:175], v[180:183], v[18:33]
	s_add_u32 m0, s32, 0x6000
	s_waitcnt lgkmcnt(1)
	v_mfma_f32_32x32x16_bf16 v[34:49], v[184:187], v[192:195], v[34:49]
	global_load_lds_dwordx4 v142, s[100:101]
	s_waitcnt lgkmcnt(0)
	v_mfma_f32_32x32x16_bf16 v[50:65], v[184:187], v[196:199], v[50:65]
	s_add_u32 m0, s32, 0x7000
	v_mfma_f32_32x32x16_bf16 v[2:17], v[188:191], v[192:195], v[2:17]
	global_load_lds_dwordx4 v143, s[100:101]
	v_mfma_f32_32x32x16_bf16 v[18:33], v[188:191], v[196:199], v[18:33]
	s_add_u32 s98, s98, 0x80
	s_addc_u32 s99, s99, 0
	s_add_u32 s100, s100, 0x80
	s_addc_u32 s101, s101, 0
	s_waitcnt vmcnt(0) lgkmcnt(0)
	s_barrier
	ds_read_b128 v[168:171], v132
	ds_read_b128 v[172:175], v132 offset:4096
	ds_read_b128 v[176:179], v136 offset:16384
	ds_read_b128 v[180:183], v136 offset:20480
	ds_read_b128 v[184:187], v133
	ds_read_b128 v[188:191], v133 offset:4096
	ds_read_b128 v[192:195], v137 offset:16384
	ds_read_b128 v[196:199], v137 offset:20480
	s_add_u32 m0, s32, 0x8000
	s_waitcnt lgkmcnt(5)
	v_mfma_f32_32x32x16_bf16 v[34:49], v[168:171], v[176:179], v[34:49]
	global_load_lds_dwordx4 v140, s[98:99]
	s_waitcnt lgkmcnt(4)
	v_mfma_f32_32x32x16_bf16 v[50:65], v[168:171], v[180:183], v[50:65]
	s_add_u32 m0, s32, 0x9000
	v_mfma_f32_32x32x16_bf16 v[2:17], v[172:175], v[176:179], v[2:17]
	global_load_lds_dwordx4 v141, s[98:99]
	v_mfma_f32_32x32x16_bf16 v[18:33], v[172:175], v[180:183], v[18:33]
	ds_read_b128 v[168:171], v134
	ds_read_b128 v[172:175], v134 offset:4096
	ds_read_b128 v[176:179], v138 offset:16384
	ds_read_b128 v[180:183], v138 offset:20480
	s_add_u32 m0, s32, 0xa000
	s_waitcnt lgkmcnt(5)
	v_mfma_f32_32x32x16_bf16 v[34:49], v[184:187], v[192:195], v[34:49]
	global_load_lds_dwordx4 v142, s[98:99]
	s_waitcnt lgkmcnt(4)
	v_mfma_f32_32x32x16_bf16 v[50:65], v[184:187], v[196:199], v[50:65]
	s_add_u32 m0, s32, 0xb000
	v_mfma_f32_32x32x16_bf16 v[2:17], v[188:191], v[192:195], v[2:17]
	global_load_lds_dwordx4 v143, s[98:99]
	v_mfma_f32_32x32x16_bf16 v[18:33], v[188:191], v[196:199], v[18:33]
	ds_read_b128 v[184:187], v135
	ds_read_b128 v[188:191], v135 offset:4096
	ds_read_b128 v[192:195], v139 offset:16384
	ds_read_b128 v[196:199], v139 offset:20480
	s_add_u32 m0, s32, 0xc000
	s_waitcnt lgkmcnt(5)
	v_mfma_f32_32x32x16_bf16 v[34:49], v[168:171], v[176:179], v[34:49]
	global_load_lds_dwordx4 v140, s[100:101]
	s_waitcnt lgkmcnt(4)
	v_mfma_f32_32x32x16_bf16 v[50:65], v[168:171], v[180:183], v[50:65]
	s_add_u32 m0, s32, 0xd000
	v_mfma_f32_32x32x16_bf16 v[2:17], v[172:175], v[176:179], v[2:17]
	global_load_lds_dwordx4 v141, s[100:101]
	v_mfma_f32_32x32x16_bf16 v[18:33], v[172:175], v[180:183], v[18:33]
	s_add_u32 m0, s32, 0xe000
	s_waitcnt lgkmcnt(1)
	v_mfma_f32_32x32x16_bf16 v[34:49], v[184:187], v[192:195], v[34:49]
	global_load_lds_dwordx4 v142, s[100:101]
	s_waitcnt lgkmcnt(0)
	v_mfma_f32_32x32x16_bf16 v[50:65], v[184:187], v[196:199], v[50:65]
	s_add_u32 m0, s32, 0xf000
	v_mfma_f32_32x32x16_bf16 v[2:17], v[188:191], v[192:195], v[2:17]
	global_load_lds_dwordx4 v143, s[100:101]
	v_mfma_f32_32x32x16_bf16 v[18:33], v[188:191], v[196:199], v[18:33]
	s_add_u32 s98, s98, 0x80
	s_addc_u32 s99, s99, 0
	s_add_u32 s100, s100, 0x80
	s_addc_u32 s101, s101, 0
	s_waitcnt vmcnt(0) lgkmcnt(0)
	s_barrier
	ds_read_b128 v[168:171], v132 offset:32768
	ds_read_b128 v[172:175], v132 offset:36864
	ds_read_b128 v[176:179], v136 offset:49152
	ds_read_b128 v[180:183], v136 offset:53248
	ds_read_b128 v[184:187], v133 offset:32768
	ds_read_b128 v[188:191], v133 offset:36864
	ds_read_b128 v[192:195], v137 offset:49152
	ds_read_b128 v[196:199], v137 offset:53248
	s_mov_b32 m0, s32
	s_waitcnt lgkmcnt(5)
	v_mfma_f32_32x32x16_bf16 v[34:49], v[168:171], v[176:179], v[34:49]
	global_load_lds_dwordx4 v140, s[98:99]
	s_waitcnt lgkmcnt(4)
	v_mfma_f32_32x32x16_bf16 v[50:65], v[168:171], v[180:183], v[50:65]
	s_add_u32 m0, s32, 0x1000
	v_mfma_f32_32x32x16_bf16 v[2:17], v[172:175], v[176:179], v[2:17]
	global_load_lds_dwordx4 v141, s[98:99]
	v_mfma_f32_32x32x16_bf16 v[18:33], v[172:175], v[180:183], v[18:33]
	ds_read_b128 v[168:171], v134 offset:32768
	ds_read_b128 v[172:175], v134 offset:36864
	ds_read_b128 v[176:179], v138 offset:49152
	ds_read_b128 v[180:183], v138 offset:53248
	s_add_u32 m0, s32, 0x2000
	s_waitcnt lgkmcnt(5)
	v_mfma_f32_32x32x16_bf16 v[34:49], v[184:187], v[192:195], v[34:49]
	global_load_lds_dwordx4 v142, s[98:99]
	s_waitcnt lgkmcnt(4)
	v_mfma_f32_32x32x16_bf16 v[50:65], v[184:187], v[196:199], v[50:65]
	s_add_u32 m0, s32, 0x3000
	v_mfma_f32_32x32x16_bf16 v[2:17], v[188:191], v[192:195], v[2:17]
	global_load_lds_dwordx4 v143, s[98:99]
	v_mfma_f32_32x32x16_bf16 v[18:33], v[188:191], v[196:199], v[18:33]
	ds_read_b128 v[184:187], v135 offset:32768
	ds_read_b128 v[188:191], v135 offset:36864
	ds_read_b128 v[192:195], v139 offset:49152
	ds_read_b128 v[196:199], v139 offset:53248
	s_add_u32 m0, s32, 0x4000
	s_waitcnt lgkmcnt(5)
	v_mfma_f32_32x32x16_bf16 v[34:49], v[168:171], v[176:179], v[34:49]
	global_load_lds_dwordx4 v140, s[100:101]
	s_waitcnt lgkmcnt(4)
	v_mfma_f32_32x32x16_bf16 v[50:65], v[168:171], v[180:183], v[50:65]
	s_add_u32 m0, s32, 0x5000
	v_mfma_f32_32x32x16_bf16 v[2:17], v[172:175], v[176:179], v[2:17]
	global_load_lds_dwordx4 v141, s[100:101]
	v_mfma_f32_32x32x16_bf16 v[18:33], v[172:175], v[180:183], v[18:33]
	s_add_u32 m0, s32, 0x6000
	s_waitcnt lgkmcnt(1)
	v_mfma_f32_32x32x16_bf16 v[34:49], v[184:187], v[192:195], v[34:49]
	global_load_lds_dwordx4 v142, s[100:101]
	s_waitcnt lgkmcnt(0)
	v_mfma_f32_32x32x16_bf16 v[50:65], v[184:187], v[196:199], v[50:65]
	s_add_u32 m0, s32, 0x7000
	v_mfma_f32_32x32x16_bf16 v[2:17], v[188:191], v[192:195], v[2:17]
	global_load_lds_dwordx4 v143, s[100:101]
	v_mfma_f32_32x32x16_bf16 v[18:33], v[188:191], v[196:199], v[18:33]
	s_add_u32 s98, s98, 0x80
	s_addc_u32 s99, s99, 0
	s_add_u32 s100, s100, 0x80
	s_addc_u32 s101, s101, 0
	s_waitcnt vmcnt(0) lgkmcnt(0)
	s_barrier
	ds_read_b128 v[168:171], v132
	ds_read_b128 v[172:175], v132 offset:4096
	ds_read_b128 v[176:179], v136 offset:16384
	ds_read_b128 v[180:183], v136 offset:20480
	ds_read_b128 v[184:187], v133
	ds_read_b128 v[188:191], v133 offset:4096
	ds_read_b128 v[192:195], v137 offset:16384
	ds_read_b128 v[196:199], v137 offset:20480
	s_add_u32 m0, s32, 0x8000
	s_waitcnt lgkmcnt(5)
	v_mfma_f32_32x32x16_bf16 v[34:49], v[168:171], v[176:179], v[34:49]
	global_load_lds_dwordx4 v140, s[98:99]
	s_waitcnt lgkmcnt(4)
	v_mfma_f32_32x32x16_bf16 v[50:65], v[168:171], v[180:183], v[50:65]
	s_add_u32 m0, s32, 0x9000
	v_mfma_f32_32x32x16_bf16 v[2:17], v[172:175], v[176:179], v[2:17]
	global_load_lds_dwordx4 v141, s[98:99]
	v_mfma_f32_32x32x16_bf16 v[18:33], v[172:175], v[180:183], v[18:33]
	ds_read_b128 v[168:171], v134
	ds_read_b128 v[172:175], v134 offset:4096
	ds_read_b128 v[176:179], v138 offset:16384
	ds_read_b128 v[180:183], v138 offset:20480
	s_add_u32 m0, s32, 0xa000
	s_waitcnt lgkmcnt(5)
	v_mfma_f32_32x32x16_bf16 v[34:49], v[184:187], v[192:195], v[34:49]
	global_load_lds_dwordx4 v142, s[98:99]
	s_waitcnt lgkmcnt(4)
	v_mfma_f32_32x32x16_bf16 v[50:65], v[184:187], v[196:199], v[50:65]
	s_add_u32 m0, s32, 0xb000
	v_mfma_f32_32x32x16_bf16 v[2:17], v[188:191], v[192:195], v[2:17]
	global_load_lds_dwordx4 v143, s[98:99]
	v_mfma_f32_32x32x16_bf16 v[18:33], v[188:191], v[196:199], v[18:33]
	ds_read_b128 v[184:187], v135
	ds_read_b128 v[188:191], v135 offset:4096
	ds_read_b128 v[192:195], v139 offset:16384
	ds_read_b128 v[196:199], v139 offset:20480
	s_add_u32 m0, s32, 0xc000
	s_waitcnt lgkmcnt(5)
	v_mfma_f32_32x32x16_bf16 v[34:49], v[168:171], v[176:179], v[34:49]
	global_load_lds_dwordx4 v140, s[100:101]
	s_waitcnt lgkmcnt(4)
	v_mfma_f32_32x32x16_bf16 v[50:65], v[168:171], v[180:183], v[50:65]
	s_add_u32 m0, s32, 0xd000
	v_mfma_f32_32x32x16_bf16 v[2:17], v[172:175], v[176:179], v[2:17]
	global_load_lds_dwordx4 v141, s[100:101]
	v_mfma_f32_32x32x16_bf16 v[18:33], v[172:175], v[180:183], v[18:33]
	s_add_u32 m0, s32, 0xe000
	s_waitcnt lgkmcnt(1)
	v_mfma_f32_32x32x16_bf16 v[34:49], v[184:187], v[192:195], v[34:49]
	global_load_lds_dwordx4 v142, s[100:101]
	s_waitcnt lgkmcnt(0)
	v_mfma_f32_32x32x16_bf16 v[50:65], v[184:187], v[196:199], v[50:65]
	s_add_u32 m0, s32, 0xf000
	v_mfma_f32_32x32x16_bf16 v[2:17], v[188:191], v[192:195], v[2:17]
	global_load_lds_dwordx4 v143, s[100:101]
	v_mfma_f32_32x32x16_bf16 v[18:33], v[188:191], v[196:199], v[18:33]
	s_add_u32 s98, s98, 0x80
	s_addc_u32 s99, s99, 0
	s_add_u32 s100, s100, 0x80
	s_addc_u32 s101, s101, 0
	s_waitcnt vmcnt(0) lgkmcnt(0)
	s_barrier
	ds_read_b128 v[168:171], v132 offset:32768
	ds_read_b128 v[172:175], v132 offset:36864
	ds_read_b128 v[176:179], v136 offset:49152
	ds_read_b128 v[180:183], v136 offset:53248
	ds_read_b128 v[184:187], v133 offset:32768
	ds_read_b128 v[188:191], v133 offset:36864
	ds_read_b128 v[192:195], v137 offset:49152
	ds_read_b128 v[196:199], v137 offset:53248
	s_mov_b32 m0, s32
	s_waitcnt lgkmcnt(5)
	v_mfma_f32_32x32x16_bf16 v[34:49], v[168:171], v[176:179], v[34:49]
	global_load_lds_dwordx4 v140, s[98:99]
	s_waitcnt lgkmcnt(4)
	v_mfma_f32_32x32x16_bf16 v[50:65], v[168:171], v[180:183], v[50:65]
	s_add_u32 m0, s32, 0x1000
	v_mfma_f32_32x32x16_bf16 v[2:17], v[172:175], v[176:179], v[2:17]
	global_load_lds_dwordx4 v141, s[98:99]
	v_mfma_f32_32x32x16_bf16 v[18:33], v[172:175], v[180:183], v[18:33]
	ds_read_b128 v[168:171], v134 offset:32768
	ds_read_b128 v[172:175], v134 offset:36864
	ds_read_b128 v[176:179], v138 offset:49152
	ds_read_b128 v[180:183], v138 offset:53248
	s_add_u32 m0, s32, 0x2000
	s_waitcnt lgkmcnt(5)
	v_mfma_f32_32x32x16_bf16 v[34:49], v[184:187], v[192:195], v[34:49]
	global_load_lds_dwordx4 v142, s[98:99]
	s_waitcnt lgkmcnt(4)
	v_mfma_f32_32x32x16_bf16 v[50:65], v[184:187], v[196:199], v[50:65]
	s_add_u32 m0, s32, 0x3000
	v_mfma_f32_32x32x16_bf16 v[2:17], v[188:191], v[192:195], v[2:17]
	global_load_lds_dwordx4 v143, s[98:99]
	v_mfma_f32_32x32x16_bf16 v[18:33], v[188:191], v[196:199], v[18:33]
	ds_read_b128 v[184:187], v135 offset:32768
	ds_read_b128 v[188:191], v135 offset:36864
	ds_read_b128 v[192:195], v139 offset:49152
	ds_read_b128 v[196:199], v139 offset:53248
	s_add_u32 m0, s32, 0x4000
	s_waitcnt lgkmcnt(5)
	v_mfma_f32_32x32x16_bf16 v[34:49], v[168:171], v[176:179], v[34:49]
	global_load_lds_dwordx4 v140, s[100:101]
	s_waitcnt lgkmcnt(4)
	v_mfma_f32_32x32x16_bf16 v[50:65], v[168:171], v[180:183], v[50:65]
	s_add_u32 m0, s32, 0x5000
	v_mfma_f32_32x32x16_bf16 v[2:17], v[172:175], v[176:179], v[2:17]
	global_load_lds_dwordx4 v141, s[100:101]
	v_mfma_f32_32x32x16_bf16 v[18:33], v[172:175], v[180:183], v[18:33]
	s_add_u32 m0, s32, 0x6000
	s_waitcnt lgkmcnt(1)
	v_mfma_f32_32x32x16_bf16 v[34:49], v[184:187], v[192:195], v[34:49]
	global_load_lds_dwordx4 v142, s[100:101]
	s_waitcnt lgkmcnt(0)
	v_mfma_f32_32x32x16_bf16 v[50:65], v[184:187], v[196:199], v[50:65]
	s_add_u32 m0, s32, 0x7000
	v_mfma_f32_32x32x16_bf16 v[2:17], v[188:191], v[192:195], v[2:17]
	global_load_lds_dwordx4 v143, s[100:101]
	v_mfma_f32_32x32x16_bf16 v[18:33], v[188:191], v[196:199], v[18:33]
	s_add_u32 s98, s98, 0x80
	s_addc_u32 s99, s99, 0
	s_add_u32 s100, s100, 0x80
	s_addc_u32 s101, s101, 0
	s_waitcnt vmcnt(0) lgkmcnt(0)
	s_barrier
	ds_read_b128 v[168:171], v132
	ds_read_b128 v[172:175], v132 offset:4096
	ds_read_b128 v[176:179], v136 offset:16384
	ds_read_b128 v[180:183], v136 offset:20480
	ds_read_b128 v[184:187], v133
	ds_read_b128 v[188:191], v133 offset:4096
	ds_read_b128 v[192:195], v137 offset:16384
	ds_read_b128 v[196:199], v137 offset:20480
	s_add_u32 m0, s32, 0x8000
	s_waitcnt lgkmcnt(5)
	v_mfma_f32_32x32x16_bf16 v[34:49], v[168:171], v[176:179], v[34:49]
	global_load_lds_dwordx4 v140, s[98:99]
	s_waitcnt lgkmcnt(4)
	v_mfma_f32_32x32x16_bf16 v[50:65], v[168:171], v[180:183], v[50:65]
	s_add_u32 m0, s32, 0x9000
	v_mfma_f32_32x32x16_bf16 v[2:17], v[172:175], v[176:179], v[2:17]
	global_load_lds_dwordx4 v141, s[98:99]
	v_mfma_f32_32x32x16_bf16 v[18:33], v[172:175], v[180:183], v[18:33]
	ds_read_b128 v[168:171], v134
	ds_read_b128 v[172:175], v134 offset:4096
	ds_read_b128 v[176:179], v138 offset:16384
	ds_read_b128 v[180:183], v138 offset:20480
	s_add_u32 m0, s32, 0xa000
	s_waitcnt lgkmcnt(5)
	v_mfma_f32_32x32x16_bf16 v[34:49], v[184:187], v[192:195], v[34:49]
	global_load_lds_dwordx4 v142, s[98:99]
	s_waitcnt lgkmcnt(4)
	v_mfma_f32_32x32x16_bf16 v[50:65], v[184:187], v[196:199], v[50:65]
	s_add_u32 m0, s32, 0xb000
	v_mfma_f32_32x32x16_bf16 v[2:17], v[188:191], v[192:195], v[2:17]
	global_load_lds_dwordx4 v143, s[98:99]
	v_mfma_f32_32x32x16_bf16 v[18:33], v[188:191], v[196:199], v[18:33]
	ds_read_b128 v[184:187], v135
	ds_read_b128 v[188:191], v135 offset:4096
	ds_read_b128 v[192:195], v139 offset:16384
	ds_read_b128 v[196:199], v139 offset:20480
	s_add_u32 m0, s32, 0xc000
	s_waitcnt lgkmcnt(5)
	v_mfma_f32_32x32x16_bf16 v[34:49], v[168:171], v[176:179], v[34:49]
	global_load_lds_dwordx4 v140, s[100:101]
	s_waitcnt lgkmcnt(4)
	v_mfma_f32_32x32x16_bf16 v[50:65], v[168:171], v[180:183], v[50:65]
	s_add_u32 m0, s32, 0xd000
	v_mfma_f32_32x32x16_bf16 v[2:17], v[172:175], v[176:179], v[2:17]
	global_load_lds_dwordx4 v141, s[100:101]
	v_mfma_f32_32x32x16_bf16 v[18:33], v[172:175], v[180:183], v[18:33]
	s_add_u32 m0, s32, 0xe000
	s_waitcnt lgkmcnt(1)
	v_mfma_f32_32x32x16_bf16 v[34:49], v[184:187], v[192:195], v[34:49]
	global_load_lds_dwordx4 v142, s[100:101]
	s_waitcnt lgkmcnt(0)
	v_mfma_f32_32x32x16_bf16 v[50:65], v[184:187], v[196:199], v[50:65]
	s_add_u32 m0, s32, 0xf000
	v_mfma_f32_32x32x16_bf16 v[2:17], v[188:191], v[192:195], v[2:17]
	global_load_lds_dwordx4 v143, s[100:101]
	v_mfma_f32_32x32x16_bf16 v[18:33], v[188:191], v[196:199], v[18:33]
	s_add_u32 s98, s98, 0x80
	s_addc_u32 s99, s99, 0
	s_add_u32 s100, s100, 0x80
	s_addc_u32 s101, s101, 0
	s_waitcnt vmcnt(0) lgkmcnt(0)
	s_barrier
	ds_read_b128 v[168:171], v132 offset:32768
	ds_read_b128 v[172:175], v132 offset:36864
	ds_read_b128 v[176:179], v136 offset:49152
	ds_read_b128 v[180:183], v136 offset:53248
	ds_read_b128 v[184:187], v133 offset:32768
	ds_read_b128 v[188:191], v133 offset:36864
	ds_read_b128 v[192:195], v137 offset:49152
	ds_read_b128 v[196:199], v137 offset:53248
	s_mov_b32 m0, s32
	s_waitcnt lgkmcnt(5)
	v_mfma_f32_32x32x16_bf16 v[34:49], v[168:171], v[176:179], v[34:49]
	global_load_lds_dwordx4 v140, s[98:99]
	s_waitcnt lgkmcnt(4)
	v_mfma_f32_32x32x16_bf16 v[50:65], v[168:171], v[180:183], v[50:65]
	s_add_u32 m0, s32, 0x1000
	v_mfma_f32_32x32x16_bf16 v[2:17], v[172:175], v[176:179], v[2:17]
	global_load_lds_dwordx4 v141, s[98:99]
	v_mfma_f32_32x32x16_bf16 v[18:33], v[172:175], v[180:183], v[18:33]
	ds_read_b128 v[168:171], v134 offset:32768
	ds_read_b128 v[172:175], v134 offset:36864
	ds_read_b128 v[176:179], v138 offset:49152
	ds_read_b128 v[180:183], v138 offset:53248
	s_add_u32 m0, s32, 0x2000
	s_waitcnt lgkmcnt(5)
	v_mfma_f32_32x32x16_bf16 v[34:49], v[184:187], v[192:195], v[34:49]
	global_load_lds_dwordx4 v142, s[98:99]
	s_waitcnt lgkmcnt(4)
	v_mfma_f32_32x32x16_bf16 v[50:65], v[184:187], v[196:199], v[50:65]
	s_add_u32 m0, s32, 0x3000
	v_mfma_f32_32x32x16_bf16 v[2:17], v[188:191], v[192:195], v[2:17]
	global_load_lds_dwordx4 v143, s[98:99]
	v_mfma_f32_32x32x16_bf16 v[18:33], v[188:191], v[196:199], v[18:33]
	ds_read_b128 v[184:187], v135 offset:32768
	ds_read_b128 v[188:191], v135 offset:36864
	ds_read_b128 v[192:195], v139 offset:49152
	ds_read_b128 v[196:199], v139 offset:53248
	s_add_u32 m0, s32, 0x4000
	s_waitcnt lgkmcnt(5)
	v_mfma_f32_32x32x16_bf16 v[34:49], v[168:171], v[176:179], v[34:49]
	global_load_lds_dwordx4 v140, s[100:101]
	s_waitcnt lgkmcnt(4)
	v_mfma_f32_32x32x16_bf16 v[50:65], v[168:171], v[180:183], v[50:65]
	s_add_u32 m0, s32, 0x5000
	v_mfma_f32_32x32x16_bf16 v[2:17], v[172:175], v[176:179], v[2:17]
	global_load_lds_dwordx4 v141, s[100:101]
	v_mfma_f32_32x32x16_bf16 v[18:33], v[172:175], v[180:183], v[18:33]
	s_add_u32 m0, s32, 0x6000
	s_waitcnt lgkmcnt(1)
	v_mfma_f32_32x32x16_bf16 v[34:49], v[184:187], v[192:195], v[34:49]
	global_load_lds_dwordx4 v142, s[100:101]
	s_waitcnt lgkmcnt(0)
	v_mfma_f32_32x32x16_bf16 v[50:65], v[184:187], v[196:199], v[50:65]
	s_add_u32 m0, s32, 0x7000
	v_mfma_f32_32x32x16_bf16 v[2:17], v[188:191], v[192:195], v[2:17]
	global_load_lds_dwordx4 v143, s[100:101]
	v_mfma_f32_32x32x16_bf16 v[18:33], v[188:191], v[196:199], v[18:33]
	s_add_u32 s98, s98, 0x80
	s_addc_u32 s99, s99, 0
	s_add_u32 s100, s100, 0x80
	s_addc_u32 s101, s101, 0
	s_waitcnt vmcnt(0) lgkmcnt(0)
	s_barrier
	ds_read_b128 v[168:171], v132
	ds_read_b128 v[172:175], v132 offset:4096
	ds_read_b128 v[176:179], v136 offset:16384
	ds_read_b128 v[180:183], v136 offset:20480
	ds_read_b128 v[184:187], v133
	ds_read_b128 v[188:191], v133 offset:4096
	ds_read_b128 v[192:195], v137 offset:16384
	ds_read_b128 v[196:199], v137 offset:20480
	s_add_u32 m0, s32, 0x8000
	s_waitcnt lgkmcnt(5)
	v_mfma_f32_32x32x16_bf16 v[34:49], v[168:171], v[176:179], v[34:49]
	global_load_lds_dwordx4 v140, s[98:99]
	s_waitcnt lgkmcnt(4)
	v_mfma_f32_32x32x16_bf16 v[50:65], v[168:171], v[180:183], v[50:65]
	s_add_u32 m0, s32, 0x9000
	v_mfma_f32_32x32x16_bf16 v[2:17], v[172:175], v[176:179], v[2:17]
	global_load_lds_dwordx4 v141, s[98:99]
	v_mfma_f32_32x32x16_bf16 v[18:33], v[172:175], v[180:183], v[18:33]
	ds_read_b128 v[168:171], v134
	ds_read_b128 v[172:175], v134 offset:4096
	ds_read_b128 v[176:179], v138 offset:16384
	ds_read_b128 v[180:183], v138 offset:20480
	s_add_u32 m0, s32, 0xa000
	s_waitcnt lgkmcnt(5)
	v_mfma_f32_32x32x16_bf16 v[34:49], v[184:187], v[192:195], v[34:49]
	global_load_lds_dwordx4 v142, s[98:99]
	s_waitcnt lgkmcnt(4)
	v_mfma_f32_32x32x16_bf16 v[50:65], v[184:187], v[196:199], v[50:65]
	s_add_u32 m0, s32, 0xb000
	v_mfma_f32_32x32x16_bf16 v[2:17], v[188:191], v[192:195], v[2:17]
	global_load_lds_dwordx4 v143, s[98:99]
	v_mfma_f32_32x32x16_bf16 v[18:33], v[188:191], v[196:199], v[18:33]
	ds_read_b128 v[184:187], v135
	ds_read_b128 v[188:191], v135 offset:4096
	ds_read_b128 v[192:195], v139 offset:16384
	ds_read_b128 v[196:199], v139 offset:20480
	s_add_u32 m0, s32, 0xc000
	s_waitcnt lgkmcnt(5)
	v_mfma_f32_32x32x16_bf16 v[34:49], v[168:171], v[176:179], v[34:49]
	global_load_lds_dwordx4 v140, s[100:101]
	s_waitcnt lgkmcnt(4)
	v_mfma_f32_32x32x16_bf16 v[50:65], v[168:171], v[180:183], v[50:65]
	s_add_u32 m0, s32, 0xd000
	v_mfma_f32_32x32x16_bf16 v[2:17], v[172:175], v[176:179], v[2:17]
	global_load_lds_dwordx4 v141, s[100:101]
	v_mfma_f32_32x32x16_bf16 v[18:33], v[172:175], v[180:183], v[18:33]
	s_add_u32 m0, s32, 0xe000
	s_waitcnt lgkmcnt(1)
	v_mfma_f32_32x32x16_bf16 v[34:49], v[184:187], v[192:195], v[34:49]
	global_load_lds_dwordx4 v142, s[100:101]
	s_waitcnt lgkmcnt(0)
	v_mfma_f32_32x32x16_bf16 v[50:65], v[184:187], v[196:199], v[50:65]
	s_add_u32 m0, s32, 0xf000
	v_mfma_f32_32x32x16_bf16 v[2:17], v[188:191], v[192:195], v[2:17]
	global_load_lds_dwordx4 v143, s[100:101]
	v_mfma_f32_32x32x16_bf16 v[18:33], v[188:191], v[196:199], v[18:33]
	s_add_u32 s98, s98, 0x80
	s_addc_u32 s99, s99, 0
	s_add_u32 s100, s100, 0x80
	s_addc_u32 s101, s101, 0
	s_waitcnt vmcnt(0) lgkmcnt(0)
	s_barrier
	ds_read_b128 v[168:171], v132 offset:32768
	ds_read_b128 v[172:175], v132 offset:36864
	ds_read_b128 v[176:179], v136 offset:49152
	ds_read_b128 v[180:183], v136 offset:53248
	ds_read_b128 v[184:187], v133 offset:32768
	ds_read_b128 v[188:191], v133 offset:36864
	ds_read_b128 v[192:195], v137 offset:49152
	ds_read_b128 v[196:199], v137 offset:53248
	s_mov_b32 m0, s32
	s_waitcnt lgkmcnt(5)
	v_mfma_f32_32x32x16_bf16 v[34:49], v[168:171], v[176:179], v[34:49]
	global_load_lds_dwordx4 v140, s[98:99]
	s_waitcnt lgkmcnt(4)
	v_mfma_f32_32x32x16_bf16 v[50:65], v[168:171], v[180:183], v[50:65]
	s_add_u32 m0, s32, 0x1000
	v_mfma_f32_32x32x16_bf16 v[2:17], v[172:175], v[176:179], v[2:17]
	global_load_lds_dwordx4 v141, s[98:99]
	v_mfma_f32_32x32x16_bf16 v[18:33], v[172:175], v[180:183], v[18:33]
	ds_read_b128 v[168:171], v134 offset:32768
	ds_read_b128 v[172:175], v134 offset:36864
	ds_read_b128 v[176:179], v138 offset:49152
	ds_read_b128 v[180:183], v138 offset:53248
	s_add_u32 m0, s32, 0x2000
	s_waitcnt lgkmcnt(5)
	v_mfma_f32_32x32x16_bf16 v[34:49], v[184:187], v[192:195], v[34:49]
	global_load_lds_dwordx4 v142, s[98:99]
	s_waitcnt lgkmcnt(4)
	v_mfma_f32_32x32x16_bf16 v[50:65], v[184:187], v[196:199], v[50:65]
	s_add_u32 m0, s32, 0x3000
	v_mfma_f32_32x32x16_bf16 v[2:17], v[188:191], v[192:195], v[2:17]
	global_load_lds_dwordx4 v143, s[98:99]
	v_mfma_f32_32x32x16_bf16 v[18:33], v[188:191], v[196:199], v[18:33]
	ds_read_b128 v[184:187], v135 offset:32768
	ds_read_b128 v[188:191], v135 offset:36864
	ds_read_b128 v[192:195], v139 offset:49152
	ds_read_b128 v[196:199], v139 offset:53248
	s_add_u32 m0, s32, 0x4000
	s_waitcnt lgkmcnt(5)
	v_mfma_f32_32x32x16_bf16 v[34:49], v[168:171], v[176:179], v[34:49]
	global_load_lds_dwordx4 v140, s[100:101]
	s_waitcnt lgkmcnt(4)
	v_mfma_f32_32x32x16_bf16 v[50:65], v[168:171], v[180:183], v[50:65]
	s_add_u32 m0, s32, 0x5000
	v_mfma_f32_32x32x16_bf16 v[2:17], v[172:175], v[176:179], v[2:17]
	global_load_lds_dwordx4 v141, s[100:101]
	v_mfma_f32_32x32x16_bf16 v[18:33], v[172:175], v[180:183], v[18:33]
	s_add_u32 m0, s32, 0x6000
	s_waitcnt lgkmcnt(1)
	v_mfma_f32_32x32x16_bf16 v[34:49], v[184:187], v[192:195], v[34:49]
	global_load_lds_dwordx4 v142, s[100:101]
	s_waitcnt lgkmcnt(0)
	v_mfma_f32_32x32x16_bf16 v[50:65], v[184:187], v[196:199], v[50:65]
	s_add_u32 m0, s32, 0x7000
	v_mfma_f32_32x32x16_bf16 v[2:17], v[188:191], v[192:195], v[2:17]
	global_load_lds_dwordx4 v143, s[100:101]
	v_mfma_f32_32x32x16_bf16 v[18:33], v[188:191], v[196:199], v[18:33]
	s_add_u32 s98, s98, 0x80
	s_addc_u32 s99, s99, 0
	s_add_u32 s100, s100, 0x80
	s_addc_u32 s101, s101, 0
	s_waitcnt vmcnt(0) lgkmcnt(0)
	s_barrier
	ds_read_b128 v[168:171], v132
	ds_read_b128 v[172:175], v132 offset:4096
	ds_read_b128 v[176:179], v136 offset:16384
	ds_read_b128 v[180:183], v136 offset:20480
	ds_read_b128 v[184:187], v133
	ds_read_b128 v[188:191], v133 offset:4096
	ds_read_b128 v[192:195], v137 offset:16384
	ds_read_b128 v[196:199], v137 offset:20480
	s_add_u32 m0, s32, 0x8000
	s_waitcnt lgkmcnt(5)
	v_mfma_f32_32x32x16_bf16 v[34:49], v[168:171], v[176:179], v[34:49]
	global_load_lds_dwordx4 v140, s[98:99]
	s_waitcnt lgkmcnt(4)
	v_mfma_f32_32x32x16_bf16 v[50:65], v[168:171], v[180:183], v[50:65]
	s_add_u32 m0, s32, 0x9000
	v_mfma_f32_32x32x16_bf16 v[2:17], v[172:175], v[176:179], v[2:17]
	global_load_lds_dwordx4 v141, s[98:99]
	v_mfma_f32_32x32x16_bf16 v[18:33], v[172:175], v[180:183], v[18:33]
	ds_read_b128 v[168:171], v134
	ds_read_b128 v[172:175], v134 offset:4096
	ds_read_b128 v[176:179], v138 offset:16384
	ds_read_b128 v[180:183], v138 offset:20480
	s_add_u32 m0, s32, 0xa000
	s_waitcnt lgkmcnt(5)
	v_mfma_f32_32x32x16_bf16 v[34:49], v[184:187], v[192:195], v[34:49]
	global_load_lds_dwordx4 v142, s[98:99]
	s_waitcnt lgkmcnt(4)
	v_mfma_f32_32x32x16_bf16 v[50:65], v[184:187], v[196:199], v[50:65]
	s_add_u32 m0, s32, 0xb000
	v_mfma_f32_32x32x16_bf16 v[2:17], v[188:191], v[192:195], v[2:17]
	global_load_lds_dwordx4 v143, s[98:99]
	v_mfma_f32_32x32x16_bf16 v[18:33], v[188:191], v[196:199], v[18:33]
	ds_read_b128 v[184:187], v135
	ds_read_b128 v[188:191], v135 offset:4096
	ds_read_b128 v[192:195], v139 offset:16384
	ds_read_b128 v[196:199], v139 offset:20480
	s_add_u32 m0, s32, 0xc000
	s_waitcnt lgkmcnt(5)
	v_mfma_f32_32x32x16_bf16 v[34:49], v[168:171], v[176:179], v[34:49]
	global_load_lds_dwordx4 v140, s[100:101]
	s_waitcnt lgkmcnt(4)
	v_mfma_f32_32x32x16_bf16 v[50:65], v[168:171], v[180:183], v[50:65]
	s_add_u32 m0, s32, 0xd000
	v_mfma_f32_32x32x16_bf16 v[2:17], v[172:175], v[176:179], v[2:17]
	global_load_lds_dwordx4 v141, s[100:101]
	v_mfma_f32_32x32x16_bf16 v[18:33], v[172:175], v[180:183], v[18:33]
	s_add_u32 m0, s32, 0xe000
	s_waitcnt lgkmcnt(1)
	v_mfma_f32_32x32x16_bf16 v[34:49], v[184:187], v[192:195], v[34:49]
	global_load_lds_dwordx4 v142, s[100:101]
	s_waitcnt lgkmcnt(0)
	v_mfma_f32_32x32x16_bf16 v[50:65], v[184:187], v[196:199], v[50:65]
	s_add_u32 m0, s32, 0xf000
	v_mfma_f32_32x32x16_bf16 v[2:17], v[188:191], v[192:195], v[2:17]
	global_load_lds_dwordx4 v143, s[100:101]
	v_mfma_f32_32x32x16_bf16 v[18:33], v[188:191], v[196:199], v[18:33]
	s_add_u32 s98, s98, 0x80
	s_addc_u32 s99, s99, 0
	s_add_u32 s100, s100, 0x80
	s_addc_u32 s101, s101, 0
	s_waitcnt vmcnt(0) lgkmcnt(0)
	s_barrier
	ds_read_b128 v[168:171], v132 offset:32768
	ds_read_b128 v[172:175], v132 offset:36864
	ds_read_b128 v[176:179], v136 offset:49152
	ds_read_b128 v[180:183], v136 offset:53248
	ds_read_b128 v[184:187], v133 offset:32768
	ds_read_b128 v[188:191], v133 offset:36864
	ds_read_b128 v[192:195], v137 offset:49152
	ds_read_b128 v[196:199], v137 offset:53248
	s_waitcnt lgkmcnt(5)
	v_mfma_f32_32x32x16_bf16 v[34:49], v[168:171], v[176:179], v[34:49]
	s_waitcnt lgkmcnt(4)
	v_mfma_f32_32x32x16_bf16 v[50:65], v[168:171], v[180:183], v[50:65]
	v_mfma_f32_32x32x16_bf16 v[2:17], v[172:175], v[176:179], v[2:17]
	v_mfma_f32_32x32x16_bf16 v[18:33], v[172:175], v[180:183], v[18:33]
	ds_read_b128 v[168:171], v134 offset:32768
	ds_read_b128 v[172:175], v134 offset:36864
	ds_read_b128 v[176:179], v138 offset:49152
	ds_read_b128 v[180:183], v138 offset:53248
	s_waitcnt lgkmcnt(5)
	v_mfma_f32_32x32x16_bf16 v[34:49], v[184:187], v[192:195], v[34:49]
	s_waitcnt lgkmcnt(4)
	v_mfma_f32_32x32x16_bf16 v[50:65], v[184:187], v[196:199], v[50:65]
	v_mfma_f32_32x32x16_bf16 v[2:17], v[188:191], v[192:195], v[2:17]
	v_mfma_f32_32x32x16_bf16 v[18:33], v[188:191], v[196:199], v[18:33]
	ds_read_b128 v[184:187], v135 offset:32768
	ds_read_b128 v[188:191], v135 offset:36864
	ds_read_b128 v[192:195], v139 offset:49152
	ds_read_b128 v[196:199], v139 offset:53248
	s_waitcnt lgkmcnt(5)
	v_mfma_f32_32x32x16_bf16 v[34:49], v[168:171], v[176:179], v[34:49]
	s_waitcnt lgkmcnt(4)
	v_mfma_f32_32x32x16_bf16 v[50:65], v[168:171], v[180:183], v[50:65]
	v_mfma_f32_32x32x16_bf16 v[2:17], v[172:175], v[176:179], v[2:17]
	v_mfma_f32_32x32x16_bf16 v[18:33], v[172:175], v[180:183], v[18:33]
	s_waitcnt lgkmcnt(1)
	v_mfma_f32_32x32x16_bf16 v[34:49], v[184:187], v[192:195], v[34:49]
	s_waitcnt lgkmcnt(0)
	v_mfma_f32_32x32x16_bf16 v[50:65], v[184:187], v[196:199], v[50:65]
	v_mfma_f32_32x32x16_bf16 v[2:17], v[188:191], v[192:195], v[2:17]
	v_mfma_f32_32x32x16_bf16 v[18:33], v[188:191], v[196:199], v[18:33]
	s_barrier
	s_nop 8
	ds_write2_b32 v100, v34, v50 offset1:32
	ds_write2_b32 v100, v35, v51 offset0:132 offset1:164
	v_add_u32_e32 v34, 0x400, v100
	ds_write2_b32 v34, v36, v52 offset0:8 offset1:40
	ds_write2_b32 v34, v37, v53 offset0:140 offset1:172
	v_add_u32_e32 v34, 0x1000, v100
	ds_write2_b32 v34, v38, v54 offset0:32 offset1:64
	ds_write2_b32 v34, v39, v55 offset0:164 offset1:196
	v_add_u32_e32 v34, 0x1400, v100
	ds_write2_b32 v34, v40, v56 offset0:40 offset1:72
	ds_write2_b32 v34, v41, v57 offset0:172 offset1:204
	v_add_u32_e32 v34, 0x2000, v100
	ds_write2_b32 v34, v42, v58 offset0:64 offset1:96
	ds_write2_b32 v34, v43, v59 offset0:196 offset1:228
	v_add_u32_e32 v34, 0x2400, v100
	ds_write2_b32 v34, v44, v60 offset0:72 offset1:104
	ds_write2_b32 v34, v45, v61 offset0:204 offset1:236
	v_add_u32_e32 v34, 0x3000, v100
	ds_write2_b32 v34, v46, v62 offset0:96 offset1:128
	v_add_u32_e32 v34, 0x3200, v100
	ds_write2_b32 v34, v47, v63 offset0:100 offset1:132
	v_add_u32_e32 v34, 0x3400, v100
	ds_write2_b32 v34, v48, v64 offset0:104 offset1:136
	v_add_u32_e32 v34, 0x3600, v100
	ds_write2_b32 v34, v49, v65 offset0:108 offset1:140
	v_add_u32_e32 v34, 0x4000, v100
	ds_write2_b32 v34, v2, v18 offset0:128 offset1:160
	v_add_u32_e32 v2, 0x4400, v100
	ds_write2_b32 v2, v3, v19 offset0:4 offset1:36
	ds_write2_b32 v2, v4, v20 offset0:136 offset1:168
	v_add_u32_e32 v2, 0x4800, v100
	ds_write2_b32 v2, v5, v21 offset0:12 offset1:44
	v_add_u32_e32 v2, 0x5000, v100
	ds_write2_b32 v2, v6, v22 offset0:160 offset1:192
	v_add_u32_e32 v2, 0x5400, v100
	ds_write2_b32 v2, v7, v23 offset0:36 offset1:68
	ds_write2_b32 v2, v8, v24 offset0:168 offset1:200
	v_add_u32_e32 v2, 0x5800, v100
	ds_write2_b32 v2, v9, v25 offset0:44 offset1:76
	v_add_u32_e32 v2, 0x6000, v100
	ds_write2_b32 v2, v10, v26 offset0:192 offset1:224
	v_add_u32_e32 v2, 0x6400, v100
	ds_write2_b32 v2, v11, v27 offset0:68 offset1:100
	ds_write2_b32 v2, v12, v28 offset0:200 offset1:232
	v_add_u32_e32 v2, 0x6800, v100
	ds_write2_b32 v2, v13, v29 offset0:76 offset1:108
	v_add_u32_e32 v2, 0x7200, v100
	ds_write2_b32 v2, v14, v30 offset0:96 offset1:128
	v_add_u32_e32 v2, 0x7400, v100
	ds_write2_b32 v2, v15, v31 offset0:100 offset1:132
	v_add_u32_e32 v2, 0x7600, v100
	ds_write2_b32 v2, v16, v32 offset0:104 offset1:136
	v_add_u32_e32 v2, 0x7800, v100
	s_cmp_lt_i32 s9, 0
	ds_write2_b32 v2, v17, v33 offset0:108 offset1:140
	s_waitcnt lgkmcnt(0)
	s_barrier
	s_cbranch_scc1 .LBB0_34
	v_add_u32_e32 v2, s9, v105
	v_ashrrev_i32_e32 v3, 31, v2
	v_lshlrev_b64 v[2:3], 11, v[2:3]
	v_lshl_add_u32 v4, s17, 7, v105
	v_lshl_add_u64 v[2:3], s[0:1], 0, v[2:3]
	v_ashrrev_i32_e32 v5, 31, v4
	v_lshl_add_u64 v[2:3], v[2:3], 0, v[0:1]
	v_lshl_add_u64 v[232:233], v[2:3], 0, s[56:57]
	v_lshl_add_u64 v[234:235], v[232:233], 0, s[56:57]
	v_lshl_add_u64 v[236:237], v[234:235], 0, s[56:57]
	global_load_dwordx4 v[66:69], v[236:237], off
	global_load_dwordx4 v[70:73], v[234:235], off
	global_load_dwordx4 v[74:77], v[232:233], off
	global_load_dwordx4 v[78:81], v[2:3], off
	v_lshlrev_b64 v[2:3], 11, v[4:5]
	v_lshl_add_u64 v[2:3], s[4:5], 0, v[2:3]
	v_lshl_add_u64 v[2:3], v[2:3], 0, v[0:1]
	v_lshl_add_u64 v[238:239], v[2:3], 0, s[56:57]
	v_lshl_add_u64 v[240:241], v[238:239], 0, s[56:57]
	v_lshl_add_u64 v[242:243], v[240:241], 0, s[56:57]
	global_load_dwordx4 v[82:85], v[242:243], off
	global_load_dwordx4 v[86:89], v[240:241], off
	global_load_dwordx4 v[90:93], v[238:239], off
	global_load_dwordx4 v[94:97], v[2:3], off
	s_branch .LBB0_34

.LBB0_65:
	v_fma_f32 v50, v50, s54, -v188
	v_fma_f32 v51, v51, s54, -v188
	v_exp_f32_e32 v50, v50
	v_exp_f32_e32 v51, v51
	v_fma_f32 v52, v52, s54, -v188
	v_fma_f32 v53, v53, s54, -v188
	v_add_f32_e32 v236, 0, v50
	v_add_f32_e32 v237, 0, v51
	v_exp_f32_e32 v52, v52
	v_exp_f32_e32 v53, v53
	v_fma_f32 v54, v54, s54, -v188
	v_fma_f32 v55, v55, s54, -v188
	v_add_f32_e32 v236, v52, v236
	v_add_f32_e32 v237, v53, v237
	v_exp_f32_e32 v54, v54
	v_exp_f32_e32 v55, v55
	v_fma_f32 v56, v56, s54, -v188
	v_fma_f32 v57, v57, s54, -v188
	v_add_f32_e32 v236, v54, v236
	v_add_f32_e32 v237, v55, v237
	v_exp_f32_e32 v56, v56
	v_exp_f32_e32 v57, v57
	v_fma_f32 v58, v58, s54, -v188
	v_fma_f32 v59, v59, s54, -v188
	v_add_f32_e32 v236, v56, v236
	v_add_f32_e32 v237, v57, v237
	v_exp_f32_e32 v58, v58
	v_exp_f32_e32 v59, v59
	v_fma_f32 v60, v60, s54, -v188
	v_fma_f32 v61, v61, s54, -v188
	v_add_f32_e32 v236, v58, v236
	v_add_f32_e32 v237, v59, v237
	v_exp_f32_e32 v60, v60
	v_exp_f32_e32 v61, v61
	v_fma_f32 v62, v62, s54, -v188
	v_fma_f32 v63, v63, s54, -v188
	v_add_f32_e32 v236, v60, v236
	v_add_f32_e32 v237, v61, v237
	v_exp_f32_e32 v62, v62
	v_exp_f32_e32 v63, v63
	v_fma_f32 v64, v64, s54, -v188
	v_fma_f32 v65, v65, s54, -v188
	v_add_f32_e32 v236, v62, v236
	v_add_f32_e32 v237, v63, v237
	v_exp_f32_e32 v64, v64
	v_exp_f32_e32 v65, v65
	v_fma_f32 v34, v34, s54, -v188
	v_fma_f32 v35, v35, s54, -v188
	v_add_f32_e32 v236, v64, v236
	v_add_f32_e32 v237, v65, v237
	v_exp_f32_e32 v202, v34
	v_exp_f32_e32 v203, v35
	v_fma_f32 v36, v36, s54, -v188
	v_fma_f32 v37, v37, s54, -v188
	v_add_f32_e32 v236, v202, v236
	v_add_f32_e32 v237, v203, v237
	v_exp_f32_e32 v204, v36
	v_exp_f32_e32 v205, v37
	v_fma_f32 v38, v38, s54, -v188
	v_fma_f32 v39, v39, s54, -v188
	v_add_f32_e32 v236, v204, v236
	v_add_f32_e32 v237, v205, v237
	v_exp_f32_e32 v218, v38
	v_exp_f32_e32 v219, v39
	v_fma_f32 v40, v40, s54, -v188
	v_fma_f32 v41, v41, s54, -v188
	v_add_f32_e32 v236, v218, v236
	v_add_f32_e32 v237, v219, v237
	v_exp_f32_e32 v220, v40
	v_exp_f32_e32 v221, v41
	v_fma_f32 v42, v42, s54, -v188
	v_fma_f32 v43, v43, s54, -v188
	v_add_f32_e32 v236, v220, v236
	v_add_f32_e32 v237, v221, v237
	v_exp_f32_e32 v200, v42
	v_exp_f32_e32 v201, v43
	v_fma_f32 v44, v44, s54, -v188
	v_fma_f32 v45, v45, s54, -v188
	v_add_f32_e32 v236, v200, v236
	v_add_f32_e32 v237, v201, v237
	v_exp_f32_e32 v222, v44
	v_exp_f32_e32 v223, v45
	v_fma_f32 v46, v46, s54, -v188
	v_fma_f32 v47, v47, s54, -v188
	v_add_f32_e32 v236, v222, v236
	v_add_f32_e32 v237, v223, v237
	v_exp_f32_e32 v232, v46
	v_exp_f32_e32 v233, v47
	v_fma_f32 v48, v48, s54, -v188
	v_fma_f32 v49, v49, s54, -v188
	v_add_f32_e32 v236, v232, v236
	v_add_f32_e32 v237, v233, v237
	v_exp_f32_e32 v234, v48
	v_exp_f32_e32 v235, v49
	v_add_f32_e32 v236, v234, v236
	v_add_f32_e32 v237, v235, v237
	s_nop 0
	v_add_f32_e32 v155, v236, v237
	s_setprio 1
	ds_read2_b64 v[38:41], v153 offset0:132 offset1:134
	ds_read2_b64 v[42:45], v129 offset0:164 offset1:166
	v_cvt_pk_bf16_f32 v34, v50, v51
	v_cvt_pk_bf16_f32 v35, v52, v53
	v_cvt_pk_bf16_f32 v36, v54, v55
	v_cvt_pk_bf16_f32 v37, v56, v57
	s_waitcnt lgkmcnt(3)
	s_nop 0
	v_mfma_f32_32x32x16_bf16 v[18:33], v[110:113], v[34:37], v[18:33]
	s_waitcnt lgkmcnt(2)
	v_mfma_f32_32x32x16_bf16 v[2:17], v[114:117], v[34:37], v[2:17]
	ds_read2_b64 v[46:49], v153 offset0:136 offset1:138
	ds_read2_b64 v[50:53], v129 offset0:168 offset1:170
	v_cvt_pk_bf16_f32 v34, v58, v59
	v_cvt_pk_bf16_f32 v35, v60, v61
	v_cvt_pk_bf16_f32 v36, v62, v63
	v_cvt_pk_bf16_f32 v37, v64, v65
	s_waitcnt lgkmcnt(3)
	s_nop 0
	v_mfma_f32_32x32x16_bf16 v[18:33], v[38:41], v[34:37], v[18:33]
	s_waitcnt lgkmcnt(2)
	v_mfma_f32_32x32x16_bf16 v[2:17], v[42:45], v[34:37], v[2:17]
	ds_read2_b64 v[38:41], v153 offset0:140 offset1:142
	ds_read2_b64 v[42:45], v129 offset0:172 offset1:174
	v_cvt_pk_bf16_f32 v34, v202, v203
	v_cvt_pk_bf16_f32 v35, v204, v205
	v_cvt_pk_bf16_f32 v36, v218, v219
	v_cvt_pk_bf16_f32 v37, v220, v221
	s_waitcnt lgkmcnt(3)
	s_nop 0
	v_mfma_f32_32x32x16_bf16 v[18:33], v[46:49], v[34:37], v[18:33]
	s_waitcnt lgkmcnt(2)
	v_mfma_f32_32x32x16_bf16 v[2:17], v[50:53], v[34:37], v[2:17]
	v_cvt_pk_bf16_f32 v34, v200, v201
	v_cvt_pk_bf16_f32 v35, v222, v223
	v_cvt_pk_bf16_f32 v36, v232, v233
	v_cvt_pk_bf16_f32 v37, v234, v235
	s_waitcnt lgkmcnt(1)
	s_nop 0
	v_mfma_f32_32x32x16_bf16 v[18:33], v[38:41], v[34:37], v[18:33]
	s_waitcnt lgkmcnt(0)
	v_mfma_f32_32x32x16_bf16 v[2:17], v[42:45], v[34:37], v[2:17]
	v_add_f32_e32 v127, v127, v155
	s_setprio 0
	s_cmp_eq_u32 s9, 1
	s_cselect_b32 s9, 0x5600, 0
	v_add3_u32 v34, s9, v147, v189
	s_waitcnt vmcnt(4)
	ds_write_b128 v34, v[90:93]
	v_add3_u32 v34, s9, v190, v191
	s_waitcnt vmcnt(3)
	ds_write_b128 v34, v[94:97]
	v_add3_u32 v34, s9, v192, v193
	s_waitcnt vmcnt(2)
	ds_write_b128 v34, v[106:109]
	v_or_b32_e32 v34, s9, v194
	s_add_i32 s14, s14, 1
	v_add3_u32 v35, v34, v195, s59
	v_add3_u32 v34, v34, v196, s59
	v_lshl_add_u64 v[172:173], v[172:173], 0, s[52:53]
	v_lshl_add_u64 v[174:175], v[174:175], 0, s[52:53]
	v_lshl_add_u64 v[176:177], v[176:177], 0, s[44:45]
	v_lshl_add_u64 v[182:183], v[182:183], 0, s[56:57]
	v_lshl_add_u64 v[178:179], v[178:179], 0, s[44:45]
	v_lshl_add_u64 v[184:185], v[184:185], 0, s[56:57]
	v_lshl_add_u64 v[180:181], v[180:181], 0, s[44:45]
	s_cmp_eq_u32 s8, s14
	v_lshl_add_u64 v[186:187], v[186:187], 0, s[56:57]
	s_waitcnt vmcnt(1)
	ds_write2_b64 v35, v[102:103], v[104:105] offset1:1
	s_waitcnt vmcnt(0)
	ds_write2_b64 v34, v[98:99], v[100:101] offset1:1
	s_waitcnt lgkmcnt(0)
	s_barrier
	s_cbranch_scc1 .LBB0_49

.LBB0_332:
	s_or_b64 exec, exec, s[14:15]
	v_readlane_b32 s1, v254, 12
	s_ashr_i32 s3, s1, 3
	s_waitcnt lgkmcnt(0)
	s_and_b32 s0, s34, -8
	s_cmp_ge_i32 s1, s0
	s_cselect_b64 s[0:1], -1, 0
	s_cmpk_gt_i32 s3, 0x26f
	s_cselect_b64 s[4:5], -1, 0
	s_or_b64 s[0:1], s[4:5], s[0:1]
	s_and_b64 vcc, exec, s[0:1]
	s_cbranch_vccnz .LBB0_733
	v_ashrrev_i32_e32 v103, 7, v146
	v_and_b32_e32 v3, 31, v146
	v_bfe_u32 v4, v146, 5, 1
	s_waitcnt vmcnt(0)
	v_lshlrev_b32_e32 v0, 2, v146
	v_lshlrev_b32_e32 v6, 6, v103
	v_readlane_b32 s0, v254, 12
	v_bfe_u32 v2, v146, 6, 1
	v_and_b32_e32 v5, 4, v0
	s_movk_i32 s4, 0x90
	v_or_b32_e32 v7, v6, v3
	v_lshlrev_b32_e32 v0, 4, v4
	s_and_b32 s64, s0, 7
	v_lshl_or_b32 v8, v2, 6, v3
	v_mad_u64_u32 v[98:99], s[0:1], v7, s4, v[0:1]
	v_mad_u32_u24 v99, v8, s4, v0
	v_lshlrev_b32_e32 v0, 2, v3
	v_lshl_or_b32 v0, v2, 8, v0
	v_lshl_or_b32 v2, v4, 2, v6
	s_movk_i32 s22, 0x210
	v_mad_u64_u32 v[100:101], s[0:1], v2, s22, v[0:1]
	v_and_b32_e32 v4, 15, v146
	v_and_b32_e32 v0, 1, v146
	s_lshr_b32 s65, s34, 3
	v_cmp_eq_u32_e64 s[42:43], 0, v0
	v_lshlrev_b32_e32 v0, 4, v4
	s_add_u32 s6, s62, 0x14f5000
	v_ashrrev_i32_e32 v109, 1, v146
	v_lshl_add_u64 v[2:3], s[62:63], 0, v[0:1]
	v_and_b32_e32 v0, 7, v146
	v_readlane_b32 s20, v254, 13
	s_addc_u32 s7, s63, 0
	v_ashrrev_i32_e32 v109, 3, v146
	v_lshlrev_b32_e32 v114, 7, v109
	s_mov_b64 s[0:1], 0x11d5000
	v_cmp_eq_u32_e64 s[4:5], 0, v0
	v_lshlrev_b32_e32 v0, 5, v4
	v_readlane_b32 s21, v254, 14
	s_add_u32 s8, s62, 0x680000
	v_lshl_add_u64 v[104:105], v[2:3], 0, s[0:1]
	v_lshl_add_u64 v[2:3], s[20:21], 0, v[0:1]
	s_mov_b64 s[0:1], 0x9000000
	s_addc_u32 s9, s63, 0
	v_lshl_add_u64 v[106:107], v[2:3], 0, s[0:1]
	v_add_u32_e32 v2, 0x100, v146
	s_add_u32 s10, s62, 0x10d4000
	v_ashrrev_i32_e32 v120, 4, v2
	v_add_u32_e32 v2, 0x200, v146
	s_addc_u32 s11, s63, 0
	v_ashrrev_i32_e32 v124, 4, v2
	v_add_u32_e32 v2, 0x300, v146
	s_add_u32 s12, s62, 0x10d4800
	v_ashrrev_i32_e32 v128, 4, v2
	v_add_u32_e32 v2, 0x400, v146
	s_addc_u32 s13, s63, 0
	v_ashrrev_i32_e32 v132, 4, v2
	v_add_u32_e32 v2, 0x500, v146
	s_add_u32 s14, s62, 0x1375000
	v_ashrrev_i32_e32 v136, 4, v2
	v_add_u32_e32 v2, 0x600, v146
	s_addc_u32 s15, s63, 0
	v_ashrrev_i32_e32 v140, 4, v2
	v_add_u32_e32 v2, 0x700, v146
	s_add_u32 s16, s62, 0x6ef5000
	v_ashrrev_i32_e32 v116, 4, v146
	v_ashrrev_i32_e32 v144, 4, v2
	s_addc_u32 s17, s63, 0
	v_mul_lo_u32 v117, v116, s22
	v_mul_lo_u32 v121, v120, s22
	v_mul_lo_u32 v125, v124, s22
	v_mul_lo_u32 v129, v128, s22
	v_mul_lo_u32 v133, v132, s22
	v_mul_lo_u32 v137, v136, s22
	v_mul_lo_u32 v141, v140, s22
	v_mul_lo_u32 v145, v144, s22
	v_lshlrev_b32_e32 v101, 3, v4
	v_cmp_gt_u32_e64 s[38:39], 4, v4
	v_cmp_gt_u32_e64 s[40:41], 2, v4
	s_add_u32 s18, s62, 0x7af5000
	v_add_u32_e32 v118, v117, v0
	v_xor_b32_e32 v4, 32, v0
	v_add_u32_e32 v122, v121, v0
	v_add_u32_e32 v126, v125, v0
	v_add_u32_e32 v130, v129, v0
	v_add_u32_e32 v134, v133, v0
	v_add_u32_e32 v138, v137, v0
	v_add_u32_e32 v142, v141, v0
	v_add_u32_e32 v147, v145, v0
	v_lshlrev_b32_e32 v0, 3, v146
	v_and_b32_e32 v115, 7, v146
	v_lshlrev_b32_e32 v115, 4, v115
	s_addc_u32 s19, s63, 0
	v_and_b32_e32 v108, 0x78, v0
	v_and_b32_e32 v150, 0x7f, v146
	v_lshlrev_b32_e32 v0, 8, v103
	s_add_u32 s20, s20, 0x8800000
	v_mad_u32_u24 v151, v150, s22, v0
	v_add_u32_e32 v0, 0x1000, v115
	v_add_u32_e32 v2, 0x2000, v115
	v_add_u32_e32 v3, 0x3000, v115
	s_movk_i32 s76, 0x1fff
	v_bfe_u32 v102, v146, 4, 3
	v_lshlrev_b32_e32 v102, 4, v102
	v_xor_b32_e32 v102, v102, v115
	v_lshrrev_b32_e32 v102, 1, v102
	s_mov_b32 s66, 0
	v_add_u32_e32 v119, v117, v4
	s_addc_u32 s21, s21, 0
	v_add_u32_e32 v123, v121, v4
	v_add_u32_e32 v127, v125, v4
	v_add_u32_e32 v131, v129, v4
	v_add_u32_e32 v135, v133, v4
	v_add_u32_e32 v139, v137, v4
	v_add_u32_e32 v143, v141, v4
	v_add_u32_e32 v148, v145, v4
	v_lshlrev_b32_e32 v149, 2, v108
	s_mov_b64 s[0:1], 0
	s_mov_b32 s67, -1
	v_add_u32_e32 v152, v114, v0
	v_add_u32_e32 v153, v114, v2
	v_add_u32_e32 v154, v114, v3
	s_branch .LBB0_335

.LBB0_349:
	s_lshl_b32 s69, s68, 7
	v_add_u32_e32 v2, s69, v109
	s_lshl_b32 s50, s46, 7
	v_ashrrev_i32_e32 v3, 31, v2
	v_lshlrev_b64 v[2:3], 11, v[2:3]
	v_add_u32_e32 v38, s50, v109
	s_lshl_b32 s98, s69, 11
	s_add_u32 s98, s6, s98
	s_addc_u32 s99, s7, 0
	s_lshl_b32 s100, s50, 11
	s_add_u32 s100, s8, s100
	s_addc_u32 s101, s9, 0
	s_mov_b64 s[26:27], -1
	s_andn2_b64 vcc, exec, s[24:25]
	v_lshl_add_u64 v[34:35], s[6:7], 0, v[2:3]
	v_ashrrev_i32_e32 v39, 31, v38
	v_lshlrev_b32_e32 v0, 1, v102
	s_cbranch_vccnz .LBB0_351
	v_lshlrev_b64 v[36:37], 11, v[38:39]
	v_lshl_add_u64 v[2:3], s[8:9], 0, v[36:37]
	v_lshl_add_u64 v[30:31], v[34:35], 0, v[0:1]
	v_lshl_add_u64 v[14:15], v[2:3], 0, v[0:1]
	v_lshl_add_u64 v[222:223], v[14:15], 0, s[56:57]
	v_lshl_add_u64 v[248:249], v[222:223], 0, s[56:57]
	v_lshl_add_u64 v[250:251], v[248:249], 0, s[56:57]
	v_lshl_add_u64 v[204:205], v[30:31], 0, s[56:57]
	v_lshl_add_u64 v[218:219], v[204:205], 0, s[56:57]
	v_lshl_add_u64 v[220:221], v[218:219], 0, s[56:57]
	global_load_dwordx4 v[2:5], v[250:251], off
	global_load_dwordx4 v[6:9], v[248:249], off
	global_load_dwordx4 v[10:13], v[222:223], off
	s_nop 0
	global_load_dwordx4 v[14:17], v[14:15], off
	s_nop 0
	global_load_dwordx4 v[18:21], v[220:221], off
	global_load_dwordx4 v[22:25], v[218:219], off
	global_load_dwordx4 v[26:29], v[204:205], off
	s_nop 0
	global_load_dwordx4 v[30:33], v[30:31], off
	s_mov_b64 s[26:27], 0

.LBB0_353:
	v_add_u32_e32 v155, v114, v115
	v_lshrrev_b32_e32 v168, 6, v146
	v_lshlrev_b32_e32 v168, 10, v168
	v_lshl_add_u32 v164, v109, 11, v0
	v_readfirstlane_b32 s32, v168
	v_add_u32_e32 v165, 0x10000, v164
	v_add_u32_e32 v166, 0x20000, v164
	v_add_u32_e32 v167, 0x30000, v164
	v_bfe_u32 v168, v146, 1, 3
	v_bfe_u32 v169, v146, 5, 1
	v_xor_b32_e32 v168, v168, v169
	v_lshlrev_b32_e32 v168, 4, v168
	v_and_b32_e32 v169, 31, v146
	v_lshrrev_b32_e32 v170, 7, v146
	v_lshl_add_u32 v170, v170, 6, v169
	v_lshl_add_u32 v156, v170, 7, v168
	v_bfe_u32 v170, v146, 6, 1
	v_lshl_add_u32 v170, v170, 6, v169
	v_lshl_add_u32 v160, v170, 7, v168
	v_xor_b32_e32 v157, 32, v156
	v_xor_b32_e32 v161, 32, v160
	v_xor_b32_e32 v158, 64, v156
	v_xor_b32_e32 v162, 64, v160
	v_xor_b32_e32 v159, 96, v156
	v_xor_b32_e32 v163, 96, v160
	s_add_u32 s98, s98, 0x80
	s_addc_u32 s99, s99, 0
	s_add_u32 s100, s100, 0x80
	s_addc_u32 s101, s101, 0
	s_add_u32 m0, s32, 0x8000
	s_nop 0
	global_load_lds_dwordx4 v164, s[98:99]
	s_add_u32 m0, s32, 0x9000
	s_nop 0
	global_load_lds_dwordx4 v165, s[98:99]
	s_add_u32 m0, s32, 0xa000
	s_nop 0
	global_load_lds_dwordx4 v166, s[98:99]
	s_add_u32 m0, s32, 0xb000
	s_nop 0
	global_load_lds_dwordx4 v167, s[98:99]
	s_add_u32 m0, s32, 0xc000
	s_nop 0
	global_load_lds_dwordx4 v164, s[100:101]
	s_add_u32 m0, s32, 0xd000
	s_nop 0
	global_load_lds_dwordx4 v165, s[100:101]
	s_add_u32 m0, s32, 0xe000
	s_nop 0
	global_load_lds_dwordx4 v166, s[100:101]
	s_add_u32 m0, s32, 0xf000
	s_nop 0
	global_load_lds_dwordx4 v167, s[100:101]
	s_add_u32 s98, s98, 0x80
	s_addc_u32 s99, s99, 0
	s_add_u32 s100, s100, 0x80
	s_addc_u32 s101, s101, 0
	s_waitcnt vmcnt(8)
	ds_write_b128 v155, v[30:33]
	ds_write_b128 v155, v[14:17] offset:16384
	ds_write_b128 v152, v[26:29]
	ds_write_b128 v152, v[10:13] offset:16384
	ds_write_b128 v153, v[22:25]
	ds_write_b128 v153, v[6:9] offset:16384
	ds_write_b128 v154, v[18:21]
	ds_write_b128 v154, v[2:5] offset:16384
	s_lshl_b32 s24, s67, 7
	s_and_b64 s[0:1], s[0:1], exec
	s_cselect_b32 s0, s24, -1
	s_waitcnt lgkmcnt(0)
	s_barrier
	ds_read_b128 v[188:191], v156
	ds_read_b128 v[192:195], v156 offset:4096
	ds_read_b128 v[196:199], v160 offset:16384
	ds_read_b128 v[200:203], v160 offset:20480
	ds_read_b128 v[232:235], v157
	ds_read_b128 v[236:239], v157 offset:4096
	ds_read_b128 v[240:243], v161 offset:16384
	ds_read_b128 v[244:247], v161 offset:20480
	s_waitcnt lgkmcnt(5)
	v_mfma_f32_32x32x16_bf16 v[34:49], v[188:191], v[196:199], 0
	s_waitcnt lgkmcnt(4)
	v_mfma_f32_32x32x16_bf16 v[50:65], v[188:191], v[200:203], 0
	v_mfma_f32_32x32x16_bf16 v[2:17], v[192:195], v[196:199], 0
	v_mfma_f32_32x32x16_bf16 v[18:33], v[192:195], v[200:203], 0
	ds_read_b128 v[188:191], v158
	ds_read_b128 v[192:195], v158 offset:4096
	ds_read_b128 v[196:199], v162 offset:16384
	ds_read_b128 v[200:203], v162 offset:20480
	s_waitcnt lgkmcnt(5)
	v_mfma_f32_32x32x16_bf16 v[34:49], v[232:235], v[240:243], v[34:49]
	s_waitcnt lgkmcnt(4)
	v_mfma_f32_32x32x16_bf16 v[50:65], v[232:235], v[244:247], v[50:65]
	v_mfma_f32_32x32x16_bf16 v[2:17], v[236:239], v[240:243], v[2:17]
	v_mfma_f32_32x32x16_bf16 v[18:33], v[236:239], v[244:247], v[18:33]
	ds_read_b128 v[232:235], v159
	ds_read_b128 v[236:239], v159 offset:4096
	ds_read_b128 v[240:243], v163 offset:16384
	ds_read_b128 v[244:247], v163 offset:20480
	s_waitcnt lgkmcnt(5)
	v_mfma_f32_32x32x16_bf16 v[34:49], v[188:191], v[196:199], v[34:49]
	s_waitcnt lgkmcnt(4)
	v_mfma_f32_32x32x16_bf16 v[50:65], v[188:191], v[200:203], v[50:65]
	v_mfma_f32_32x32x16_bf16 v[2:17], v[192:195], v[196:199], v[2:17]
	v_mfma_f32_32x32x16_bf16 v[18:33], v[192:195], v[200:203], v[18:33]
	s_waitcnt lgkmcnt(1)
	v_mfma_f32_32x32x16_bf16 v[34:49], v[232:235], v[240:243], v[34:49]
	s_waitcnt lgkmcnt(0)
	v_mfma_f32_32x32x16_bf16 v[50:65], v[232:235], v[244:247], v[50:65]
	v_mfma_f32_32x32x16_bf16 v[2:17], v[236:239], v[240:243], v[2:17]
	v_mfma_f32_32x32x16_bf16 v[18:33], v[236:239], v[244:247], v[18:33]
	s_waitcnt vmcnt(0) lgkmcnt(0)
	s_barrier
	ds_read_b128 v[188:191], v156 offset:32768
	ds_read_b128 v[192:195], v156 offset:36864
	ds_read_b128 v[196:199], v160 offset:49152
	ds_read_b128 v[200:203], v160 offset:53248
	ds_read_b128 v[232:235], v157 offset:32768
	ds_read_b128 v[236:239], v157 offset:36864
	ds_read_b128 v[240:243], v161 offset:49152
	ds_read_b128 v[244:247], v161 offset:53248
	s_mov_b32 m0, s32
	s_waitcnt lgkmcnt(5)
	v_mfma_f32_32x32x16_bf16 v[34:49], v[188:191], v[196:199], v[34:49]
	global_load_lds_dwordx4 v164, s[98:99]
	s_waitcnt lgkmcnt(4)
	v_mfma_f32_32x32x16_bf16 v[50:65], v[188:191], v[200:203], v[50:65]
	s_add_u32 m0, s32, 0x1000
	v_mfma_f32_32x32x16_bf16 v[2:17], v[192:195], v[196:199], v[2:17]
	global_load_lds_dwordx4 v165, s[98:99]
	v_mfma_f32_32x32x16_bf16 v[18:33], v[192:195], v[200:203], v[18:33]
	ds_read_b128 v[188:191], v158 offset:32768
	ds_read_b128 v[192:195], v158 offset:36864
	ds_read_b128 v[196:199], v162 offset:49152
	ds_read_b128 v[200:203], v162 offset:53248
	s_add_u32 m0, s32, 0x2000
	s_waitcnt lgkmcnt(5)
	v_mfma_f32_32x32x16_bf16 v[34:49], v[232:235], v[240:243], v[34:49]
	global_load_lds_dwordx4 v166, s[98:99]
	s_waitcnt lgkmcnt(4)
	v_mfma_f32_32x32x16_bf16 v[50:65], v[232:235], v[244:247], v[50:65]
	s_add_u32 m0, s32, 0x3000
	v_mfma_f32_32x32x16_bf16 v[2:17], v[236:239], v[240:243], v[2:17]
	global_load_lds_dwordx4 v167, s[98:99]
	v_mfma_f32_32x32x16_bf16 v[18:33], v[236:239], v[244:247], v[18:33]
	ds_read_b128 v[232:235], v159 offset:32768
	ds_read_b128 v[236:239], v159 offset:36864
	ds_read_b128 v[240:243], v163 offset:49152
	ds_read_b128 v[244:247], v163 offset:53248
	s_add_u32 m0, s32, 0x4000
	s_waitcnt lgkmcnt(5)
	v_mfma_f32_32x32x16_bf16 v[34:49], v[188:191], v[196:199], v[34:49]
	global_load_lds_dwordx4 v164, s[100:101]
	s_waitcnt lgkmcnt(4)
	v_mfma_f32_32x32x16_bf16 v[50:65], v[188:191], v[200:203], v[50:65]
	s_add_u32 m0, s32, 0x5000
	v_mfma_f32_32x32x16_bf16 v[2:17], v[192:195], v[196:199], v[2:17]
	global_load_lds_dwordx4 v165, s[100:101]
	v_mfma_f32_32x32x16_bf16 v[18:33], v[192:195], v[200:203], v[18:33]
	s_add_u32 m0, s32, 0x6000
	s_waitcnt lgkmcnt(1)
	v_mfma_f32_32x32x16_bf16 v[34:49], v[232:235], v[240:243], v[34:49]
	global_load_lds_dwordx4 v166, s[100:101]
	s_waitcnt lgkmcnt(0)
	v_mfma_f32_32x32x16_bf16 v[50:65], v[232:235], v[244:247], v[50:65]
	s_add_u32 m0, s32, 0x7000
	v_mfma_f32_32x32x16_bf16 v[2:17], v[236:239], v[240:243], v[2:17]
	global_load_lds_dwordx4 v167, s[100:101]
	v_mfma_f32_32x32x16_bf16 v[18:33], v[236:239], v[244:247], v[18:33]
	s_add_u32 s98, s98, 0x80
	s_addc_u32 s99, s99, 0
	s_add_u32 s100, s100, 0x80
	s_addc_u32 s101, s101, 0
	s_waitcnt vmcnt(0) lgkmcnt(0)
	s_barrier
	ds_read_b128 v[188:191], v156
	ds_read_b128 v[192:195], v156 offset:4096
	ds_read_b128 v[196:199], v160 offset:16384
	ds_read_b128 v[200:203], v160 offset:20480
	ds_read_b128 v[232:235], v157
	ds_read_b128 v[236:239], v157 offset:4096
	ds_read_b128 v[240:243], v161 offset:16384
	ds_read_b128 v[244:247], v161 offset:20480
	s_add_u32 m0, s32, 0x8000
	s_waitcnt lgkmcnt(5)
	v_mfma_f32_32x32x16_bf16 v[34:49], v[188:191], v[196:199], v[34:49]
	global_load_lds_dwordx4 v164, s[98:99]
	s_waitcnt lgkmcnt(4)
	v_mfma_f32_32x32x16_bf16 v[50:65], v[188:191], v[200:203], v[50:65]
	s_add_u32 m0, s32, 0x9000
	v_mfma_f32_32x32x16_bf16 v[2:17], v[192:195], v[196:199], v[2:17]
	global_load_lds_dwordx4 v165, s[98:99]
	v_mfma_f32_32x32x16_bf16 v[18:33], v[192:195], v[200:203], v[18:33]
	ds_read_b128 v[188:191], v158
	ds_read_b128 v[192:195], v158 offset:4096
	ds_read_b128 v[196:199], v162 offset:16384
	ds_read_b128 v[200:203], v162 offset:20480
	s_add_u32 m0, s32, 0xa000
	s_waitcnt lgkmcnt(5)
	v_mfma_f32_32x32x16_bf16 v[34:49], v[232:235], v[240:243], v[34:49]
	global_load_lds_dwordx4 v166, s[98:99]
	s_waitcnt lgkmcnt(4)
	v_mfma_f32_32x32x16_bf16 v[50:65], v[232:235], v[244:247], v[50:65]
	s_add_u32 m0, s32, 0xb000
	v_mfma_f32_32x32x16_bf16 v[2:17], v[236:239], v[240:243], v[2:17]
	global_load_lds_dwordx4 v167, s[98:99]
	v_mfma_f32_32x32x16_bf16 v[18:33], v[236:239], v[244:247], v[18:33]
	ds_read_b128 v[232:235], v159
	ds_read_b128 v[236:239], v159 offset:4096
	ds_read_b128 v[240:243], v163 offset:16384
	ds_read_b128 v[244:247], v163 offset:20480
	s_add_u32 m0, s32, 0xc000
	s_waitcnt lgkmcnt(5)
	v_mfma_f32_32x32x16_bf16 v[34:49], v[188:191], v[196:199], v[34:49]
	global_load_lds_dwordx4 v164, s[100:101]
	s_waitcnt lgkmcnt(4)
	v_mfma_f32_32x32x16_bf16 v[50:65], v[188:191], v[200:203], v[50:65]
	s_add_u32 m0, s32, 0xd000
	v_mfma_f32_32x32x16_bf16 v[2:17], v[192:195], v[196:199], v[2:17]
	global_load_lds_dwordx4 v165, s[100:101]
	v_mfma_f32_32x32x16_bf16 v[18:33], v[192:195], v[200:203], v[18:33]
	s_add_u32 m0, s32, 0xe000
	s_waitcnt lgkmcnt(1)
	v_mfma_f32_32x32x16_bf16 v[34:49], v[232:235], v[240:243], v[34:49]
	global_load_lds_dwordx4 v166, s[100:101]
	s_waitcnt lgkmcnt(0)
	v_mfma_f32_32x32x16_bf16 v[50:65], v[232:235], v[244:247], v[50:65]
	s_add_u32 m0, s32, 0xf000
	v_mfma_f32_32x32x16_bf16 v[2:17], v[236:239], v[240:243], v[2:17]
	global_load_lds_dwordx4 v167, s[100:101]
	v_mfma_f32_32x32x16_bf16 v[18:33], v[236:239], v[244:247], v[18:33]
	s_add_u32 s98, s98, 0x80
	s_addc_u32 s99, s99, 0
	s_add_u32 s100, s100, 0x80
	s_addc_u32 s101, s101, 0
	s_waitcnt vmcnt(0) lgkmcnt(0)
	s_barrier
	ds_read_b128 v[188:191], v156 offset:32768
	ds_read_b128 v[192:195], v156 offset:36864
	ds_read_b128 v[196:199], v160 offset:49152
	ds_read_b128 v[200:203], v160 offset:53248
	ds_read_b128 v[232:235], v157 offset:32768
	ds_read_b128 v[236:239], v157 offset:36864
	ds_read_b128 v[240:243], v161 offset:49152
	ds_read_b128 v[244:247], v161 offset:53248
	s_mov_b32 m0, s32
	s_waitcnt lgkmcnt(5)
	v_mfma_f32_32x32x16_bf16 v[34:49], v[188:191], v[196:199], v[34:49]
	global_load_lds_dwordx4 v164, s[98:99]
	s_waitcnt lgkmcnt(4)
	v_mfma_f32_32x32x16_bf16 v[50:65], v[188:191], v[200:203], v[50:65]
	s_add_u32 m0, s32, 0x1000
	v_mfma_f32_32x32x16_bf16 v[2:17], v[192:195], v[196:199], v[2:17]
	global_load_lds_dwordx4 v165, s[98:99]
	v_mfma_f32_32x32x16_bf16 v[18:33], v[192:195], v[200:203], v[18:33]
	ds_read_b128 v[188:191], v158 offset:32768
	ds_read_b128 v[192:195], v158 offset:36864
	ds_read_b128 v[196:199], v162 offset:49152
	ds_read_b128 v[200:203], v162 offset:53248
	s_add_u32 m0, s32, 0x2000
	s_waitcnt lgkmcnt(5)
	v_mfma_f32_32x32x16_bf16 v[34:49], v[232:235], v[240:243], v[34:49]
	global_load_lds_dwordx4 v166, s[98:99]
	s_waitcnt lgkmcnt(4)
	v_mfma_f32_32x32x16_bf16 v[50:65], v[232:235], v[244:247], v[50:65]
	s_add_u32 m0, s32, 0x3000
	v_mfma_f32_32x32x16_bf16 v[2:17], v[236:239], v[240:243], v[2:17]
	global_load_lds_dwordx4 v167, s[98:99]
	v_mfma_f32_32x32x16_bf16 v[18:33], v[236:239], v[244:247], v[18:33]
	ds_read_b128 v[232:235], v159 offset:32768
	ds_read_b128 v[236:239], v159 offset:36864
	ds_read_b128 v[240:243], v163 offset:49152
	ds_read_b128 v[244:247], v163 offset:53248
	s_add_u32 m0, s32, 0x4000
	s_waitcnt lgkmcnt(5)
	v_mfma_f32_32x32x16_bf16 v[34:49], v[188:191], v[196:199], v[34:49]
	global_load_lds_dwordx4 v164, s[100:101]
	s_waitcnt lgkmcnt(4)
	v_mfma_f32_32x32x16_bf16 v[50:65], v[188:191], v[200:203], v[50:65]
	s_add_u32 m0, s32, 0x5000
	v_mfma_f32_32x32x16_bf16 v[2:17], v[192:195], v[196:199], v[2:17]
	global_load_lds_dwordx4 v165, s[100:101]
	v_mfma_f32_32x32x16_bf16 v[18:33], v[192:195], v[200:203], v[18:33]
	s_add_u32 m0, s32, 0x6000
	s_waitcnt lgkmcnt(1)
	v_mfma_f32_32x32x16_bf16 v[34:49], v[232:235], v[240:243], v[34:49]
	global_load_lds_dwordx4 v166, s[100:101]
	s_waitcnt lgkmcnt(0)
	v_mfma_f32_32x32x16_bf16 v[50:65], v[232:235], v[244:247], v[50:65]
	s_add_u32 m0, s32, 0x7000
	v_mfma_f32_32x32x16_bf16 v[2:17], v[236:239], v[240:243], v[2:17]
	global_load_lds_dwordx4 v167, s[100:101]
	v_mfma_f32_32x32x16_bf16 v[18:33], v[236:239], v[244:247], v[18:33]
	s_add_u32 s98, s98, 0x80
	s_addc_u32 s99, s99, 0
	s_add_u32 s100, s100, 0x80
	s_addc_u32 s101, s101, 0
	s_waitcnt vmcnt(0) lgkmcnt(0)
	s_barrier
	ds_read_b128 v[188:191], v156
	ds_read_b128 v[192:195], v156 offset:4096
	ds_read_b128 v[196:199], v160 offset:16384
	ds_read_b128 v[200:203], v160 offset:20480
	ds_read_b128 v[232:235], v157
	ds_read_b128 v[236:239], v157 offset:4096
	ds_read_b128 v[240:243], v161 offset:16384
	ds_read_b128 v[244:247], v161 offset:20480
	s_add_u32 m0, s32, 0x8000
	s_waitcnt lgkmcnt(5)
	v_mfma_f32_32x32x16_bf16 v[34:49], v[188:191], v[196:199], v[34:49]
	global_load_lds_dwordx4 v164, s[98:99]
	s_waitcnt lgkmcnt(4)
	v_mfma_f32_32x32x16_bf16 v[50:65], v[188:191], v[200:203], v[50:65]
	s_add_u32 m0, s32, 0x9000
	v_mfma_f32_32x32x16_bf16 v[2:17], v[192:195], v[196:199], v[2:17]
	global_load_lds_dwordx4 v165, s[98:99]
	v_mfma_f32_32x32x16_bf16 v[18:33], v[192:195], v[200:203], v[18:33]
	ds_read_b128 v[188:191], v158
	ds_read_b128 v[192:195], v158 offset:4096
	ds_read_b128 v[196:199], v162 offset:16384
	ds_read_b128 v[200:203], v162 offset:20480
	s_add_u32 m0, s32, 0xa000
	s_waitcnt lgkmcnt(5)
	v_mfma_f32_32x32x16_bf16 v[34:49], v[232:235], v[240:243], v[34:49]
	global_load_lds_dwordx4 v166, s[98:99]
	s_waitcnt lgkmcnt(4)
	v_mfma_f32_32x32x16_bf16 v[50:65], v[232:235], v[244:247], v[50:65]
	s_add_u32 m0, s32, 0xb000
	v_mfma_f32_32x32x16_bf16 v[2:17], v[236:239], v[240:243], v[2:17]
	global_load_lds_dwordx4 v167, s[98:99]
	v_mfma_f32_32x32x16_bf16 v[18:33], v[236:239], v[244:247], v[18:33]
	ds_read_b128 v[232:235], v159
	ds_read_b128 v[236:239], v159 offset:4096
	ds_read_b128 v[240:243], v163 offset:16384
	ds_read_b128 v[244:247], v163 offset:20480
	s_add_u32 m0, s32, 0xc000
	s_waitcnt lgkmcnt(5)
	v_mfma_f32_32x32x16_bf16 v[34:49], v[188:191], v[196:199], v[34:49]
	global_load_lds_dwordx4 v164, s[100:101]
	s_waitcnt lgkmcnt(4)
	v_mfma_f32_32x32x16_bf16 v[50:65], v[188:191], v[200:203], v[50:65]
	s_add_u32 m0, s32, 0xd000
	v_mfma_f32_32x32x16_bf16 v[2:17], v[192:195], v[196:199], v[2:17]
	global_load_lds_dwordx4 v165, s[100:101]
	v_mfma_f32_32x32x16_bf16 v[18:33], v[192:195], v[200:203], v[18:33]
	s_add_u32 m0, s32, 0xe000
	s_waitcnt lgkmcnt(1)
	v_mfma_f32_32x32x16_bf16 v[34:49], v[232:235], v[240:243], v[34:49]
	global_load_lds_dwordx4 v166, s[100:101]
	s_waitcnt lgkmcnt(0)
	v_mfma_f32_32x32x16_bf16 v[50:65], v[232:235], v[244:247], v[50:65]
	s_add_u32 m0, s32, 0xf000
	v_mfma_f32_32x32x16_bf16 v[2:17], v[236:239], v[240:243], v[2:17]
	global_load_lds_dwordx4 v167, s[100:101]
	v_mfma_f32_32x32x16_bf16 v[18:33], v[236:239], v[244:247], v[18:33]
	s_add_u32 s98, s98, 0x80
	s_addc_u32 s99, s99, 0
	s_add_u32 s100, s100, 0x80
	s_addc_u32 s101, s101, 0
	s_waitcnt vmcnt(0) lgkmcnt(0)
	s_barrier
	ds_read_b128 v[188:191], v156 offset:32768
	ds_read_b128 v[192:195], v156 offset:36864
	ds_read_b128 v[196:199], v160 offset:49152
	ds_read_b128 v[200:203], v160 offset:53248
	ds_read_b128 v[232:235], v157 offset:32768
	ds_read_b128 v[236:239], v157 offset:36864
	ds_read_b128 v[240:243], v161 offset:49152
	ds_read_b128 v[244:247], v161 offset:53248
	s_mov_b32 m0, s32
	s_waitcnt lgkmcnt(5)
	v_mfma_f32_32x32x16_bf16 v[34:49], v[188:191], v[196:199], v[34:49]
	global_load_lds_dwordx4 v164, s[98:99]
	s_waitcnt lgkmcnt(4)
	v_mfma_f32_32x32x16_bf16 v[50:65], v[188:191], v[200:203], v[50:65]
	s_add_u32 m0, s32, 0x1000
	v_mfma_f32_32x32x16_bf16 v[2:17], v[192:195], v[196:199], v[2:17]
	global_load_lds_dwordx4 v165, s[98:99]
	v_mfma_f32_32x32x16_bf16 v[18:33], v[192:195], v[200:203], v[18:33]
	ds_read_b128 v[188:191], v158 offset:32768
	ds_read_b128 v[192:195], v158 offset:36864
	ds_read_b128 v[196:199], v162 offset:49152
	ds_read_b128 v[200:203], v162 offset:53248
	s_add_u32 m0, s32, 0x2000
	s_waitcnt lgkmcnt(5)
	v_mfma_f32_32x32x16_bf16 v[34:49], v[232:235], v[240:243], v[34:49]
	global_load_lds_dwordx4 v166, s[98:99]
	s_waitcnt lgkmcnt(4)
	v_mfma_f32_32x32x16_bf16 v[50:65], v[232:235], v[244:247], v[50:65]
	s_add_u32 m0, s32, 0x3000
	v_mfma_f32_32x32x16_bf16 v[2:17], v[236:239], v[240:243], v[2:17]
	global_load_lds_dwordx4 v167, s[98:99]
	v_mfma_f32_32x32x16_bf16 v[18:33], v[236:239], v[244:247], v[18:33]
	ds_read_b128 v[232:235], v159 offset:32768
	ds_read_b128 v[236:239], v159 offset:36864
	ds_read_b128 v[240:243], v163 offset:49152
	ds_read_b128 v[244:247], v163 offset:53248
	s_add_u32 m0, s32, 0x4000
	s_waitcnt lgkmcnt(5)
	v_mfma_f32_32x32x16_bf16 v[34:49], v[188:191], v[196:199], v[34:49]
	global_load_lds_dwordx4 v164, s[100:101]
	s_waitcnt lgkmcnt(4)
	v_mfma_f32_32x32x16_bf16 v[50:65], v[188:191], v[200:203], v[50:65]
	s_add_u32 m0, s32, 0x5000
	v_mfma_f32_32x32x16_bf16 v[2:17], v[192:195], v[196:199], v[2:17]
	global_load_lds_dwordx4 v165, s[100:101]
	v_mfma_f32_32x32x16_bf16 v[18:33], v[192:195], v[200:203], v[18:33]
	s_add_u32 m0, s32, 0x6000
	s_waitcnt lgkmcnt(1)
	v_mfma_f32_32x32x16_bf16 v[34:49], v[232:235], v[240:243], v[34:49]
	global_load_lds_dwordx4 v166, s[100:101]
	s_waitcnt lgkmcnt(0)
	v_mfma_f32_32x32x16_bf16 v[50:65], v[232:235], v[244:247], v[50:65]
	s_add_u32 m0, s32, 0x7000
	v_mfma_f32_32x32x16_bf16 v[2:17], v[236:239], v[240:243], v[2:17]
	global_load_lds_dwordx4 v167, s[100:101]
	v_mfma_f32_32x32x16_bf16 v[18:33], v[236:239], v[244:247], v[18:33]
	s_add_u32 s98, s98, 0x80
	s_addc_u32 s99, s99, 0
	s_add_u32 s100, s100, 0x80
	s_addc_u32 s101, s101, 0
	s_waitcnt vmcnt(0) lgkmcnt(0)
	s_barrier
	ds_read_b128 v[188:191], v156
	ds_read_b128 v[192:195], v156 offset:4096
	ds_read_b128 v[196:199], v160 offset:16384
	ds_read_b128 v[200:203], v160 offset:20480
	ds_read_b128 v[232:235], v157
	ds_read_b128 v[236:239], v157 offset:4096
	ds_read_b128 v[240:243], v161 offset:16384
	ds_read_b128 v[244:247], v161 offset:20480
	s_add_u32 m0, s32, 0x8000
	s_waitcnt lgkmcnt(5)
	v_mfma_f32_32x32x16_bf16 v[34:49], v[188:191], v[196:199], v[34:49]
	global_load_lds_dwordx4 v164, s[98:99]
	s_waitcnt lgkmcnt(4)
	v_mfma_f32_32x32x16_bf16 v[50:65], v[188:191], v[200:203], v[50:65]
	s_add_u32 m0, s32, 0x9000
	v_mfma_f32_32x32x16_bf16 v[2:17], v[192:195], v[196:199], v[2:17]
	global_load_lds_dwordx4 v165, s[98:99]
	v_mfma_f32_32x32x16_bf16 v[18:33], v[192:195], v[200:203], v[18:33]
	ds_read_b128 v[188:191], v158
	ds_read_b128 v[192:195], v158 offset:4096
	ds_read_b128 v[196:199], v162 offset:16384
	ds_read_b128 v[200:203], v162 offset:20480
	s_add_u32 m0, s32, 0xa000
	s_waitcnt lgkmcnt(5)
	v_mfma_f32_32x32x16_bf16 v[34:49], v[232:235], v[240:243], v[34:49]
	global_load_lds_dwordx4 v166, s[98:99]
	s_waitcnt lgkmcnt(4)
	v_mfma_f32_32x32x16_bf16 v[50:65], v[232:235], v[244:247], v[50:65]
	s_add_u32 m0, s32, 0xb000
	v_mfma_f32_32x32x16_bf16 v[2:17], v[236:239], v[240:243], v[2:17]
	global_load_lds_dwordx4 v167, s[98:99]
	v_mfma_f32_32x32x16_bf16 v[18:33], v[236:239], v[244:247], v[18:33]
	ds_read_b128 v[232:235], v159
	ds_read_b128 v[236:239], v159 offset:4096
	ds_read_b128 v[240:243], v163 offset:16384
	ds_read_b128 v[244:247], v163 offset:20480
	s_add_u32 m0, s32, 0xc000
	s_waitcnt lgkmcnt(5)
	v_mfma_f32_32x32x16_bf16 v[34:49], v[188:191], v[196:199], v[34:49]
	global_load_lds_dwordx4 v164, s[100:101]
	s_waitcnt lgkmcnt(4)
	v_mfma_f32_32x32x16_bf16 v[50:65], v[188:191], v[200:203], v[50:65]
	s_add_u32 m0, s32, 0xd000
	v_mfma_f32_32x32x16_bf16 v[2:17], v[192:195], v[196:199], v[2:17]
	global_load_lds_dwordx4 v165, s[100:101]
	v_mfma_f32_32x32x16_bf16 v[18:33], v[192:195], v[200:203], v[18:33]
	s_add_u32 m0, s32, 0xe000
	s_waitcnt lgkmcnt(1)
	v_mfma_f32_32x32x16_bf16 v[34:49], v[232:235], v[240:243], v[34:49]
	global_load_lds_dwordx4 v166, s[100:101]
	s_waitcnt lgkmcnt(0)
	v_mfma_f32_32x32x16_bf16 v[50:65], v[232:235], v[244:247], v[50:65]
	s_add_u32 m0, s32, 0xf000
	v_mfma_f32_32x32x16_bf16 v[2:17], v[236:239], v[240:243], v[2:17]
	global_load_lds_dwordx4 v167, s[100:101]
	v_mfma_f32_32x32x16_bf16 v[18:33], v[236:239], v[244:247], v[18:33]
	s_add_u32 s98, s98, 0x80
	s_addc_u32 s99, s99, 0
	s_add_u32 s100, s100, 0x80
	s_addc_u32 s101, s101, 0
	s_waitcnt vmcnt(0) lgkmcnt(0)
	s_barrier
	ds_read_b128 v[188:191], v156 offset:32768
	ds_read_b128 v[192:195], v156 offset:36864
	ds_read_b128 v[196:199], v160 offset:49152
	ds_read_b128 v[200:203], v160 offset:53248
	ds_read_b128 v[232:235], v157 offset:32768
	ds_read_b128 v[236:239], v157 offset:36864
	ds_read_b128 v[240:243], v161 offset:49152
	ds_read_b128 v[244:247], v161 offset:53248
	s_mov_b32 m0, s32
	s_waitcnt lgkmcnt(5)
	v_mfma_f32_32x32x16_bf16 v[34:49], v[188:191], v[196:199], v[34:49]
	global_load_lds_dwordx4 v164, s[98:99]
	s_waitcnt lgkmcnt(4)
	v_mfma_f32_32x32x16_bf16 v[50:65], v[188:191], v[200:203], v[50:65]
	s_add_u32 m0, s32, 0x1000
	v_mfma_f32_32x32x16_bf16 v[2:17], v[192:195], v[196:199], v[2:17]
	global_load_lds_dwordx4 v165, s[98:99]
	v_mfma_f32_32x32x16_bf16 v[18:33], v[192:195], v[200:203], v[18:33]
	ds_read_b128 v[188:191], v158 offset:32768
	ds_read_b128 v[192:195], v158 offset:36864
	ds_read_b128 v[196:199], v162 offset:49152
	ds_read_b128 v[200:203], v162 offset:53248
	s_add_u32 m0, s32, 0x2000
	s_waitcnt lgkmcnt(5)
	v_mfma_f32_32x32x16_bf16 v[34:49], v[232:235], v[240:243], v[34:49]
	global_load_lds_dwordx4 v166, s[98:99]
	s_waitcnt lgkmcnt(4)
	v_mfma_f32_32x32x16_bf16 v[50:65], v[232:235], v[244:247], v[50:65]
	s_add_u32 m0, s32, 0x3000
	v_mfma_f32_32x32x16_bf16 v[2:17], v[236:239], v[240:243], v[2:17]
	global_load_lds_dwordx4 v167, s[98:99]
	v_mfma_f32_32x32x16_bf16 v[18:33], v[236:239], v[244:247], v[18:33]
	ds_read_b128 v[232:235], v159 offset:32768
	ds_read_b128 v[236:239], v159 offset:36864
	ds_read_b128 v[240:243], v163 offset:49152
	ds_read_b128 v[244:247], v163 offset:53248
	s_add_u32 m0, s32, 0x4000
	s_waitcnt lgkmcnt(5)
	v_mfma_f32_32x32x16_bf16 v[34:49], v[188:191], v[196:199], v[34:49]
	global_load_lds_dwordx4 v164, s[100:101]
	s_waitcnt lgkmcnt(4)
	v_mfma_f32_32x32x16_bf16 v[50:65], v[188:191], v[200:203], v[50:65]
	s_add_u32 m0, s32, 0x5000
	v_mfma_f32_32x32x16_bf16 v[2:17], v[192:195], v[196:199], v[2:17]
	global_load_lds_dwordx4 v165, s[100:101]
	v_mfma_f32_32x32x16_bf16 v[18:33], v[192:195], v[200:203], v[18:33]
	s_add_u32 m0, s32, 0x6000
	s_waitcnt lgkmcnt(1)
	v_mfma_f32_32x32x16_bf16 v[34:49], v[232:235], v[240:243], v[34:49]
	global_load_lds_dwordx4 v166, s[100:101]
	s_waitcnt lgkmcnt(0)
	v_mfma_f32_32x32x16_bf16 v[50:65], v[232:235], v[244:247], v[50:65]
	s_add_u32 m0, s32, 0x7000
	v_mfma_f32_32x32x16_bf16 v[2:17], v[236:239], v[240:243], v[2:17]
	global_load_lds_dwordx4 v167, s[100:101]
	v_mfma_f32_32x32x16_bf16 v[18:33], v[236:239], v[244:247], v[18:33]
	s_add_u32 s98, s98, 0x80
	s_addc_u32 s99, s99, 0
	s_add_u32 s100, s100, 0x80
	s_addc_u32 s101, s101, 0
	s_waitcnt vmcnt(0) lgkmcnt(0)
	s_barrier
	ds_read_b128 v[188:191], v156
	ds_read_b128 v[192:195], v156 offset:4096
	ds_read_b128 v[196:199], v160 offset:16384
	ds_read_b128 v[200:203], v160 offset:20480
	ds_read_b128 v[232:235], v157
	ds_read_b128 v[236:239], v157 offset:4096
	ds_read_b128 v[240:243], v161 offset:16384
	ds_read_b128 v[244:247], v161 offset:20480
	s_add_u32 m0, s32, 0x8000
	s_waitcnt lgkmcnt(5)
	v_mfma_f32_32x32x16_bf16 v[34:49], v[188:191], v[196:199], v[34:49]
	global_load_lds_dwordx4 v164, s[98:99]
	s_waitcnt lgkmcnt(4)
	v_mfma_f32_32x32x16_bf16 v[50:65], v[188:191], v[200:203], v[50:65]
	s_add_u32 m0, s32, 0x9000
	v_mfma_f32_32x32x16_bf16 v[2:17], v[192:195], v[196:199], v[2:17]
	global_load_lds_dwordx4 v165, s[98:99]
	v_mfma_f32_32x32x16_bf16 v[18:33], v[192:195], v[200:203], v[18:33]
	ds_read_b128 v[188:191], v158
	ds_read_b128 v[192:195], v158 offset:4096
	ds_read_b128 v[196:199], v162 offset:16384
	ds_read_b128 v[200:203], v162 offset:20480
	s_add_u32 m0, s32, 0xa000
	s_waitcnt lgkmcnt(5)
	v_mfma_f32_32x32x16_bf16 v[34:49], v[232:235], v[240:243], v[34:49]
	global_load_lds_dwordx4 v166, s[98:99]
	s_waitcnt lgkmcnt(4)
	v_mfma_f32_32x32x16_bf16 v[50:65], v[232:235], v[244:247], v[50:65]
	s_add_u32 m0, s32, 0xb000
	v_mfma_f32_32x32x16_bf16 v[2:17], v[236:239], v[240:243], v[2:17]
	global_load_lds_dwordx4 v167, s[98:99]
	v_mfma_f32_32x32x16_bf16 v[18:33], v[236:239], v[244:247], v[18:33]
	ds_read_b128 v[232:235], v159
	ds_read_b128 v[236:239], v159 offset:4096
	ds_read_b128 v[240:243], v163 offset:16384
	ds_read_b128 v[244:247], v163 offset:20480
	s_add_u32 m0, s32, 0xc000
	s_waitcnt lgkmcnt(5)
	v_mfma_f32_32x32x16_bf16 v[34:49], v[188:191], v[196:199], v[34:49]
	global_load_lds_dwordx4 v164, s[100:101]
	s_waitcnt lgkmcnt(4)
	v_mfma_f32_32x32x16_bf16 v[50:65], v[188:191], v[200:203], v[50:65]
	s_add_u32 m0, s32, 0xd000
	v_mfma_f32_32x32x16_bf16 v[2:17], v[192:195], v[196:199], v[2:17]
	global_load_lds_dwordx4 v165, s[100:101]
	v_mfma_f32_32x32x16_bf16 v[18:33], v[192:195], v[200:203], v[18:33]
	s_add_u32 m0, s32, 0xe000
	s_waitcnt lgkmcnt(1)
	v_mfma_f32_32x32x16_bf16 v[34:49], v[232:235], v[240:243], v[34:49]
	global_load_lds_dwordx4 v166, s[100:101]
	s_waitcnt lgkmcnt(0)
	v_mfma_f32_32x32x16_bf16 v[50:65], v[232:235], v[244:247], v[50:65]
	s_add_u32 m0, s32, 0xf000
	v_mfma_f32_32x32x16_bf16 v[2:17], v[236:239], v[240:243], v[2:17]
	global_load_lds_dwordx4 v167, s[100:101]
	v_mfma_f32_32x32x16_bf16 v[18:33], v[236:239], v[244:247], v[18:33]
	s_add_u32 s98, s98, 0x80
	s_addc_u32 s99, s99, 0
	s_add_u32 s100, s100, 0x80
	s_addc_u32 s101, s101, 0
	s_waitcnt vmcnt(0) lgkmcnt(0)
	s_barrier
	ds_read_b128 v[188:191], v156 offset:32768
	ds_read_b128 v[192:195], v156 offset:36864
	ds_read_b128 v[196:199], v160 offset:49152
	ds_read_b128 v[200:203], v160 offset:53248
	ds_read_b128 v[232:235], v157 offset:32768
	ds_read_b128 v[236:239], v157 offset:36864
	ds_read_b128 v[240:243], v161 offset:49152
	ds_read_b128 v[244:247], v161 offset:53248
	s_mov_b32 m0, s32
	s_waitcnt lgkmcnt(5)
	v_mfma_f32_32x32x16_bf16 v[34:49], v[188:191], v[196:199], v[34:49]
	global_load_lds_dwordx4 v164, s[98:99]
	s_waitcnt lgkmcnt(4)
	v_mfma_f32_32x32x16_bf16 v[50:65], v[188:191], v[200:203], v[50:65]
	s_add_u32 m0, s32, 0x1000
	v_mfma_f32_32x32x16_bf16 v[2:17], v[192:195], v[196:199], v[2:17]
	global_load_lds_dwordx4 v165, s[98:99]
	v_mfma_f32_32x32x16_bf16 v[18:33], v[192:195], v[200:203], v[18:33]
	ds_read_b128 v[188:191], v158 offset:32768
	ds_read_b128 v[192:195], v158 offset:36864
	ds_read_b128 v[196:199], v162 offset:49152
	ds_read_b128 v[200:203], v162 offset:53248
	s_add_u32 m0, s32, 0x2000
	s_waitcnt lgkmcnt(5)
	v_mfma_f32_32x32x16_bf16 v[34:49], v[232:235], v[240:243], v[34:49]
	global_load_lds_dwordx4 v166, s[98:99]
	s_waitcnt lgkmcnt(4)
	v_mfma_f32_32x32x16_bf16 v[50:65], v[232:235], v[244:247], v[50:65]
	s_add_u32 m0, s32, 0x3000
	v_mfma_f32_32x32x16_bf16 v[2:17], v[236:239], v[240:243], v[2:17]
	global_load_lds_dwordx4 v167, s[98:99]
	v_mfma_f32_32x32x16_bf16 v[18:33], v[236:239], v[244:247], v[18:33]
	ds_read_b128 v[232:235], v159 offset:32768
	ds_read_b128 v[236:239], v159 offset:36864
	ds_read_b128 v[240:243], v163 offset:49152
	ds_read_b128 v[244:247], v163 offset:53248
	s_add_u32 m0, s32, 0x4000
	s_waitcnt lgkmcnt(5)
	v_mfma_f32_32x32x16_bf16 v[34:49], v[188:191], v[196:199], v[34:49]
	global_load_lds_dwordx4 v164, s[100:101]
	s_waitcnt lgkmcnt(4)
	v_mfma_f32_32x32x16_bf16 v[50:65], v[188:191], v[200:203], v[50:65]
	s_add_u32 m0, s32, 0x5000
	v_mfma_f32_32x32x16_bf16 v[2:17], v[192:195], v[196:199], v[2:17]
	global_load_lds_dwordx4 v165, s[100:101]
	v_mfma_f32_32x32x16_bf16 v[18:33], v[192:195], v[200:203], v[18:33]
	s_add_u32 m0, s32, 0x6000
	s_waitcnt lgkmcnt(1)
	v_mfma_f32_32x32x16_bf16 v[34:49], v[232:235], v[240:243], v[34:49]
	global_load_lds_dwordx4 v166, s[100:101]
	s_waitcnt lgkmcnt(0)
	v_mfma_f32_32x32x16_bf16 v[50:65], v[232:235], v[244:247], v[50:65]
	s_add_u32 m0, s32, 0x7000
	v_mfma_f32_32x32x16_bf16 v[2:17], v[236:239], v[240:243], v[2:17]
	global_load_lds_dwordx4 v167, s[100:101]
	v_mfma_f32_32x32x16_bf16 v[18:33], v[236:239], v[244:247], v[18:33]
	s_add_u32 s98, s98, 0x80
	s_addc_u32 s99, s99, 0
	s_add_u32 s100, s100, 0x80
	s_addc_u32 s101, s101, 0
	s_waitcnt vmcnt(0) lgkmcnt(0)
	s_barrier
	ds_read_b128 v[188:191], v156
	ds_read_b128 v[192:195], v156 offset:4096
	ds_read_b128 v[196:199], v160 offset:16384
	ds_read_b128 v[200:203], v160 offset:20480
	ds_read_b128 v[232:235], v157
	ds_read_b128 v[236:239], v157 offset:4096
	ds_read_b128 v[240:243], v161 offset:16384
	ds_read_b128 v[244:247], v161 offset:20480
	s_add_u32 m0, s32, 0x8000
	s_waitcnt lgkmcnt(5)
	v_mfma_f32_32x32x16_bf16 v[34:49], v[188:191], v[196:199], v[34:49]
	global_load_lds_dwordx4 v164, s[98:99]
	s_waitcnt lgkmcnt(4)
	v_mfma_f32_32x32x16_bf16 v[50:65], v[188:191], v[200:203], v[50:65]
	s_add_u32 m0, s32, 0x9000
	v_mfma_f32_32x32x16_bf16 v[2:17], v[192:195], v[196:199], v[2:17]
	global_load_lds_dwordx4 v165, s[98:99]
	v_mfma_f32_32x32x16_bf16 v[18:33], v[192:195], v[200:203], v[18:33]
	ds_read_b128 v[188:191], v158
	ds_read_b128 v[192:195], v158 offset:4096
	ds_read_b128 v[196:199], v162 offset:16384
	ds_read_b128 v[200:203], v162 offset:20480
	s_add_u32 m0, s32, 0xa000
	s_waitcnt lgkmcnt(5)
	v_mfma_f32_32x32x16_bf16 v[34:49], v[232:235], v[240:243], v[34:49]
	global_load_lds_dwordx4 v166, s[98:99]
	s_waitcnt lgkmcnt(4)
	v_mfma_f32_32x32x16_bf16 v[50:65], v[232:235], v[244:247], v[50:65]
	s_add_u32 m0, s32, 0xb000
	v_mfma_f32_32x32x16_bf16 v[2:17], v[236:239], v[240:243], v[2:17]
	global_load_lds_dwordx4 v167, s[98:99]
	v_mfma_f32_32x32x16_bf16 v[18:33], v[236:239], v[244:247], v[18:33]
	ds_read_b128 v[232:235], v159
	ds_read_b128 v[236:239], v159 offset:4096
	ds_read_b128 v[240:243], v163 offset:16384
	ds_read_b128 v[244:247], v163 offset:20480
	s_add_u32 m0, s32, 0xc000
	s_waitcnt lgkmcnt(5)
	v_mfma_f32_32x32x16_bf16 v[34:49], v[188:191], v[196:199], v[34:49]
	global_load_lds_dwordx4 v164, s[100:101]
	s_waitcnt lgkmcnt(4)
	v_mfma_f32_32x32x16_bf16 v[50:65], v[188:191], v[200:203], v[50:65]
	s_add_u32 m0, s32, 0xd000
	v_mfma_f32_32x32x16_bf16 v[2:17], v[192:195], v[196:199], v[2:17]
	global_load_lds_dwordx4 v165, s[100:101]
	v_mfma_f32_32x32x16_bf16 v[18:33], v[192:195], v[200:203], v[18:33]
	s_add_u32 m0, s32, 0xe000
	s_waitcnt lgkmcnt(1)
	v_mfma_f32_32x32x16_bf16 v[34:49], v[232:235], v[240:243], v[34:49]
	global_load_lds_dwordx4 v166, s[100:101]
	s_waitcnt lgkmcnt(0)
	v_mfma_f32_32x32x16_bf16 v[50:65], v[232:235], v[244:247], v[50:65]
	s_add_u32 m0, s32, 0xf000
	v_mfma_f32_32x32x16_bf16 v[2:17], v[236:239], v[240:243], v[2:17]
	global_load_lds_dwordx4 v167, s[100:101]
	v_mfma_f32_32x32x16_bf16 v[18:33], v[236:239], v[244:247], v[18:33]
	s_add_u32 s98, s98, 0x80
	s_addc_u32 s99, s99, 0
	s_add_u32 s100, s100, 0x80
	s_addc_u32 s101, s101, 0
	s_waitcnt vmcnt(0) lgkmcnt(0)
	s_barrier
	ds_read_b128 v[188:191], v156 offset:32768
	ds_read_b128 v[192:195], v156 offset:36864
	ds_read_b128 v[196:199], v160 offset:49152
	ds_read_b128 v[200:203], v160 offset:53248
	ds_read_b128 v[232:235], v157 offset:32768
	ds_read_b128 v[236:239], v157 offset:36864
	ds_read_b128 v[240:243], v161 offset:49152
	ds_read_b128 v[244:247], v161 offset:53248
	s_mov_b32 m0, s32
	s_waitcnt lgkmcnt(5)
	v_mfma_f32_32x32x16_bf16 v[34:49], v[188:191], v[196:199], v[34:49]
	global_load_lds_dwordx4 v164, s[98:99]
	s_waitcnt lgkmcnt(4)
	v_mfma_f32_32x32x16_bf16 v[50:65], v[188:191], v[200:203], v[50:65]
	s_add_u32 m0, s32, 0x1000
	v_mfma_f32_32x32x16_bf16 v[2:17], v[192:195], v[196:199], v[2:17]
	global_load_lds_dwordx4 v165, s[98:99]
	v_mfma_f32_32x32x16_bf16 v[18:33], v[192:195], v[200:203], v[18:33]
	ds_read_b128 v[188:191], v158 offset:32768
	ds_read_b128 v[192:195], v158 offset:36864
	ds_read_b128 v[196:199], v162 offset:49152
	ds_read_b128 v[200:203], v162 offset:53248
	s_add_u32 m0, s32, 0x2000
	s_waitcnt lgkmcnt(5)
	v_mfma_f32_32x32x16_bf16 v[34:49], v[232:235], v[240:243], v[34:49]
	global_load_lds_dwordx4 v166, s[98:99]
	s_waitcnt lgkmcnt(4)
	v_mfma_f32_32x32x16_bf16 v[50:65], v[232:235], v[244:247], v[50:65]
	s_add_u32 m0, s32, 0x3000
	v_mfma_f32_32x32x16_bf16 v[2:17], v[236:239], v[240:243], v[2:17]
	global_load_lds_dwordx4 v167, s[98:99]
	v_mfma_f32_32x32x16_bf16 v[18:33], v[236:239], v[244:247], v[18:33]
	ds_read_b128 v[232:235], v159 offset:32768
	ds_read_b128 v[236:239], v159 offset:36864
	ds_read_b128 v[240:243], v163 offset:49152
	ds_read_b128 v[244:247], v163 offset:53248
	s_add_u32 m0, s32, 0x4000
	s_waitcnt lgkmcnt(5)
	v_mfma_f32_32x32x16_bf16 v[34:49], v[188:191], v[196:199], v[34:49]
	global_load_lds_dwordx4 v164, s[100:101]
	s_waitcnt lgkmcnt(4)
	v_mfma_f32_32x32x16_bf16 v[50:65], v[188:191], v[200:203], v[50:65]
	s_add_u32 m0, s32, 0x5000
	v_mfma_f32_32x32x16_bf16 v[2:17], v[192:195], v[196:199], v[2:17]
	global_load_lds_dwordx4 v165, s[100:101]
	v_mfma_f32_32x32x16_bf16 v[18:33], v[192:195], v[200:203], v[18:33]
	s_add_u32 m0, s32, 0x6000
	s_waitcnt lgkmcnt(1)
	v_mfma_f32_32x32x16_bf16 v[34:49], v[232:235], v[240:243], v[34:49]
	global_load_lds_dwordx4 v166, s[100:101]
	s_waitcnt lgkmcnt(0)
	v_mfma_f32_32x32x16_bf16 v[50:65], v[232:235], v[244:247], v[50:65]
	s_add_u32 m0, s32, 0x7000
	v_mfma_f32_32x32x16_bf16 v[2:17], v[236:239], v[240:243], v[2:17]
	global_load_lds_dwordx4 v167, s[100:101]
	v_mfma_f32_32x32x16_bf16 v[18:33], v[236:239], v[244:247], v[18:33]
	s_add_u32 s98, s98, 0x80
	s_addc_u32 s99, s99, 0
	s_add_u32 s100, s100, 0x80
	s_addc_u32 s101, s101, 0
	s_waitcnt vmcnt(0) lgkmcnt(0)
	s_barrier
	ds_read_b128 v[188:191], v156
	ds_read_b128 v[192:195], v156 offset:4096
	ds_read_b128 v[196:199], v160 offset:16384
	ds_read_b128 v[200:203], v160 offset:20480
	ds_read_b128 v[232:235], v157
	ds_read_b128 v[236:239], v157 offset:4096
	ds_read_b128 v[240:243], v161 offset:16384
	ds_read_b128 v[244:247], v161 offset:20480
	s_add_u32 m0, s32, 0x8000
	s_waitcnt lgkmcnt(5)
	v_mfma_f32_32x32x16_bf16 v[34:49], v[188:191], v[196:199], v[34:49]
	global_load_lds_dwordx4 v164, s[98:99]
	s_waitcnt lgkmcnt(4)
	v_mfma_f32_32x32x16_bf16 v[50:65], v[188:191], v[200:203], v[50:65]
	s_add_u32 m0, s32, 0x9000
	v_mfma_f32_32x32x16_bf16 v[2:17], v[192:195], v[196:199], v[2:17]
	global_load_lds_dwordx4 v165, s[98:99]
	v_mfma_f32_32x32x16_bf16 v[18:33], v[192:195], v[200:203], v[18:33]
	ds_read_b128 v[188:191], v158
	ds_read_b128 v[192:195], v158 offset:4096
	ds_read_b128 v[196:199], v162 offset:16384
	ds_read_b128 v[200:203], v162 offset:20480
	s_add_u32 m0, s32, 0xa000
	s_waitcnt lgkmcnt(5)
	v_mfma_f32_32x32x16_bf16 v[34:49], v[232:235], v[240:243], v[34:49]
	global_load_lds_dwordx4 v166, s[98:99]
	s_waitcnt lgkmcnt(4)
	v_mfma_f32_32x32x16_bf16 v[50:65], v[232:235], v[244:247], v[50:65]
	s_add_u32 m0, s32, 0xb000
	v_mfma_f32_32x32x16_bf16 v[2:17], v[236:239], v[240:243], v[2:17]
	global_load_lds_dwordx4 v167, s[98:99]
	v_mfma_f32_32x32x16_bf16 v[18:33], v[236:239], v[244:247], v[18:33]
	ds_read_b128 v[232:235], v159
	ds_read_b128 v[236:239], v159 offset:4096
	ds_read_b128 v[240:243], v163 offset:16384
	ds_read_b128 v[244:247], v163 offset:20480
	s_add_u32 m0, s32, 0xc000
	s_waitcnt lgkmcnt(5)
	v_mfma_f32_32x32x16_bf16 v[34:49], v[188:191], v[196:199], v[34:49]
	global_load_lds_dwordx4 v164, s[100:101]
	s_waitcnt lgkmcnt(4)
	v_mfma_f32_32x32x16_bf16 v[50:65], v[188:191], v[200:203], v[50:65]
	s_add_u32 m0, s32, 0xd000
	v_mfma_f32_32x32x16_bf16 v[2:17], v[192:195], v[196:199], v[2:17]
	global_load_lds_dwordx4 v165, s[100:101]
	v_mfma_f32_32x32x16_bf16 v[18:33], v[192:195], v[200:203], v[18:33]
	s_add_u32 m0, s32, 0xe000
	s_waitcnt lgkmcnt(1)
	v_mfma_f32_32x32x16_bf16 v[34:49], v[232:235], v[240:243], v[34:49]
	global_load_lds_dwordx4 v166, s[100:101]
	s_waitcnt lgkmcnt(0)
	v_mfma_f32_32x32x16_bf16 v[50:65], v[232:235], v[244:247], v[50:65]
	s_add_u32 m0, s32, 0xf000
	v_mfma_f32_32x32x16_bf16 v[2:17], v[236:239], v[240:243], v[2:17]
	global_load_lds_dwordx4 v167, s[100:101]
	v_mfma_f32_32x32x16_bf16 v[18:33], v[236:239], v[244:247], v[18:33]
	s_add_u32 s98, s98, 0x80
	s_addc_u32 s99, s99, 0
	s_add_u32 s100, s100, 0x80
	s_addc_u32 s101, s101, 0
	s_waitcnt vmcnt(0) lgkmcnt(0)
	s_barrier
	ds_read_b128 v[188:191], v156 offset:32768
	ds_read_b128 v[192:195], v156 offset:36864
	ds_read_b128 v[196:199], v160 offset:49152
	ds_read_b128 v[200:203], v160 offset:53248
	ds_read_b128 v[232:235], v157 offset:32768
	ds_read_b128 v[236:239], v157 offset:36864
	ds_read_b128 v[240:243], v161 offset:49152
	ds_read_b128 v[244:247], v161 offset:53248
	s_mov_b32 m0, s32
	s_waitcnt lgkmcnt(5)
	v_mfma_f32_32x32x16_bf16 v[34:49], v[188:191], v[196:199], v[34:49]
	global_load_lds_dwordx4 v164, s[98:99]
	s_waitcnt lgkmcnt(4)
	v_mfma_f32_32x32x16_bf16 v[50:65], v[188:191], v[200:203], v[50:65]
	s_add_u32 m0, s32, 0x1000
	v_mfma_f32_32x32x16_bf16 v[2:17], v[192:195], v[196:199], v[2:17]
	global_load_lds_dwordx4 v165, s[98:99]
	v_mfma_f32_32x32x16_bf16 v[18:33], v[192:195], v[200:203], v[18:33]
	ds_read_b128 v[188:191], v158 offset:32768
	ds_read_b128 v[192:195], v158 offset:36864
	ds_read_b128 v[196:199], v162 offset:49152
	ds_read_b128 v[200:203], v162 offset:53248
	s_add_u32 m0, s32, 0x2000
	s_waitcnt lgkmcnt(5)
	v_mfma_f32_32x32x16_bf16 v[34:49], v[232:235], v[240:243], v[34:49]
	global_load_lds_dwordx4 v166, s[98:99]
	s_waitcnt lgkmcnt(4)
	v_mfma_f32_32x32x16_bf16 v[50:65], v[232:235], v[244:247], v[50:65]
	s_add_u32 m0, s32, 0x3000
	v_mfma_f32_32x32x16_bf16 v[2:17], v[236:239], v[240:243], v[2:17]
	global_load_lds_dwordx4 v167, s[98:99]
	v_mfma_f32_32x32x16_bf16 v[18:33], v[236:239], v[244:247], v[18:33]
	ds_read_b128 v[232:235], v159 offset:32768
	ds_read_b128 v[236:239], v159 offset:36864
	ds_read_b128 v[240:243], v163 offset:49152
	ds_read_b128 v[244:247], v163 offset:53248
	s_add_u32 m0, s32, 0x4000
	s_waitcnt lgkmcnt(5)
	v_mfma_f32_32x32x16_bf16 v[34:49], v[188:191], v[196:199], v[34:49]
	global_load_lds_dwordx4 v164, s[100:101]
	s_waitcnt lgkmcnt(4)
	v_mfma_f32_32x32x16_bf16 v[50:65], v[188:191], v[200:203], v[50:65]
	s_add_u32 m0, s32, 0x5000
	v_mfma_f32_32x32x16_bf16 v[2:17], v[192:195], v[196:199], v[2:17]
	global_load_lds_dwordx4 v165, s[100:101]
	v_mfma_f32_32x32x16_bf16 v[18:33], v[192:195], v[200:203], v[18:33]
	s_add_u32 m0, s32, 0x6000
	s_waitcnt lgkmcnt(1)
	v_mfma_f32_32x32x16_bf16 v[34:49], v[232:235], v[240:243], v[34:49]
	global_load_lds_dwordx4 v166, s[100:101]
	s_waitcnt lgkmcnt(0)
	v_mfma_f32_32x32x16_bf16 v[50:65], v[232:235], v[244:247], v[50:65]
	s_add_u32 m0, s32, 0x7000
	v_mfma_f32_32x32x16_bf16 v[2:17], v[236:239], v[240:243], v[2:17]
	global_load_lds_dwordx4 v167, s[100:101]
	v_mfma_f32_32x32x16_bf16 v[18:33], v[236:239], v[244:247], v[18:33]
	s_add_u32 s98, s98, 0x80
	s_addc_u32 s99, s99, 0
	s_add_u32 s100, s100, 0x80
	s_addc_u32 s101, s101, 0
	s_waitcnt vmcnt(0) lgkmcnt(0)
	s_barrier
	ds_read_b128 v[188:191], v156
	ds_read_b128 v[192:195], v156 offset:4096
	ds_read_b128 v[196:199], v160 offset:16384
	ds_read_b128 v[200:203], v160 offset:20480
	ds_read_b128 v[232:235], v157
	ds_read_b128 v[236:239], v157 offset:4096
	ds_read_b128 v[240:243], v161 offset:16384
	ds_read_b128 v[244:247], v161 offset:20480
	s_add_u32 m0, s32, 0x8000
	s_waitcnt lgkmcnt(5)
	v_mfma_f32_32x32x16_bf16 v[34:49], v[188:191], v[196:199], v[34:49]
	global_load_lds_dwordx4 v164, s[98:99]
	s_waitcnt lgkmcnt(4)
	v_mfma_f32_32x32x16_bf16 v[50:65], v[188:191], v[200:203], v[50:65]
	s_add_u32 m0, s32, 0x9000
	v_mfma_f32_32x32x16_bf16 v[2:17], v[192:195], v[196:199], v[2:17]
	global_load_lds_dwordx4 v165, s[98:99]
	v_mfma_f32_32x32x16_bf16 v[18:33], v[192:195], v[200:203], v[18:33]
	ds_read_b128 v[188:191], v158
	ds_read_b128 v[192:195], v158 offset:4096
	ds_read_b128 v[196:199], v162 offset:16384
	ds_read_b128 v[200:203], v162 offset:20480
	s_add_u32 m0, s32, 0xa000
	s_waitcnt lgkmcnt(5)
	v_mfma_f32_32x32x16_bf16 v[34:49], v[232:235], v[240:243], v[34:49]
	global_load_lds_dwordx4 v166, s[98:99]
	s_waitcnt lgkmcnt(4)
	v_mfma_f32_32x32x16_bf16 v[50:65], v[232:235], v[244:247], v[50:65]
	s_add_u32 m0, s32, 0xb000
	v_mfma_f32_32x32x16_bf16 v[2:17], v[236:239], v[240:243], v[2:17]
	global_load_lds_dwordx4 v167, s[98:99]
	v_mfma_f32_32x32x16_bf16 v[18:33], v[236:239], v[244:247], v[18:33]
	ds_read_b128 v[232:235], v159
	ds_read_b128 v[236:239], v159 offset:4096
	ds_read_b128 v[240:243], v163 offset:16384
	ds_read_b128 v[244:247], v163 offset:20480
	s_add_u32 m0, s32, 0xc000
	s_waitcnt lgkmcnt(5)
	v_mfma_f32_32x32x16_bf16 v[34:49], v[188:191], v[196:199], v[34:49]
	global_load_lds_dwordx4 v164, s[100:101]
	s_waitcnt lgkmcnt(4)
	v_mfma_f32_32x32x16_bf16 v[50:65], v[188:191], v[200:203], v[50:65]
	s_add_u32 m0, s32, 0xd000
	v_mfma_f32_32x32x16_bf16 v[2:17], v[192:195], v[196:199], v[2:17]
	global_load_lds_dwordx4 v165, s[100:101]
	v_mfma_f32_32x32x16_bf16 v[18:33], v[192:195], v[200:203], v[18:33]
	s_add_u32 m0, s32, 0xe000
	s_waitcnt lgkmcnt(1)
	v_mfma_f32_32x32x16_bf16 v[34:49], v[232:235], v[240:243], v[34:49]
	global_load_lds_dwordx4 v166, s[100:101]
	s_waitcnt lgkmcnt(0)
	v_mfma_f32_32x32x16_bf16 v[50:65], v[232:235], v[244:247], v[50:65]
	s_add_u32 m0, s32, 0xf000
	v_mfma_f32_32x32x16_bf16 v[2:17], v[236:239], v[240:243], v[2:17]
	global_load_lds_dwordx4 v167, s[100:101]
	v_mfma_f32_32x32x16_bf16 v[18:33], v[236:239], v[244:247], v[18:33]
	s_add_u32 s98, s98, 0x80
	s_addc_u32 s99, s99, 0
	s_add_u32 s100, s100, 0x80
	s_addc_u32 s101, s101, 0
	s_waitcnt vmcnt(0) lgkmcnt(0)
	s_barrier
	ds_read_b128 v[188:191], v156 offset:32768
	ds_read_b128 v[192:195], v156 offset:36864
	ds_read_b128 v[196:199], v160 offset:49152
	ds_read_b128 v[200:203], v160 offset:53248
	ds_read_b128 v[232:235], v157 offset:32768
	ds_read_b128 v[236:239], v157 offset:36864
	ds_read_b128 v[240:243], v161 offset:49152
	ds_read_b128 v[244:247], v161 offset:53248
	s_waitcnt lgkmcnt(5)
	v_mfma_f32_32x32x16_bf16 v[34:49], v[188:191], v[196:199], v[34:49]
	s_waitcnt lgkmcnt(4)
	v_mfma_f32_32x32x16_bf16 v[50:65], v[188:191], v[200:203], v[50:65]
	v_mfma_f32_32x32x16_bf16 v[2:17], v[192:195], v[196:199], v[2:17]
	v_mfma_f32_32x32x16_bf16 v[18:33], v[192:195], v[200:203], v[18:33]
	ds_read_b128 v[188:191], v158 offset:32768
	ds_read_b128 v[192:195], v158 offset:36864
	ds_read_b128 v[196:199], v162 offset:49152
	ds_read_b128 v[200:203], v162 offset:53248
	s_waitcnt lgkmcnt(5)
	v_mfma_f32_32x32x16_bf16 v[34:49], v[232:235], v[240:243], v[34:49]
	s_waitcnt lgkmcnt(4)
	v_mfma_f32_32x32x16_bf16 v[50:65], v[232:235], v[244:247], v[50:65]
	v_mfma_f32_32x32x16_bf16 v[2:17], v[236:239], v[240:243], v[2:17]
	v_mfma_f32_32x32x16_bf16 v[18:33], v[236:239], v[244:247], v[18:33]
	ds_read_b128 v[232:235], v159 offset:32768
	ds_read_b128 v[236:239], v159 offset:36864
	ds_read_b128 v[240:243], v163 offset:49152
	ds_read_b128 v[244:247], v163 offset:53248
	s_waitcnt lgkmcnt(5)
	v_mfma_f32_32x32x16_bf16 v[34:49], v[188:191], v[196:199], v[34:49]
	s_waitcnt lgkmcnt(4)
	v_mfma_f32_32x32x16_bf16 v[50:65], v[188:191], v[200:203], v[50:65]
	v_mfma_f32_32x32x16_bf16 v[2:17], v[192:195], v[196:199], v[2:17]
	v_mfma_f32_32x32x16_bf16 v[18:33], v[192:195], v[200:203], v[18:33]
	s_waitcnt lgkmcnt(1)
	v_mfma_f32_32x32x16_bf16 v[34:49], v[232:235], v[240:243], v[34:49]
	s_waitcnt lgkmcnt(0)
	v_mfma_f32_32x32x16_bf16 v[50:65], v[232:235], v[244:247], v[50:65]
	v_mfma_f32_32x32x16_bf16 v[2:17], v[236:239], v[240:243], v[2:17]
	v_mfma_f32_32x32x16_bf16 v[18:33], v[236:239], v[244:247], v[18:33]
	s_barrier
	s_nop 8
	ds_write2_b32 v100, v34, v50 offset1:32
	ds_write2_b32 v100, v35, v51 offset0:132 offset1:164
	v_add_u32_e32 v34, 0x400, v100
	ds_write2_b32 v34, v36, v52 offset0:8 offset1:40
	ds_write2_b32 v34, v37, v53 offset0:140 offset1:172
	v_add_u32_e32 v34, 0x1000, v100
	ds_write2_b32 v34, v38, v54 offset0:32 offset1:64
	ds_write2_b32 v34, v39, v55 offset0:164 offset1:196
	v_add_u32_e32 v34, 0x1400, v100
	ds_write2_b32 v34, v40, v56 offset0:40 offset1:72
	ds_write2_b32 v34, v41, v57 offset0:172 offset1:204
	v_add_u32_e32 v34, 0x2000, v100
	ds_write2_b32 v34, v42, v58 offset0:64 offset1:96
	ds_write2_b32 v34, v43, v59 offset0:196 offset1:228
	v_add_u32_e32 v34, 0x2400, v100
	ds_write2_b32 v34, v44, v60 offset0:72 offset1:104
	ds_write2_b32 v34, v45, v61 offset0:204 offset1:236
	v_add_u32_e32 v34, 0x3000, v100
	ds_write2_b32 v34, v46, v62 offset0:96 offset1:128
	v_add_u32_e32 v34, 0x3200, v100
	ds_write2_b32 v34, v47, v63 offset0:100 offset1:132
	v_add_u32_e32 v34, 0x3400, v100
	ds_write2_b32 v34, v48, v64 offset0:104 offset1:136
	v_add_u32_e32 v34, 0x3600, v100
	ds_write2_b32 v34, v49, v65 offset0:108 offset1:140
	v_add_u32_e32 v34, 0x4000, v100
	ds_write2_b32 v34, v2, v18 offset0:128 offset1:160
	v_add_u32_e32 v2, 0x4400, v100
	ds_write2_b32 v2, v3, v19 offset0:4 offset1:36
	ds_write2_b32 v2, v4, v20 offset0:136 offset1:168
	v_add_u32_e32 v2, 0x4800, v100
	ds_write2_b32 v2, v5, v21 offset0:12 offset1:44
	v_add_u32_e32 v2, 0x5000, v100
	ds_write2_b32 v2, v6, v22 offset0:160 offset1:192
	v_add_u32_e32 v2, 0x5400, v100
	ds_write2_b32 v2, v7, v23 offset0:36 offset1:68
	ds_write2_b32 v2, v8, v24 offset0:168 offset1:200
	v_add_u32_e32 v2, 0x5800, v100
	ds_write2_b32 v2, v9, v25 offset0:44 offset1:76
	v_add_u32_e32 v2, 0x6000, v100
	ds_write2_b32 v2, v10, v26 offset0:192 offset1:224
	v_add_u32_e32 v2, 0x6400, v100
	ds_write2_b32 v2, v11, v27 offset0:68 offset1:100
	ds_write2_b32 v2, v12, v28 offset0:200 offset1:232
	v_add_u32_e32 v2, 0x6800, v100
	ds_write2_b32 v2, v13, v29 offset0:76 offset1:108
	v_add_u32_e32 v2, 0x7200, v100
	ds_write2_b32 v2, v14, v30 offset0:96 offset1:128
	v_add_u32_e32 v2, 0x7400, v100
	ds_write2_b32 v2, v15, v31 offset0:100 offset1:132
	v_add_u32_e32 v2, 0x7600, v100
	ds_write2_b32 v2, v16, v32 offset0:104 offset1:136
	v_add_u32_e32 v2, 0x7800, v100
	s_cmp_lt_i32 s0, 0
	ds_write2_b32 v2, v17, v33 offset0:108 offset1:140
	s_waitcnt lgkmcnt(0)
	s_barrier
	s_cbranch_scc1 .LBB0_355
	v_add_u32_e32 v2, s0, v109
	v_ashrrev_i32_e32 v3, 31, v2
	v_lshlrev_b64 v[2:3], 11, v[2:3]
	v_lshl_add_u32 v4, s66, 7, v109
	v_lshl_add_u64 v[2:3], s[6:7], 0, v[2:3]
	v_ashrrev_i32_e32 v5, 31, v4
	v_lshl_add_u64 v[2:3], v[2:3], 0, v[0:1]
	v_lshl_add_u64 v[204:205], v[2:3], 0, s[56:57]
	v_lshl_add_u64 v[218:219], v[204:205], 0, s[56:57]
	v_lshl_add_u64 v[220:221], v[218:219], 0, s[56:57]
	global_load_dwordx4 v[66:69], v[220:221], off
	global_load_dwordx4 v[70:73], v[218:219], off
	global_load_dwordx4 v[74:77], v[204:205], off
	global_load_dwordx4 v[78:81], v[2:3], off
	v_lshlrev_b64 v[2:3], 11, v[4:5]
	v_lshl_add_u64 v[2:3], s[8:9], 0, v[2:3]
	v_lshl_add_u64 v[2:3], v[2:3], 0, v[0:1]
	v_lshl_add_u64 v[222:223], v[2:3], 0, s[56:57]
	v_lshl_add_u64 v[248:249], v[222:223], 0, s[56:57]
	v_lshl_add_u64 v[250:251], v[248:249], 0, s[56:57]
	global_load_dwordx4 v[82:85], v[250:251], off
	global_load_dwordx4 v[86:89], v[248:249], off
	global_load_dwordx4 v[90:93], v[222:223], off
	global_load_dwordx4 v[94:97], v[2:3], off

.LBB0_770:
	s_andn2_b64 vcc, exec, s[0:1]
	s_cbranch_vccnz .LBB0_784
	s_load_dword s6, s[46:47], 0x0
	v_readlane_b32 s1, v254, 12
	s_ashr_i32 s3, s1, 3
	s_waitcnt lgkmcnt(0)
	s_and_b32 s0, s6, -8
	s_cmp_ge_i32 s1, s0
	s_cselect_b64 s[0:1], -1, 0
	s_cmpk_gt_i32 s3, 0xbf
	s_cselect_b64 s[4:5], -1, 0
	s_or_b64 s[0:1], s[4:5], s[0:1]
	s_and_b64 vcc, exec, s[0:1]
	s_cbranch_vccnz .LBB0_784
	s_add_u32 s0, s62, 0x14f5000
	v_ashrrev_i32_e32 v105, 1, v146
	s_addc_u32 s1, s63, 0
	v_and_b32_e32 v3, 31, v146
	v_bfe_u32 v4, v146, 5, 1
	s_waitcnt vmcnt(0)
	v_lshlrev_b32_e32 v0, 2, v146
	v_and_b32_e32 v6, 0xffffffc0, v105
	s_add_u32 s4, s62, 0x480000
	v_readlane_b32 s7, v254, 12
	v_bfe_u32 v2, v146, 6, 1
	v_and_b32_e32 v5, 4, v0
	s_movk_i32 s8, 0x90
	v_or_b32_e32 v7, v6, v3
	v_lshlrev_b32_e32 v0, 4, v4
	s_addc_u32 s5, s63, 0
	s_and_b32 s14, s7, 7
	s_lshr_b32 s15, s6, 3
	v_lshl_or_b32 v8, v2, 6, v3
	v_mad_u64_u32 v[98:99], s[6:7], v7, s8, v[0:1]
	v_mad_u32_u24 v99, v8, s8, v0
	v_lshlrev_b32_e32 v0, 2, v3
	v_ashrrev_i32_e32 v105, 3, v146
	v_lshlrev_b32_e32 v110, 7, v105
	v_lshl_or_b32 v0, v2, 8, v0
	v_lshl_or_b32 v2, v4, 2, v6
	s_movk_i32 s8, 0x210
	v_mad_u64_u32 v[100:101], s[6:7], v2, s8, v[0:1]
	v_lshlrev_b32_e32 v0, 3, v146
	v_and_b32_e32 v0, 0x78, v0
	v_lshlrev_b32_e32 v4, 2, v0
	v_lshlrev_b32_e32 v0, 1, v0
	v_lshl_add_u64 v[2:3], s[62:63], 0, v[0:1]
	s_mov_b64 s[6:7], 0x44f5000
	v_lshl_add_u64 v[102:103], v[2:3], 0, s[6:7]
	v_add_u32_e32 v2, 0x100, v146
	v_add_u32_e32 v3, 0x200, v146
	v_add_u32_e32 v6, 0x300, v146
	v_add_u32_e32 v7, 0x400, v146
	v_add_u32_e32 v8, 0x500, v146
	v_add_u32_e32 v9, 0x600, v146
	v_add_u32_e32 v10, 0x700, v146
	v_and_b32_e32 v111, 7, v146
	v_lshlrev_b32_e32 v111, 4, v111
	v_ashrrev_i32_e32 v101, 4, v146
	v_ashrrev_i32_e32 v112, 4, v2
	v_ashrrev_i32_e32 v113, 4, v3
	v_ashrrev_i32_e32 v114, 4, v6
	v_ashrrev_i32_e32 v115, 4, v7
	v_ashrrev_i32_e32 v116, 4, v8
	v_ashrrev_i32_e32 v117, 4, v9
	v_ashrrev_i32_e32 v118, 4, v10
	v_mul_lo_u32 v0, v101, s8
	v_mul_lo_u32 v2, v112, s8
	v_mul_lo_u32 v3, v113, s8
	v_mul_lo_u32 v6, v114, s8
	v_mul_lo_u32 v7, v115, s8
	v_mul_lo_u32 v8, v116, s8
	v_mul_lo_u32 v9, v117, s8
	v_mul_lo_u32 v10, v118, s8
	v_bfe_u32 v104, v146, 4, 3
	v_lshlrev_b32_e32 v104, 4, v104
	v_xor_b32_e32 v104, v104, v111
	v_lshrrev_b32_e32 v104, 1, v104
	v_add_u32_e32 v5, 0x1000, v111
	v_add_u32_e32 v11, 0x2000, v111
	v_add_u32_e32 v12, 0x3000, v111
	s_mov_b32 s17, 0
	s_mov_b32 s16, -1
	s_mov_b64 s[8:9], 0
	v_add_u32_e32 v119, v110, v5
	v_add_u32_e32 v120, v110, v11
	v_add_u32_e32 v121, v110, v12
	v_add_u32_e32 v122, v4, v0
	v_add_u32_e32 v123, v4, v2
	v_add_u32_e32 v124, v4, v3
	v_add_u32_e32 v125, v4, v6
	v_add_u32_e32 v126, v4, v7
	v_add_u32_e32 v127, v4, v8
	v_add_u32_e32 v128, v4, v9
	v_add_u32_e32 v129, v4, v10
	s_branch .LBB0_774

.LBB0_778:
	s_lshl_b32 s18, s12, 7
	v_add_u32_e32 v2, s18, v105
	s_xor_b64 s[20:21], s[8:9], -1
	s_lshl_b32 s8, s13, 7
	v_ashrrev_i32_e32 v3, 31, v2
	v_lshlrev_b64 v[2:3], 11, v[2:3]
	v_add_u32_e32 v38, s8, v105
	s_lshl_b32 s98, s18, 11
	s_add_u32 s98, s0, s98
	s_addc_u32 s99, s1, 0
	s_lshl_b32 s100, s8, 11
	s_add_u32 s100, s4, s100
	s_addc_u32 s101, s5, 0
	s_mov_b64 s[12:13], -1
	s_andn2_b64 vcc, exec, s[20:21]
	v_lshl_add_u64 v[34:35], s[0:1], 0, v[2:3]
	v_ashrrev_i32_e32 v39, 31, v38
	v_lshlrev_b32_e32 v0, 1, v104
	s_cbranch_vccnz .LBB0_780
	v_lshlrev_b64 v[36:37], 11, v[38:39]
	v_lshl_add_u64 v[2:3], s[4:5], 0, v[36:37]
	v_lshl_add_u64 v[30:31], v[34:35], 0, v[0:1]
	v_lshl_add_u64 v[14:15], v[2:3], 0, v[0:1]
	v_lshl_add_u64 v[244:245], v[14:15], 0, s[56:57]
	v_lshl_add_u64 v[246:247], v[244:245], 0, s[56:57]
	v_lshl_add_u64 v[248:249], v[246:247], 0, s[56:57]
	v_lshl_add_u64 v[238:239], v[30:31], 0, s[56:57]
	v_lshl_add_u64 v[240:241], v[238:239], 0, s[56:57]
	v_lshl_add_u64 v[242:243], v[240:241], 0, s[56:57]
	global_load_dwordx4 v[2:5], v[248:249], off
	global_load_dwordx4 v[6:9], v[246:247], off
	global_load_dwordx4 v[10:13], v[244:245], off
	s_nop 0
	global_load_dwordx4 v[14:17], v[14:15], off
	s_nop 0
	global_load_dwordx4 v[18:21], v[242:243], off
	global_load_dwordx4 v[22:25], v[240:241], off
	global_load_dwordx4 v[26:29], v[238:239], off
	s_nop 0
	global_load_dwordx4 v[30:33], v[30:31], off
	s_mov_b64 s[12:13], 0

.LBB0_782:
	v_add_u32_e32 v130, v110, v111
	v_lshrrev_b32_e32 v148, 6, v146
	v_lshlrev_b32_e32 v148, 10, v148
	v_lshl_add_u32 v140, v105, 11, v0
	v_readfirstlane_b32 s32, v148
	v_add_u32_e32 v141, 0x10000, v140
	v_add_u32_e32 v142, 0x20000, v140
	v_add_u32_e32 v143, 0x30000, v140
	v_bfe_u32 v148, v146, 1, 3
	v_bfe_u32 v149, v146, 5, 1
	v_xor_b32_e32 v148, v148, v149
	v_lshlrev_b32_e32 v148, 4, v148
	v_and_b32_e32 v149, 31, v146
	v_lshrrev_b32_e32 v150, 7, v146
	v_lshl_add_u32 v150, v150, 6, v149
	v_lshl_add_u32 v132, v150, 7, v148
	v_bfe_u32 v150, v146, 6, 1
	v_lshl_add_u32 v150, v150, 6, v149
	v_lshl_add_u32 v136, v150, 7, v148
	v_xor_b32_e32 v133, 32, v132
	v_xor_b32_e32 v137, 32, v136
	v_xor_b32_e32 v134, 64, v132
	v_xor_b32_e32 v138, 64, v136
	v_xor_b32_e32 v135, 96, v132
	v_xor_b32_e32 v139, 96, v136
	s_add_u32 s98, s98, 0x80
	s_addc_u32 s99, s99, 0
	s_add_u32 s100, s100, 0x80
	s_addc_u32 s101, s101, 0
	s_add_u32 m0, s32, 0x8000
	s_nop 0
	global_load_lds_dwordx4 v140, s[98:99]
	s_add_u32 m0, s32, 0x9000
	s_nop 0
	global_load_lds_dwordx4 v141, s[98:99]
	s_add_u32 m0, s32, 0xa000
	s_nop 0
	global_load_lds_dwordx4 v142, s[98:99]
	s_add_u32 m0, s32, 0xb000
	s_nop 0
	global_load_lds_dwordx4 v143, s[98:99]
	s_add_u32 m0, s32, 0xc000
	s_nop 0
	global_load_lds_dwordx4 v140, s[100:101]
	s_add_u32 m0, s32, 0xd000
	s_nop 0
	global_load_lds_dwordx4 v141, s[100:101]
	s_add_u32 m0, s32, 0xe000
	s_nop 0
	global_load_lds_dwordx4 v142, s[100:101]
	s_add_u32 m0, s32, 0xf000
	s_nop 0
	global_load_lds_dwordx4 v143, s[100:101]
	s_add_u32 s98, s98, 0x80
	s_addc_u32 s99, s99, 0
	s_add_u32 s100, s100, 0x80
	s_addc_u32 s101, s101, 0
	s_waitcnt vmcnt(8)
	ds_write_b128 v130, v[30:33]
	ds_write_b128 v130, v[14:17] offset:16384
	ds_write_b128 v119, v[26:29]
	ds_write_b128 v119, v[10:13] offset:16384
	ds_write_b128 v120, v[22:25]
	ds_write_b128 v120, v[6:9] offset:16384
	ds_write_b128 v121, v[18:21]
	ds_write_b128 v121, v[2:5] offset:16384
	s_lshl_b32 s9, s16, 7
	s_and_b64 s[10:11], s[10:11], exec
	s_cselect_b32 s9, s9, -1
	s_waitcnt lgkmcnt(0)
	s_barrier
	ds_read_b128 v[168:171], v132
	ds_read_b128 v[172:175], v132 offset:4096
	ds_read_b128 v[176:179], v136 offset:16384
	ds_read_b128 v[180:183], v136 offset:20480
	ds_read_b128 v[184:187], v133
	ds_read_b128 v[188:191], v133 offset:4096
	ds_read_b128 v[192:195], v137 offset:16384
	ds_read_b128 v[196:199], v137 offset:20480
	s_waitcnt lgkmcnt(5)
	v_mfma_f32_32x32x16_bf16 v[34:49], v[168:171], v[176:179], 0
	s_waitcnt lgkmcnt(4)
	v_mfma_f32_32x32x16_bf16 v[50:65], v[168:171], v[180:183], 0
	v_mfma_f32_32x32x16_bf16 v[2:17], v[172:175], v[176:179], 0
	v_mfma_f32_32x32x16_bf16 v[18:33], v[172:175], v[180:183], 0
	ds_read_b128 v[168:171], v134
	ds_read_b128 v[172:175], v134 offset:4096
	ds_read_b128 v[176:179], v138 offset:16384
	ds_read_b128 v[180:183], v138 offset:20480
	s_waitcnt lgkmcnt(5)
	v_mfma_f32_32x32x16_bf16 v[34:49], v[184:187], v[192:195], v[34:49]
	s_waitcnt lgkmcnt(4)
	v_mfma_f32_32x32x16_bf16 v[50:65], v[184:187], v[196:199], v[50:65]
	v_mfma_f32_32x32x16_bf16 v[2:17], v[188:191], v[192:195], v[2:17]
	v_mfma_f32_32x32x16_bf16 v[18:33], v[188:191], v[196:199], v[18:33]
	ds_read_b128 v[184:187], v135
	ds_read_b128 v[188:191], v135 offset:4096
	ds_read_b128 v[192:195], v139 offset:16384
	ds_read_b128 v[196:199], v139 offset:20480
	s_waitcnt lgkmcnt(5)
	v_mfma_f32_32x32x16_bf16 v[34:49], v[168:171], v[176:179], v[34:49]
	s_waitcnt lgkmcnt(4)
	v_mfma_f32_32x32x16_bf16 v[50:65], v[168:171], v[180:183], v[50:65]
	v_mfma_f32_32x32x16_bf16 v[2:17], v[172:175], v[176:179], v[2:17]
	v_mfma_f32_32x32x16_bf16 v[18:33], v[172:175], v[180:183], v[18:33]
	s_waitcnt lgkmcnt(1)
	v_mfma_f32_32x32x16_bf16 v[34:49], v[184:187], v[192:195], v[34:49]
	s_waitcnt lgkmcnt(0)
	v_mfma_f32_32x32x16_bf16 v[50:65], v[184:187], v[196:199], v[50:65]
	v_mfma_f32_32x32x16_bf16 v[2:17], v[188:191], v[192:195], v[2:17]
	v_mfma_f32_32x32x16_bf16 v[18:33], v[188:191], v[196:199], v[18:33]
	s_waitcnt vmcnt(0) lgkmcnt(0)
	s_barrier
	ds_read_b128 v[168:171], v132 offset:32768
	ds_read_b128 v[172:175], v132 offset:36864
	ds_read_b128 v[176:179], v136 offset:49152
	ds_read_b128 v[180:183], v136 offset:53248
	ds_read_b128 v[184:187], v133 offset:32768
	ds_read_b128 v[188:191], v133 offset:36864
	ds_read_b128 v[192:195], v137 offset:49152
	ds_read_b128 v[196:199], v137 offset:53248
	s_mov_b32 m0, s32
	s_waitcnt lgkmcnt(5)
	v_mfma_f32_32x32x16_bf16 v[34:49], v[168:171], v[176:179], v[34:49]
	global_load_lds_dwordx4 v140, s[98:99]
	s_waitcnt lgkmcnt(4)
	v_mfma_f32_32x32x16_bf16 v[50:65], v[168:171], v[180:183], v[50:65]
	s_add_u32 m0, s32, 0x1000
	v_mfma_f32_32x32x16_bf16 v[2:17], v[172:175], v[176:179], v[2:17]
	global_load_lds_dwordx4 v141, s[98:99]
	v_mfma_f32_32x32x16_bf16 v[18:33], v[172:175], v[180:183], v[18:33]
	ds_read_b128 v[168:171], v134 offset:32768
	ds_read_b128 v[172:175], v134 offset:36864
	ds_read_b128 v[176:179], v138 offset:49152
	ds_read_b128 v[180:183], v138 offset:53248
	s_add_u32 m0, s32, 0x2000
	s_waitcnt lgkmcnt(5)
	v_mfma_f32_32x32x16_bf16 v[34:49], v[184:187], v[192:195], v[34:49]
	global_load_lds_dwordx4 v142, s[98:99]
	s_waitcnt lgkmcnt(4)
	v_mfma_f32_32x32x16_bf16 v[50:65], v[184:187], v[196:199], v[50:65]
	s_add_u32 m0, s32, 0x3000
	v_mfma_f32_32x32x16_bf16 v[2:17], v[188:191], v[192:195], v[2:17]
	global_load_lds_dwordx4 v143, s[98:99]
	v_mfma_f32_32x32x16_bf16 v[18:33], v[188:191], v[196:199], v[18:33]
	ds_read_b128 v[184:187], v135 offset:32768
	ds_read_b128 v[188:191], v135 offset:36864
	ds_read_b128 v[192:195], v139 offset:49152
	ds_read_b128 v[196:199], v139 offset:53248
	s_add_u32 m0, s32, 0x4000
	s_waitcnt lgkmcnt(5)
	v_mfma_f32_32x32x16_bf16 v[34:49], v[168:171], v[176:179], v[34:49]
	global_load_lds_dwordx4 v140, s[100:101]
	s_waitcnt lgkmcnt(4)
	v_mfma_f32_32x32x16_bf16 v[50:65], v[168:171], v[180:183], v[50:65]
	s_add_u32 m0, s32, 0x5000
	v_mfma_f32_32x32x16_bf16 v[2:17], v[172:175], v[176:179], v[2:17]
	global_load_lds_dwordx4 v141, s[100:101]
	v_mfma_f32_32x32x16_bf16 v[18:33], v[172:175], v[180:183], v[18:33]
	s_add_u32 m0, s32, 0x6000
	s_waitcnt lgkmcnt(1)
	v_mfma_f32_32x32x16_bf16 v[34:49], v[184:187], v[192:195], v[34:49]
	global_load_lds_dwordx4 v142, s[100:101]
	s_waitcnt lgkmcnt(0)
	v_mfma_f32_32x32x16_bf16 v[50:65], v[184:187], v[196:199], v[50:65]
	s_add_u32 m0, s32, 0x7000
	v_mfma_f32_32x32x16_bf16 v[2:17], v[188:191], v[192:195], v[2:17]
	global_load_lds_dwordx4 v143, s[100:101]
	v_mfma_f32_32x32x16_bf16 v[18:33], v[188:191], v[196:199], v[18:33]
	s_add_u32 s98, s98, 0x80
	s_addc_u32 s99, s99, 0
	s_add_u32 s100, s100, 0x80
	s_addc_u32 s101, s101, 0
	s_waitcnt vmcnt(0) lgkmcnt(0)
	s_barrier
	ds_read_b128 v[168:171], v132
	ds_read_b128 v[172:175], v132 offset:4096
	ds_read_b128 v[176:179], v136 offset:16384
	ds_read_b128 v[180:183], v136 offset:20480
	ds_read_b128 v[184:187], v133
	ds_read_b128 v[188:191], v133 offset:4096
	ds_read_b128 v[192:195], v137 offset:16384
	ds_read_b128 v[196:199], v137 offset:20480
	s_add_u32 m0, s32, 0x8000
	s_waitcnt lgkmcnt(5)
	v_mfma_f32_32x32x16_bf16 v[34:49], v[168:171], v[176:179], v[34:49]
	global_load_lds_dwordx4 v140, s[98:99]
	s_waitcnt lgkmcnt(4)
	v_mfma_f32_32x32x16_bf16 v[50:65], v[168:171], v[180:183], v[50:65]
	s_add_u32 m0, s32, 0x9000
	v_mfma_f32_32x32x16_bf16 v[2:17], v[172:175], v[176:179], v[2:17]
	global_load_lds_dwordx4 v141, s[98:99]
	v_mfma_f32_32x32x16_bf16 v[18:33], v[172:175], v[180:183], v[18:33]
	ds_read_b128 v[168:171], v134
	ds_read_b128 v[172:175], v134 offset:4096
	ds_read_b128 v[176:179], v138 offset:16384
	ds_read_b128 v[180:183], v138 offset:20480
	s_add_u32 m0, s32, 0xa000
	s_waitcnt lgkmcnt(5)
	v_mfma_f32_32x32x16_bf16 v[34:49], v[184:187], v[192:195], v[34:49]
	global_load_lds_dwordx4 v142, s[98:99]
	s_waitcnt lgkmcnt(4)
	v_mfma_f32_32x32x16_bf16 v[50:65], v[184:187], v[196:199], v[50:65]
	s_add_u32 m0, s32, 0xb000
	v_mfma_f32_32x32x16_bf16 v[2:17], v[188:191], v[192:195], v[2:17]
	global_load_lds_dwordx4 v143, s[98:99]
	v_mfma_f32_32x32x16_bf16 v[18:33], v[188:191], v[196:199], v[18:33]
	ds_read_b128 v[184:187], v135
	ds_read_b128 v[188:191], v135 offset:4096
	ds_read_b128 v[192:195], v139 offset:16384
	ds_read_b128 v[196:199], v139 offset:20480
	s_add_u32 m0, s32, 0xc000
	s_waitcnt lgkmcnt(5)
	v_mfma_f32_32x32x16_bf16 v[34:49], v[168:171], v[176:179], v[34:49]
	global_load_lds_dwordx4 v140, s[100:101]
	s_waitcnt lgkmcnt(4)
	v_mfma_f32_32x32x16_bf16 v[50:65], v[168:171], v[180:183], v[50:65]
	s_add_u32 m0, s32, 0xd000
	v_mfma_f32_32x32x16_bf16 v[2:17], v[172:175], v[176:179], v[2:17]
	global_load_lds_dwordx4 v141, s[100:101]
	v_mfma_f32_32x32x16_bf16 v[18:33], v[172:175], v[180:183], v[18:33]
	s_add_u32 m0, s32, 0xe000
	s_waitcnt lgkmcnt(1)
	v_mfma_f32_32x32x16_bf16 v[34:49], v[184:187], v[192:195], v[34:49]
	global_load_lds_dwordx4 v142, s[100:101]
	s_waitcnt lgkmcnt(0)
	v_mfma_f32_32x32x16_bf16 v[50:65], v[184:187], v[196:199], v[50:65]
	s_add_u32 m0, s32, 0xf000
	v_mfma_f32_32x32x16_bf16 v[2:17], v[188:191], v[192:195], v[2:17]
	global_load_lds_dwordx4 v143, s[100:101]
	v_mfma_f32_32x32x16_bf16 v[18:33], v[188:191], v[196:199], v[18:33]
	s_add_u32 s98, s98, 0x80
	s_addc_u32 s99, s99, 0
	s_add_u32 s100, s100, 0x80
	s_addc_u32 s101, s101, 0
	s_waitcnt vmcnt(0) lgkmcnt(0)
	s_barrier
	ds_read_b128 v[168:171], v132 offset:32768
	ds_read_b128 v[172:175], v132 offset:36864
	ds_read_b128 v[176:179], v136 offset:49152
	ds_read_b128 v[180:183], v136 offset:53248
	ds_read_b128 v[184:187], v133 offset:32768
	ds_read_b128 v[188:191], v133 offset:36864
	ds_read_b128 v[192:195], v137 offset:49152
	ds_read_b128 v[196:199], v137 offset:53248
	s_mov_b32 m0, s32
	s_waitcnt lgkmcnt(5)
	v_mfma_f32_32x32x16_bf16 v[34:49], v[168:171], v[176:179], v[34:49]
	global_load_lds_dwordx4 v140, s[98:99]
	s_waitcnt lgkmcnt(4)
	v_mfma_f32_32x32x16_bf16 v[50:65], v[168:171], v[180:183], v[50:65]
	s_add_u32 m0, s32, 0x1000
	v_mfma_f32_32x32x16_bf16 v[2:17], v[172:175], v[176:179], v[2:17]
	global_load_lds_dwordx4 v141, s[98:99]
	v_mfma_f32_32x32x16_bf16 v[18:33], v[172:175], v[180:183], v[18:33]
	ds_read_b128 v[168:171], v134 offset:32768
	ds_read_b128 v[172:175], v134 offset:36864
	ds_read_b128 v[176:179], v138 offset:49152
	ds_read_b128 v[180:183], v138 offset:53248
	s_add_u32 m0, s32, 0x2000
	s_waitcnt lgkmcnt(5)
	v_mfma_f32_32x32x16_bf16 v[34:49], v[184:187], v[192:195], v[34:49]
	global_load_lds_dwordx4 v142, s[98:99]
	s_waitcnt lgkmcnt(4)
	v_mfma_f32_32x32x16_bf16 v[50:65], v[184:187], v[196:199], v[50:65]
	s_add_u32 m0, s32, 0x3000
	v_mfma_f32_32x32x16_bf16 v[2:17], v[188:191], v[192:195], v[2:17]
	global_load_lds_dwordx4 v143, s[98:99]
	v_mfma_f32_32x32x16_bf16 v[18:33], v[188:191], v[196:199], v[18:33]
	ds_read_b128 v[184:187], v135 offset:32768
	ds_read_b128 v[188:191], v135 offset:36864
	ds_read_b128 v[192:195], v139 offset:49152
	ds_read_b128 v[196:199], v139 offset:53248
	s_add_u32 m0, s32, 0x4000
	s_waitcnt lgkmcnt(5)
	v_mfma_f32_32x32x16_bf16 v[34:49], v[168:171], v[176:179], v[34:49]
	global_load_lds_dwordx4 v140, s[100:101]
	s_waitcnt lgkmcnt(4)
	v_mfma_f32_32x32x16_bf16 v[50:65], v[168:171], v[180:183], v[50:65]
	s_add_u32 m0, s32, 0x5000
	v_mfma_f32_32x32x16_bf16 v[2:17], v[172:175], v[176:179], v[2:17]
	global_load_lds_dwordx4 v141, s[100:101]
	v_mfma_f32_32x32x16_bf16 v[18:33], v[172:175], v[180:183], v[18:33]
	s_add_u32 m0, s32, 0x6000
	s_waitcnt lgkmcnt(1)
	v_mfma_f32_32x32x16_bf16 v[34:49], v[184:187], v[192:195], v[34:49]
	global_load_lds_dwordx4 v142, s[100:101]
	s_waitcnt lgkmcnt(0)
	v_mfma_f32_32x32x16_bf16 v[50:65], v[184:187], v[196:199], v[50:65]
	s_add_u32 m0, s32, 0x7000
	v_mfma_f32_32x32x16_bf16 v[2:17], v[188:191], v[192:195], v[2:17]
	global_load_lds_dwordx4 v143, s[100:101]
	v_mfma_f32_32x32x16_bf16 v[18:33], v[188:191], v[196:199], v[18:33]
	s_add_u32 s98, s98, 0x80
	s_addc_u32 s99, s99, 0
	s_add_u32 s100, s100, 0x80
	s_addc_u32 s101, s101, 0
	s_waitcnt vmcnt(0) lgkmcnt(0)
	s_barrier
	ds_read_b128 v[168:171], v132
	ds_read_b128 v[172:175], v132 offset:4096
	ds_read_b128 v[176:179], v136 offset:16384
	ds_read_b128 v[180:183], v136 offset:20480
	ds_read_b128 v[184:187], v133
	ds_read_b128 v[188:191], v133 offset:4096
	ds_read_b128 v[192:195], v137 offset:16384
	ds_read_b128 v[196:199], v137 offset:20480
	s_add_u32 m0, s32, 0x8000
	s_waitcnt lgkmcnt(5)
	v_mfma_f32_32x32x16_bf16 v[34:49], v[168:171], v[176:179], v[34:49]
	global_load_lds_dwordx4 v140, s[98:99]
	s_waitcnt lgkmcnt(4)
	v_mfma_f32_32x32x16_bf16 v[50:65], v[168:171], v[180:183], v[50:65]
	s_add_u32 m0, s32, 0x9000
	v_mfma_f32_32x32x16_bf16 v[2:17], v[172:175], v[176:179], v[2:17]
	global_load_lds_dwordx4 v141, s[98:99]
	v_mfma_f32_32x32x16_bf16 v[18:33], v[172:175], v[180:183], v[18:33]
	ds_read_b128 v[168:171], v134
	ds_read_b128 v[172:175], v134 offset:4096
	ds_read_b128 v[176:179], v138 offset:16384
	ds_read_b128 v[180:183], v138 offset:20480
	s_add_u32 m0, s32, 0xa000
	s_waitcnt lgkmcnt(5)
	v_mfma_f32_32x32x16_bf16 v[34:49], v[184:187], v[192:195], v[34:49]
	global_load_lds_dwordx4 v142, s[98:99]
	s_waitcnt lgkmcnt(4)
	v_mfma_f32_32x32x16_bf16 v[50:65], v[184:187], v[196:199], v[50:65]
	s_add_u32 m0, s32, 0xb000
	v_mfma_f32_32x32x16_bf16 v[2:17], v[188:191], v[192:195], v[2:17]
	global_load_lds_dwordx4 v143, s[98:99]
	v_mfma_f32_32x32x16_bf16 v[18:33], v[188:191], v[196:199], v[18:33]
	ds_read_b128 v[184:187], v135
	ds_read_b128 v[188:191], v135 offset:4096
	ds_read_b128 v[192:195], v139 offset:16384
	ds_read_b128 v[196:199], v139 offset:20480
	s_add_u32 m0, s32, 0xc000
	s_waitcnt lgkmcnt(5)
	v_mfma_f32_32x32x16_bf16 v[34:49], v[168:171], v[176:179], v[34:49]
	global_load_lds_dwordx4 v140, s[100:101]
	s_waitcnt lgkmcnt(4)
	v_mfma_f32_32x32x16_bf16 v[50:65], v[168:171], v[180:183], v[50:65]
	s_add_u32 m0, s32, 0xd000
	v_mfma_f32_32x32x16_bf16 v[2:17], v[172:175], v[176:179], v[2:17]
	global_load_lds_dwordx4 v141, s[100:101]
	v_mfma_f32_32x32x16_bf16 v[18:33], v[172:175], v[180:183], v[18:33]
	s_add_u32 m0, s32, 0xe000
	s_waitcnt lgkmcnt(1)
	v_mfma_f32_32x32x16_bf16 v[34:49], v[184:187], v[192:195], v[34:49]
	global_load_lds_dwordx4 v142, s[100:101]
	s_waitcnt lgkmcnt(0)
	v_mfma_f32_32x32x16_bf16 v[50:65], v[184:187], v[196:199], v[50:65]
	s_add_u32 m0, s32, 0xf000
	v_mfma_f32_32x32x16_bf16 v[2:17], v[188:191], v[192:195], v[2:17]
	global_load_lds_dwordx4 v143, s[100:101]
	v_mfma_f32_32x32x16_bf16 v[18:33], v[188:191], v[196:199], v[18:33]
	s_add_u32 s98, s98, 0x80
	s_addc_u32 s99, s99, 0
	s_add_u32 s100, s100, 0x80
	s_addc_u32 s101, s101, 0
	s_waitcnt vmcnt(0) lgkmcnt(0)
	s_barrier
	ds_read_b128 v[168:171], v132 offset:32768
	ds_read_b128 v[172:175], v132 offset:36864
	ds_read_b128 v[176:179], v136 offset:49152
	ds_read_b128 v[180:183], v136 offset:53248
	ds_read_b128 v[184:187], v133 offset:32768
	ds_read_b128 v[188:191], v133 offset:36864
	ds_read_b128 v[192:195], v137 offset:49152
	ds_read_b128 v[196:199], v137 offset:53248
	s_mov_b32 m0, s32
	s_waitcnt lgkmcnt(5)
	v_mfma_f32_32x32x16_bf16 v[34:49], v[168:171], v[176:179], v[34:49]
	global_load_lds_dwordx4 v140, s[98:99]
	s_waitcnt lgkmcnt(4)
	v_mfma_f32_32x32x16_bf16 v[50:65], v[168:171], v[180:183], v[50:65]
	s_add_u32 m0, s32, 0x1000
	v_mfma_f32_32x32x16_bf16 v[2:17], v[172:175], v[176:179], v[2:17]
	global_load_lds_dwordx4 v141, s[98:99]
	v_mfma_f32_32x32x16_bf16 v[18:33], v[172:175], v[180:183], v[18:33]
	ds_read_b128 v[168:171], v134 offset:32768
	ds_read_b128 v[172:175], v134 offset:36864
	ds_read_b128 v[176:179], v138 offset:49152
	ds_read_b128 v[180:183], v138 offset:53248
	s_add_u32 m0, s32, 0x2000
	s_waitcnt lgkmcnt(5)
	v_mfma_f32_32x32x16_bf16 v[34:49], v[184:187], v[192:195], v[34:49]
	global_load_lds_dwordx4 v142, s[98:99]
	s_waitcnt lgkmcnt(4)
	v_mfma_f32_32x32x16_bf16 v[50:65], v[184:187], v[196:199], v[50:65]
	s_add_u32 m0, s32, 0x3000
	v_mfma_f32_32x32x16_bf16 v[2:17], v[188:191], v[192:195], v[2:17]
	global_load_lds_dwordx4 v143, s[98:99]
	v_mfma_f32_32x32x16_bf16 v[18:33], v[188:191], v[196:199], v[18:33]
	ds_read_b128 v[184:187], v135 offset:32768
	ds_read_b128 v[188:191], v135 offset:36864
	ds_read_b128 v[192:195], v139 offset:49152
	ds_read_b128 v[196:199], v139 offset:53248
	s_add_u32 m0, s32, 0x4000
	s_waitcnt lgkmcnt(5)
	v_mfma_f32_32x32x16_bf16 v[34:49], v[168:171], v[176:179], v[34:49]
	global_load_lds_dwordx4 v140, s[100:101]
	s_waitcnt lgkmcnt(4)
	v_mfma_f32_32x32x16_bf16 v[50:65], v[168:171], v[180:183], v[50:65]
	s_add_u32 m0, s32, 0x5000
	v_mfma_f32_32x32x16_bf16 v[2:17], v[172:175], v[176:179], v[2:17]
	global_load_lds_dwordx4 v141, s[100:101]
	v_mfma_f32_32x32x16_bf16 v[18:33], v[172:175], v[180:183], v[18:33]
	s_add_u32 m0, s32, 0x6000
	s_waitcnt lgkmcnt(1)
	v_mfma_f32_32x32x16_bf16 v[34:49], v[184:187], v[192:195], v[34:49]
	global_load_lds_dwordx4 v142, s[100:101]
	s_waitcnt lgkmcnt(0)
	v_mfma_f32_32x32x16_bf16 v[50:65], v[184:187], v[196:199], v[50:65]
	s_add_u32 m0, s32, 0x7000
	v_mfma_f32_32x32x16_bf16 v[2:17], v[188:191], v[192:195], v[2:17]
	global_load_lds_dwordx4 v143, s[100:101]
	v_mfma_f32_32x32x16_bf16 v[18:33], v[188:191], v[196:199], v[18:33]
	s_add_u32 s98, s98, 0x80
	s_addc_u32 s99, s99, 0
	s_add_u32 s100, s100, 0x80
	s_addc_u32 s101, s101, 0
	s_waitcnt vmcnt(0) lgkmcnt(0)
	s_barrier
	ds_read_b128 v[168:171], v132
	ds_read_b128 v[172:175], v132 offset:4096
	ds_read_b128 v[176:179], v136 offset:16384
	ds_read_b128 v[180:183], v136 offset:20480
	ds_read_b128 v[184:187], v133
	ds_read_b128 v[188:191], v133 offset:4096
	ds_read_b128 v[192:195], v137 offset:16384
	ds_read_b128 v[196:199], v137 offset:20480
	s_add_u32 m0, s32, 0x8000
	s_waitcnt lgkmcnt(5)
	v_mfma_f32_32x32x16_bf16 v[34:49], v[168:171], v[176:179], v[34:49]
	global_load_lds_dwordx4 v140, s[98:99]
	s_waitcnt lgkmcnt(4)
	v_mfma_f32_32x32x16_bf16 v[50:65], v[168:171], v[180:183], v[50:65]
	s_add_u32 m0, s32, 0x9000
	v_mfma_f32_32x32x16_bf16 v[2:17], v[172:175], v[176:179], v[2:17]
	global_load_lds_dwordx4 v141, s[98:99]
	v_mfma_f32_32x32x16_bf16 v[18:33], v[172:175], v[180:183], v[18:33]
	ds_read_b128 v[168:171], v134
	ds_read_b128 v[172:175], v134 offset:4096
	ds_read_b128 v[176:179], v138 offset:16384
	ds_read_b128 v[180:183], v138 offset:20480
	s_add_u32 m0, s32, 0xa000
	s_waitcnt lgkmcnt(5)
	v_mfma_f32_32x32x16_bf16 v[34:49], v[184:187], v[192:195], v[34:49]
	global_load_lds_dwordx4 v142, s[98:99]
	s_waitcnt lgkmcnt(4)
	v_mfma_f32_32x32x16_bf16 v[50:65], v[184:187], v[196:199], v[50:65]
	s_add_u32 m0, s32, 0xb000
	v_mfma_f32_32x32x16_bf16 v[2:17], v[188:191], v[192:195], v[2:17]
	global_load_lds_dwordx4 v143, s[98:99]
	v_mfma_f32_32x32x16_bf16 v[18:33], v[188:191], v[196:199], v[18:33]
	ds_read_b128 v[184:187], v135
	ds_read_b128 v[188:191], v135 offset:4096
	ds_read_b128 v[192:195], v139 offset:16384
	ds_read_b128 v[196:199], v139 offset:20480
	s_add_u32 m0, s32, 0xc000
	s_waitcnt lgkmcnt(5)
	v_mfma_f32_32x32x16_bf16 v[34:49], v[168:171], v[176:179], v[34:49]
	global_load_lds_dwordx4 v140, s[100:101]
	s_waitcnt lgkmcnt(4)
	v_mfma_f32_32x32x16_bf16 v[50:65], v[168:171], v[180:183], v[50:65]
	s_add_u32 m0, s32, 0xd000
	v_mfma_f32_32x32x16_bf16 v[2:17], v[172:175], v[176:179], v[2:17]
	global_load_lds_dwordx4 v141, s[100:101]
	v_mfma_f32_32x32x16_bf16 v[18:33], v[172:175], v[180:183], v[18:33]
	s_add_u32 m0, s32, 0xe000
	s_waitcnt lgkmcnt(1)
	v_mfma_f32_32x32x16_bf16 v[34:49], v[184:187], v[192:195], v[34:49]
	global_load_lds_dwordx4 v142, s[100:101]
	s_waitcnt lgkmcnt(0)
	v_mfma_f32_32x32x16_bf16 v[50:65], v[184:187], v[196:199], v[50:65]
	s_add_u32 m0, s32, 0xf000
	v_mfma_f32_32x32x16_bf16 v[2:17], v[188:191], v[192:195], v[2:17]
	global_load_lds_dwordx4 v143, s[100:101]
	v_mfma_f32_32x32x16_bf16 v[18:33], v[188:191], v[196:199], v[18:33]
	s_add_u32 s98, s98, 0x80
	s_addc_u32 s99, s99, 0
	s_add_u32 s100, s100, 0x80
	s_addc_u32 s101, s101, 0
	s_waitcnt vmcnt(0) lgkmcnt(0)
	s_barrier
	ds_read_b128 v[168:171], v132 offset:32768
	ds_read_b128 v[172:175], v132 offset:36864
	ds_read_b128 v[176:179], v136 offset:49152
	ds_read_b128 v[180:183], v136 offset:53248
	ds_read_b128 v[184:187], v133 offset:32768
	ds_read_b128 v[188:191], v133 offset:36864
	ds_read_b128 v[192:195], v137 offset:49152
	ds_read_b128 v[196:199], v137 offset:53248
	s_mov_b32 m0, s32
	s_waitcnt lgkmcnt(5)
	v_mfma_f32_32x32x16_bf16 v[34:49], v[168:171], v[176:179], v[34:49]
	global_load_lds_dwordx4 v140, s[98:99]
	s_waitcnt lgkmcnt(4)
	v_mfma_f32_32x32x16_bf16 v[50:65], v[168:171], v[180:183], v[50:65]
	s_add_u32 m0, s32, 0x1000
	v_mfma_f32_32x32x16_bf16 v[2:17], v[172:175], v[176:179], v[2:17]
	global_load_lds_dwordx4 v141, s[98:99]
	v_mfma_f32_32x32x16_bf16 v[18:33], v[172:175], v[180:183], v[18:33]
	ds_read_b128 v[168:171], v134 offset:32768
	ds_read_b128 v[172:175], v134 offset:36864
	ds_read_b128 v[176:179], v138 offset:49152
	ds_read_b128 v[180:183], v138 offset:53248
	s_add_u32 m0, s32, 0x2000
	s_waitcnt lgkmcnt(5)
	v_mfma_f32_32x32x16_bf16 v[34:49], v[184:187], v[192:195], v[34:49]
	global_load_lds_dwordx4 v142, s[98:99]
	s_waitcnt lgkmcnt(4)
	v_mfma_f32_32x32x16_bf16 v[50:65], v[184:187], v[196:199], v[50:65]
	s_add_u32 m0, s32, 0x3000
	v_mfma_f32_32x32x16_bf16 v[2:17], v[188:191], v[192:195], v[2:17]
	global_load_lds_dwordx4 v143, s[98:99]
	v_mfma_f32_32x32x16_bf16 v[18:33], v[188:191], v[196:199], v[18:33]
	ds_read_b128 v[184:187], v135 offset:32768
	ds_read_b128 v[188:191], v135 offset:36864
	ds_read_b128 v[192:195], v139 offset:49152
	ds_read_b128 v[196:199], v139 offset:53248
	s_add_u32 m0, s32, 0x4000
	s_waitcnt lgkmcnt(5)
	v_mfma_f32_32x32x16_bf16 v[34:49], v[168:171], v[176:179], v[34:49]
	global_load_lds_dwordx4 v140, s[100:101]
	s_waitcnt lgkmcnt(4)
	v_mfma_f32_32x32x16_bf16 v[50:65], v[168:171], v[180:183], v[50:65]
	s_add_u32 m0, s32, 0x5000
	v_mfma_f32_32x32x16_bf16 v[2:17], v[172:175], v[176:179], v[2:17]
	global_load_lds_dwordx4 v141, s[100:101]
	v_mfma_f32_32x32x16_bf16 v[18:33], v[172:175], v[180:183], v[18:33]
	s_add_u32 m0, s32, 0x6000
	s_waitcnt lgkmcnt(1)
	v_mfma_f32_32x32x16_bf16 v[34:49], v[184:187], v[192:195], v[34:49]
	global_load_lds_dwordx4 v142, s[100:101]
	s_waitcnt lgkmcnt(0)
	v_mfma_f32_32x32x16_bf16 v[50:65], v[184:187], v[196:199], v[50:65]
	s_add_u32 m0, s32, 0x7000
	v_mfma_f32_32x32x16_bf16 v[2:17], v[188:191], v[192:195], v[2:17]
	global_load_lds_dwordx4 v143, s[100:101]
	v_mfma_f32_32x32x16_bf16 v[18:33], v[188:191], v[196:199], v[18:33]
	s_add_u32 s98, s98, 0x80
	s_addc_u32 s99, s99, 0
	s_add_u32 s100, s100, 0x80
	s_addc_u32 s101, s101, 0
	s_waitcnt vmcnt(0) lgkmcnt(0)
	s_barrier
	ds_read_b128 v[168:171], v132
	ds_read_b128 v[172:175], v132 offset:4096
	ds_read_b128 v[176:179], v136 offset:16384
	ds_read_b128 v[180:183], v136 offset:20480
	ds_read_b128 v[184:187], v133
	ds_read_b128 v[188:191], v133 offset:4096
	ds_read_b128 v[192:195], v137 offset:16384
	ds_read_b128 v[196:199], v137 offset:20480
	s_add_u32 m0, s32, 0x8000
	s_waitcnt lgkmcnt(5)
	v_mfma_f32_32x32x16_bf16 v[34:49], v[168:171], v[176:179], v[34:49]
	global_load_lds_dwordx4 v140, s[98:99]
	s_waitcnt lgkmcnt(4)
	v_mfma_f32_32x32x16_bf16 v[50:65], v[168:171], v[180:183], v[50:65]
	s_add_u32 m0, s32, 0x9000
	v_mfma_f32_32x32x16_bf16 v[2:17], v[172:175], v[176:179], v[2:17]
	global_load_lds_dwordx4 v141, s[98:99]
	v_mfma_f32_32x32x16_bf16 v[18:33], v[172:175], v[180:183], v[18:33]
	ds_read_b128 v[168:171], v134
	ds_read_b128 v[172:175], v134 offset:4096
	ds_read_b128 v[176:179], v138 offset:16384
	ds_read_b128 v[180:183], v138 offset:20480
	s_add_u32 m0, s32, 0xa000
	s_waitcnt lgkmcnt(5)
	v_mfma_f32_32x32x16_bf16 v[34:49], v[184:187], v[192:195], v[34:49]
	global_load_lds_dwordx4 v142, s[98:99]
	s_waitcnt lgkmcnt(4)
	v_mfma_f32_32x32x16_bf16 v[50:65], v[184:187], v[196:199], v[50:65]
	s_add_u32 m0, s32, 0xb000
	v_mfma_f32_32x32x16_bf16 v[2:17], v[188:191], v[192:195], v[2:17]
	global_load_lds_dwordx4 v143, s[98:99]
	v_mfma_f32_32x32x16_bf16 v[18:33], v[188:191], v[196:199], v[18:33]
	ds_read_b128 v[184:187], v135
	ds_read_b128 v[188:191], v135 offset:4096
	ds_read_b128 v[192:195], v139 offset:16384
	ds_read_b128 v[196:199], v139 offset:20480
	s_add_u32 m0, s32, 0xc000
	s_waitcnt lgkmcnt(5)
	v_mfma_f32_32x32x16_bf16 v[34:49], v[168:171], v[176:179], v[34:49]
	global_load_lds_dwordx4 v140, s[100:101]
	s_waitcnt lgkmcnt(4)
	v_mfma_f32_32x32x16_bf16 v[50:65], v[168:171], v[180:183], v[50:65]
	s_add_u32 m0, s32, 0xd000
	v_mfma_f32_32x32x16_bf16 v[2:17], v[172:175], v[176:179], v[2:17]
	global_load_lds_dwordx4 v141, s[100:101]
	v_mfma_f32_32x32x16_bf16 v[18:33], v[172:175], v[180:183], v[18:33]
	s_add_u32 m0, s32, 0xe000
	s_waitcnt lgkmcnt(1)
	v_mfma_f32_32x32x16_bf16 v[34:49], v[184:187], v[192:195], v[34:49]
	global_load_lds_dwordx4 v142, s[100:101]
	s_waitcnt lgkmcnt(0)
	v_mfma_f32_32x32x16_bf16 v[50:65], v[184:187], v[196:199], v[50:65]
	s_add_u32 m0, s32, 0xf000
	v_mfma_f32_32x32x16_bf16 v[2:17], v[188:191], v[192:195], v[2:17]
	global_load_lds_dwordx4 v143, s[100:101]
	v_mfma_f32_32x32x16_bf16 v[18:33], v[188:191], v[196:199], v[18:33]
	s_add_u32 s98, s98, 0x80
	s_addc_u32 s99, s99, 0
	s_add_u32 s100, s100, 0x80
	s_addc_u32 s101, s101, 0
	s_waitcnt vmcnt(0) lgkmcnt(0)
	s_barrier
	ds_read_b128 v[168:171], v132 offset:32768
	ds_read_b128 v[172:175], v132 offset:36864
	ds_read_b128 v[176:179], v136 offset:49152
	ds_read_b128 v[180:183], v136 offset:53248
	ds_read_b128 v[184:187], v133 offset:32768
	ds_read_b128 v[188:191], v133 offset:36864
	ds_read_b128 v[192:195], v137 offset:49152
	ds_read_b128 v[196:199], v137 offset:53248
	s_mov_b32 m0, s32
	s_waitcnt lgkmcnt(5)
	v_mfma_f32_32x32x16_bf16 v[34:49], v[168:171], v[176:179], v[34:49]
	global_load_lds_dwordx4 v140, s[98:99]
	s_waitcnt lgkmcnt(4)
	v_mfma_f32_32x32x16_bf16 v[50:65], v[168:171], v[180:183], v[50:65]
	s_add_u32 m0, s32, 0x1000
	v_mfma_f32_32x32x16_bf16 v[2:17], v[172:175], v[176:179], v[2:17]
	global_load_lds_dwordx4 v141, s[98:99]
	v_mfma_f32_32x32x16_bf16 v[18:33], v[172:175], v[180:183], v[18:33]
	ds_read_b128 v[168:171], v134 offset:32768
	ds_read_b128 v[172:175], v134 offset:36864
	ds_read_b128 v[176:179], v138 offset:49152
	ds_read_b128 v[180:183], v138 offset:53248
	s_add_u32 m0, s32, 0x2000
	s_waitcnt lgkmcnt(5)
	v_mfma_f32_32x32x16_bf16 v[34:49], v[184:187], v[192:195], v[34:49]
	global_load_lds_dwordx4 v142, s[98:99]
	s_waitcnt lgkmcnt(4)
	v_mfma_f32_32x32x16_bf16 v[50:65], v[184:187], v[196:199], v[50:65]
	s_add_u32 m0, s32, 0x3000
	v_mfma_f32_32x32x16_bf16 v[2:17], v[188:191], v[192:195], v[2:17]
	global_load_lds_dwordx4 v143, s[98:99]
	v_mfma_f32_32x32x16_bf16 v[18:33], v[188:191], v[196:199], v[18:33]
	ds_read_b128 v[184:187], v135 offset:32768
	ds_read_b128 v[188:191], v135 offset:36864
	ds_read_b128 v[192:195], v139 offset:49152
	ds_read_b128 v[196:199], v139 offset:53248
	s_add_u32 m0, s32, 0x4000
	s_waitcnt lgkmcnt(5)
	v_mfma_f32_32x32x16_bf16 v[34:49], v[168:171], v[176:179], v[34:49]
	global_load_lds_dwordx4 v140, s[100:101]
	s_waitcnt lgkmcnt(4)
	v_mfma_f32_32x32x16_bf16 v[50:65], v[168:171], v[180:183], v[50:65]
	s_add_u32 m0, s32, 0x5000
	v_mfma_f32_32x32x16_bf16 v[2:17], v[172:175], v[176:179], v[2:17]
	global_load_lds_dwordx4 v141, s[100:101]
	v_mfma_f32_32x32x16_bf16 v[18:33], v[172:175], v[180:183], v[18:33]
	s_add_u32 m0, s32, 0x6000
	s_waitcnt lgkmcnt(1)
	v_mfma_f32_32x32x16_bf16 v[34:49], v[184:187], v[192:195], v[34:49]
	global_load_lds_dwordx4 v142, s[100:101]
	s_waitcnt lgkmcnt(0)
	v_mfma_f32_32x32x16_bf16 v[50:65], v[184:187], v[196:199], v[50:65]
	s_add_u32 m0, s32, 0x7000
	v_mfma_f32_32x32x16_bf16 v[2:17], v[188:191], v[192:195], v[2:17]
	global_load_lds_dwordx4 v143, s[100:101]
	v_mfma_f32_32x32x16_bf16 v[18:33], v[188:191], v[196:199], v[18:33]
	s_add_u32 s98, s98, 0x80
	s_addc_u32 s99, s99, 0
	s_add_u32 s100, s100, 0x80
	s_addc_u32 s101, s101, 0
	s_waitcnt vmcnt(0) lgkmcnt(0)
	s_barrier
	ds_read_b128 v[168:171], v132
	ds_read_b128 v[172:175], v132 offset:4096
	ds_read_b128 v[176:179], v136 offset:16384
	ds_read_b128 v[180:183], v136 offset:20480
	ds_read_b128 v[184:187], v133
	ds_read_b128 v[188:191], v133 offset:4096
	ds_read_b128 v[192:195], v137 offset:16384
	ds_read_b128 v[196:199], v137 offset:20480
	s_add_u32 m0, s32, 0x8000
	s_waitcnt lgkmcnt(5)
	v_mfma_f32_32x32x16_bf16 v[34:49], v[168:171], v[176:179], v[34:49]
	global_load_lds_dwordx4 v140, s[98:99]
	s_waitcnt lgkmcnt(4)
	v_mfma_f32_32x32x16_bf16 v[50:65], v[168:171], v[180:183], v[50:65]
	s_add_u32 m0, s32, 0x9000
	v_mfma_f32_32x32x16_bf16 v[2:17], v[172:175], v[176:179], v[2:17]
	global_load_lds_dwordx4 v141, s[98:99]
	v_mfma_f32_32x32x16_bf16 v[18:33], v[172:175], v[180:183], v[18:33]
	ds_read_b128 v[168:171], v134
	ds_read_b128 v[172:175], v134 offset:4096
	ds_read_b128 v[176:179], v138 offset:16384
	ds_read_b128 v[180:183], v138 offset:20480
	s_add_u32 m0, s32, 0xa000
	s_waitcnt lgkmcnt(5)
	v_mfma_f32_32x32x16_bf16 v[34:49], v[184:187], v[192:195], v[34:49]
	global_load_lds_dwordx4 v142, s[98:99]
	s_waitcnt lgkmcnt(4)
	v_mfma_f32_32x32x16_bf16 v[50:65], v[184:187], v[196:199], v[50:65]
	s_add_u32 m0, s32, 0xb000
	v_mfma_f32_32x32x16_bf16 v[2:17], v[188:191], v[192:195], v[2:17]
	global_load_lds_dwordx4 v143, s[98:99]
	v_mfma_f32_32x32x16_bf16 v[18:33], v[188:191], v[196:199], v[18:33]
	ds_read_b128 v[184:187], v135
	ds_read_b128 v[188:191], v135 offset:4096
	ds_read_b128 v[192:195], v139 offset:16384
	ds_read_b128 v[196:199], v139 offset:20480
	s_add_u32 m0, s32, 0xc000
	s_waitcnt lgkmcnt(5)
	v_mfma_f32_32x32x16_bf16 v[34:49], v[168:171], v[176:179], v[34:49]
	global_load_lds_dwordx4 v140, s[100:101]
	s_waitcnt lgkmcnt(4)
	v_mfma_f32_32x32x16_bf16 v[50:65], v[168:171], v[180:183], v[50:65]
	s_add_u32 m0, s32, 0xd000
	v_mfma_f32_32x32x16_bf16 v[2:17], v[172:175], v[176:179], v[2:17]
	global_load_lds_dwordx4 v141, s[100:101]
	v_mfma_f32_32x32x16_bf16 v[18:33], v[172:175], v[180:183], v[18:33]
	s_add_u32 m0, s32, 0xe000
	s_waitcnt lgkmcnt(1)
	v_mfma_f32_32x32x16_bf16 v[34:49], v[184:187], v[192:195], v[34:49]
	global_load_lds_dwordx4 v142, s[100:101]
	s_waitcnt lgkmcnt(0)
	v_mfma_f32_32x32x16_bf16 v[50:65], v[184:187], v[196:199], v[50:65]
	s_add_u32 m0, s32, 0xf000
	v_mfma_f32_32x32x16_bf16 v[2:17], v[188:191], v[192:195], v[2:17]
	global_load_lds_dwordx4 v143, s[100:101]
	v_mfma_f32_32x32x16_bf16 v[18:33], v[188:191], v[196:199], v[18:33]
	s_add_u32 s98, s98, 0x80
	s_addc_u32 s99, s99, 0
	s_add_u32 s100, s100, 0x80
	s_addc_u32 s101, s101, 0
	s_waitcnt vmcnt(0) lgkmcnt(0)
	s_barrier
	ds_read_b128 v[168:171], v132 offset:32768
	ds_read_b128 v[172:175], v132 offset:36864
	ds_read_b128 v[176:179], v136 offset:49152
	ds_read_b128 v[180:183], v136 offset:53248
	ds_read_b128 v[184:187], v133 offset:32768
	ds_read_b128 v[188:191], v133 offset:36864
	ds_read_b128 v[192:195], v137 offset:49152
	ds_read_b128 v[196:199], v137 offset:53248
	s_mov_b32 m0, s32
	s_waitcnt lgkmcnt(5)
	v_mfma_f32_32x32x16_bf16 v[34:49], v[168:171], v[176:179], v[34:49]
	global_load_lds_dwordx4 v140, s[98:99]
	s_waitcnt lgkmcnt(4)
	v_mfma_f32_32x32x16_bf16 v[50:65], v[168:171], v[180:183], v[50:65]
	s_add_u32 m0, s32, 0x1000
	v_mfma_f32_32x32x16_bf16 v[2:17], v[172:175], v[176:179], v[2:17]
	global_load_lds_dwordx4 v141, s[98:99]
	v_mfma_f32_32x32x16_bf16 v[18:33], v[172:175], v[180:183], v[18:33]
	ds_read_b128 v[168:171], v134 offset:32768
	ds_read_b128 v[172:175], v134 offset:36864
	ds_read_b128 v[176:179], v138 offset:49152
	ds_read_b128 v[180:183], v138 offset:53248
	s_add_u32 m0, s32, 0x2000
	s_waitcnt lgkmcnt(5)
	v_mfma_f32_32x32x16_bf16 v[34:49], v[184:187], v[192:195], v[34:49]
	global_load_lds_dwordx4 v142, s[98:99]
	s_waitcnt lgkmcnt(4)
	v_mfma_f32_32x32x16_bf16 v[50:65], v[184:187], v[196:199], v[50:65]
	s_add_u32 m0, s32, 0x3000
	v_mfma_f32_32x32x16_bf16 v[2:17], v[188:191], v[192:195], v[2:17]
	global_load_lds_dwordx4 v143, s[98:99]
	v_mfma_f32_32x32x16_bf16 v[18:33], v[188:191], v[196:199], v[18:33]
	ds_read_b128 v[184:187], v135 offset:32768
	ds_read_b128 v[188:191], v135 offset:36864
	ds_read_b128 v[192:195], v139 offset:49152
	ds_read_b128 v[196:199], v139 offset:53248
	s_add_u32 m0, s32, 0x4000
	s_waitcnt lgkmcnt(5)
	v_mfma_f32_32x32x16_bf16 v[34:49], v[168:171], v[176:179], v[34:49]
	global_load_lds_dwordx4 v140, s[100:101]
	s_waitcnt lgkmcnt(4)
	v_mfma_f32_32x32x16_bf16 v[50:65], v[168:171], v[180:183], v[50:65]
	s_add_u32 m0, s32, 0x5000
	v_mfma_f32_32x32x16_bf16 v[2:17], v[172:175], v[176:179], v[2:17]
	global_load_lds_dwordx4 v141, s[100:101]
	v_mfma_f32_32x32x16_bf16 v[18:33], v[172:175], v[180:183], v[18:33]
	s_add_u32 m0, s32, 0x6000
	s_waitcnt lgkmcnt(1)
	v_mfma_f32_32x32x16_bf16 v[34:49], v[184:187], v[192:195], v[34:49]
	global_load_lds_dwordx4 v142, s[100:101]
	s_waitcnt lgkmcnt(0)
	v_mfma_f32_32x32x16_bf16 v[50:65], v[184:187], v[196:199], v[50:65]
	s_add_u32 m0, s32, 0x7000
	v_mfma_f32_32x32x16_bf16 v[2:17], v[188:191], v[192:195], v[2:17]
	global_load_lds_dwordx4 v143, s[100:101]
	v_mfma_f32_32x32x16_bf16 v[18:33], v[188:191], v[196:199], v[18:33]
	s_add_u32 s98, s98, 0x80
	s_addc_u32 s99, s99, 0
	s_add_u32 s100, s100, 0x80
	s_addc_u32 s101, s101, 0
	s_waitcnt vmcnt(0) lgkmcnt(0)
	s_barrier
	ds_read_b128 v[168:171], v132
	ds_read_b128 v[172:175], v132 offset:4096
	ds_read_b128 v[176:179], v136 offset:16384
	ds_read_b128 v[180:183], v136 offset:20480
	ds_read_b128 v[184:187], v133
	ds_read_b128 v[188:191], v133 offset:4096
	ds_read_b128 v[192:195], v137 offset:16384
	ds_read_b128 v[196:199], v137 offset:20480
	s_add_u32 m0, s32, 0x8000
	s_waitcnt lgkmcnt(5)
	v_mfma_f32_32x32x16_bf16 v[34:49], v[168:171], v[176:179], v[34:49]
	global_load_lds_dwordx4 v140, s[98:99]
	s_waitcnt lgkmcnt(4)
	v_mfma_f32_32x32x16_bf16 v[50:65], v[168:171], v[180:183], v[50:65]
	s_add_u32 m0, s32, 0x9000
	v_mfma_f32_32x32x16_bf16 v[2:17], v[172:175], v[176:179], v[2:17]
	global_load_lds_dwordx4 v141, s[98:99]
	v_mfma_f32_32x32x16_bf16 v[18:33], v[172:175], v[180:183], v[18:33]
	ds_read_b128 v[168:171], v134
	ds_read_b128 v[172:175], v134 offset:4096
	ds_read_b128 v[176:179], v138 offset:16384
	ds_read_b128 v[180:183], v138 offset:20480
	s_add_u32 m0, s32, 0xa000
	s_waitcnt lgkmcnt(5)
	v_mfma_f32_32x32x16_bf16 v[34:49], v[184:187], v[192:195], v[34:49]
	global_load_lds_dwordx4 v142, s[98:99]
	s_waitcnt lgkmcnt(4)
	v_mfma_f32_32x32x16_bf16 v[50:65], v[184:187], v[196:199], v[50:65]
	s_add_u32 m0, s32, 0xb000
	v_mfma_f32_32x32x16_bf16 v[2:17], v[188:191], v[192:195], v[2:17]
	global_load_lds_dwordx4 v143, s[98:99]
	v_mfma_f32_32x32x16_bf16 v[18:33], v[188:191], v[196:199], v[18:33]
	ds_read_b128 v[184:187], v135
	ds_read_b128 v[188:191], v135 offset:4096
	ds_read_b128 v[192:195], v139 offset:16384
	ds_read_b128 v[196:199], v139 offset:20480
	s_add_u32 m0, s32, 0xc000
	s_waitcnt lgkmcnt(5)
	v_mfma_f32_32x32x16_bf16 v[34:49], v[168:171], v[176:179], v[34:49]
	global_load_lds_dwordx4 v140, s[100:101]
	s_waitcnt lgkmcnt(4)
	v_mfma_f32_32x32x16_bf16 v[50:65], v[168:171], v[180:183], v[50:65]
	s_add_u32 m0, s32, 0xd000
	v_mfma_f32_32x32x16_bf16 v[2:17], v[172:175], v[176:179], v[2:17]
	global_load_lds_dwordx4 v141, s[100:101]
	v_mfma_f32_32x32x16_bf16 v[18:33], v[172:175], v[180:183], v[18:33]
	s_add_u32 m0, s32, 0xe000
	s_waitcnt lgkmcnt(1)
	v_mfma_f32_32x32x16_bf16 v[34:49], v[184:187], v[192:195], v[34:49]
	global_load_lds_dwordx4 v142, s[100:101]
	s_waitcnt lgkmcnt(0)
	v_mfma_f32_32x32x16_bf16 v[50:65], v[184:187], v[196:199], v[50:65]
	s_add_u32 m0, s32, 0xf000
	v_mfma_f32_32x32x16_bf16 v[2:17], v[188:191], v[192:195], v[2:17]
	global_load_lds_dwordx4 v143, s[100:101]
	v_mfma_f32_32x32x16_bf16 v[18:33], v[188:191], v[196:199], v[18:33]
	s_add_u32 s98, s98, 0x80
	s_addc_u32 s99, s99, 0
	s_add_u32 s100, s100, 0x80
	s_addc_u32 s101, s101, 0
	s_waitcnt vmcnt(0) lgkmcnt(0)
	s_barrier
	ds_read_b128 v[168:171], v132 offset:32768
	ds_read_b128 v[172:175], v132 offset:36864
	ds_read_b128 v[176:179], v136 offset:49152
	ds_read_b128 v[180:183], v136 offset:53248
	ds_read_b128 v[184:187], v133 offset:32768
	ds_read_b128 v[188:191], v133 offset:36864
	ds_read_b128 v[192:195], v137 offset:49152
	ds_read_b128 v[196:199], v137 offset:53248
	s_mov_b32 m0, s32
	s_waitcnt lgkmcnt(5)
	v_mfma_f32_32x32x16_bf16 v[34:49], v[168:171], v[176:179], v[34:49]
	global_load_lds_dwordx4 v140, s[98:99]
	s_waitcnt lgkmcnt(4)
	v_mfma_f32_32x32x16_bf16 v[50:65], v[168:171], v[180:183], v[50:65]
	s_add_u32 m0, s32, 0x1000
	v_mfma_f32_32x32x16_bf16 v[2:17], v[172:175], v[176:179], v[2:17]
	global_load_lds_dwordx4 v141, s[98:99]
	v_mfma_f32_32x32x16_bf16 v[18:33], v[172:175], v[180:183], v[18:33]
	ds_read_b128 v[168:171], v134 offset:32768
	ds_read_b128 v[172:175], v134 offset:36864
	ds_read_b128 v[176:179], v138 offset:49152
	ds_read_b128 v[180:183], v138 offset:53248
	s_add_u32 m0, s32, 0x2000
	s_waitcnt lgkmcnt(5)
	v_mfma_f32_32x32x16_bf16 v[34:49], v[184:187], v[192:195], v[34:49]
	global_load_lds_dwordx4 v142, s[98:99]
	s_waitcnt lgkmcnt(4)
	v_mfma_f32_32x32x16_bf16 v[50:65], v[184:187], v[196:199], v[50:65]
	s_add_u32 m0, s32, 0x3000
	v_mfma_f32_32x32x16_bf16 v[2:17], v[188:191], v[192:195], v[2:17]
	global_load_lds_dwordx4 v143, s[98:99]
	v_mfma_f32_32x32x16_bf16 v[18:33], v[188:191], v[196:199], v[18:33]
	ds_read_b128 v[184:187], v135 offset:32768
	ds_read_b128 v[188:191], v135 offset:36864
	ds_read_b128 v[192:195], v139 offset:49152
	ds_read_b128 v[196:199], v139 offset:53248
	s_add_u32 m0, s32, 0x4000
	s_waitcnt lgkmcnt(5)
	v_mfma_f32_32x32x16_bf16 v[34:49], v[168:171], v[176:179], v[34:49]
	global_load_lds_dwordx4 v140, s[100:101]
	s_waitcnt lgkmcnt(4)
	v_mfma_f32_32x32x16_bf16 v[50:65], v[168:171], v[180:183], v[50:65]
	s_add_u32 m0, s32, 0x5000
	v_mfma_f32_32x32x16_bf16 v[2:17], v[172:175], v[176:179], v[2:17]
	global_load_lds_dwordx4 v141, s[100:101]
	v_mfma_f32_32x32x16_bf16 v[18:33], v[172:175], v[180:183], v[18:33]
	s_add_u32 m0, s32, 0x6000
	s_waitcnt lgkmcnt(1)
	v_mfma_f32_32x32x16_bf16 v[34:49], v[184:187], v[192:195], v[34:49]
	global_load_lds_dwordx4 v142, s[100:101]
	s_waitcnt lgkmcnt(0)
	v_mfma_f32_32x32x16_bf16 v[50:65], v[184:187], v[196:199], v[50:65]
	s_add_u32 m0, s32, 0x7000
	v_mfma_f32_32x32x16_bf16 v[2:17], v[188:191], v[192:195], v[2:17]
	global_load_lds_dwordx4 v143, s[100:101]
	v_mfma_f32_32x32x16_bf16 v[18:33], v[188:191], v[196:199], v[18:33]
	s_add_u32 s98, s98, 0x80
	s_addc_u32 s99, s99, 0
	s_add_u32 s100, s100, 0x80
	s_addc_u32 s101, s101, 0
	s_waitcnt vmcnt(0) lgkmcnt(0)
	s_barrier
	ds_read_b128 v[168:171], v132
	ds_read_b128 v[172:175], v132 offset:4096
	ds_read_b128 v[176:179], v136 offset:16384
	ds_read_b128 v[180:183], v136 offset:20480
	ds_read_b128 v[184:187], v133
	ds_read_b128 v[188:191], v133 offset:4096
	ds_read_b128 v[192:195], v137 offset:16384
	ds_read_b128 v[196:199], v137 offset:20480
	s_add_u32 m0, s32, 0x8000
	s_waitcnt lgkmcnt(5)
	v_mfma_f32_32x32x16_bf16 v[34:49], v[168:171], v[176:179], v[34:49]
	global_load_lds_dwordx4 v140, s[98:99]
	s_waitcnt lgkmcnt(4)
	v_mfma_f32_32x32x16_bf16 v[50:65], v[168:171], v[180:183], v[50:65]
	s_add_u32 m0, s32, 0x9000
	v_mfma_f32_32x32x16_bf16 v[2:17], v[172:175], v[176:179], v[2:17]
	global_load_lds_dwordx4 v141, s[98:99]
	v_mfma_f32_32x32x16_bf16 v[18:33], v[172:175], v[180:183], v[18:33]
	ds_read_b128 v[168:171], v134
	ds_read_b128 v[172:175], v134 offset:4096
	ds_read_b128 v[176:179], v138 offset:16384
	ds_read_b128 v[180:183], v138 offset:20480
	s_add_u32 m0, s32, 0xa000
	s_waitcnt lgkmcnt(5)
	v_mfma_f32_32x32x16_bf16 v[34:49], v[184:187], v[192:195], v[34:49]
	global_load_lds_dwordx4 v142, s[98:99]
	s_waitcnt lgkmcnt(4)
	v_mfma_f32_32x32x16_bf16 v[50:65], v[184:187], v[196:199], v[50:65]
	s_add_u32 m0, s32, 0xb000
	v_mfma_f32_32x32x16_bf16 v[2:17], v[188:191], v[192:195], v[2:17]
	global_load_lds_dwordx4 v143, s[98:99]
	v_mfma_f32_32x32x16_bf16 v[18:33], v[188:191], v[196:199], v[18:33]
	ds_read_b128 v[184:187], v135
	ds_read_b128 v[188:191], v135 offset:4096
	ds_read_b128 v[192:195], v139 offset:16384
	ds_read_b128 v[196:199], v139 offset:20480
	s_add_u32 m0, s32, 0xc000
	s_waitcnt lgkmcnt(5)
	v_mfma_f32_32x32x16_bf16 v[34:49], v[168:171], v[176:179], v[34:49]
	global_load_lds_dwordx4 v140, s[100:101]
	s_waitcnt lgkmcnt(4)
	v_mfma_f32_32x32x16_bf16 v[50:65], v[168:171], v[180:183], v[50:65]
	s_add_u32 m0, s32, 0xd000
	v_mfma_f32_32x32x16_bf16 v[2:17], v[172:175], v[176:179], v[2:17]
	global_load_lds_dwordx4 v141, s[100:101]
	v_mfma_f32_32x32x16_bf16 v[18:33], v[172:175], v[180:183], v[18:33]
	s_add_u32 m0, s32, 0xe000
	s_waitcnt lgkmcnt(1)
	v_mfma_f32_32x32x16_bf16 v[34:49], v[184:187], v[192:195], v[34:49]
	global_load_lds_dwordx4 v142, s[100:101]
	s_waitcnt lgkmcnt(0)
	v_mfma_f32_32x32x16_bf16 v[50:65], v[184:187], v[196:199], v[50:65]
	s_add_u32 m0, s32, 0xf000
	v_mfma_f32_32x32x16_bf16 v[2:17], v[188:191], v[192:195], v[2:17]
	global_load_lds_dwordx4 v143, s[100:101]
	v_mfma_f32_32x32x16_bf16 v[18:33], v[188:191], v[196:199], v[18:33]
	s_add_u32 s98, s98, 0x80
	s_addc_u32 s99, s99, 0
	s_add_u32 s100, s100, 0x80
	s_addc_u32 s101, s101, 0
	s_waitcnt vmcnt(0) lgkmcnt(0)
	s_barrier
	ds_read_b128 v[168:171], v132 offset:32768
	ds_read_b128 v[172:175], v132 offset:36864
	ds_read_b128 v[176:179], v136 offset:49152
	ds_read_b128 v[180:183], v136 offset:53248
	ds_read_b128 v[184:187], v133 offset:32768
	ds_read_b128 v[188:191], v133 offset:36864
	ds_read_b128 v[192:195], v137 offset:49152
	ds_read_b128 v[196:199], v137 offset:53248
	s_waitcnt lgkmcnt(5)
	v_mfma_f32_32x32x16_bf16 v[34:49], v[168:171], v[176:179], v[34:49]
	s_waitcnt lgkmcnt(4)
	v_mfma_f32_32x32x16_bf16 v[50:65], v[168:171], v[180:183], v[50:65]
	v_mfma_f32_32x32x16_bf16 v[2:17], v[172:175], v[176:179], v[2:17]
	v_mfma_f32_32x32x16_bf16 v[18:33], v[172:175], v[180:183], v[18:33]
	ds_read_b128 v[168:171], v134 offset:32768
	ds_read_b128 v[172:175], v134 offset:36864
	ds_read_b128 v[176:179], v138 offset:49152
	ds_read_b128 v[180:183], v138 offset:53248
	s_waitcnt lgkmcnt(5)
	v_mfma_f32_32x32x16_bf16 v[34:49], v[184:187], v[192:195], v[34:49]
	s_waitcnt lgkmcnt(4)
	v_mfma_f32_32x32x16_bf16 v[50:65], v[184:187], v[196:199], v[50:65]
	v_mfma_f32_32x32x16_bf16 v[2:17], v[188:191], v[192:195], v[2:17]
	v_mfma_f32_32x32x16_bf16 v[18:33], v[188:191], v[196:199], v[18:33]
	ds_read_b128 v[184:187], v135 offset:32768
	ds_read_b128 v[188:191], v135 offset:36864
	ds_read_b128 v[192:195], v139 offset:49152
	ds_read_b128 v[196:199], v139 offset:53248
	s_waitcnt lgkmcnt(5)
	v_mfma_f32_32x32x16_bf16 v[34:49], v[168:171], v[176:179], v[34:49]
	s_waitcnt lgkmcnt(4)
	v_mfma_f32_32x32x16_bf16 v[50:65], v[168:171], v[180:183], v[50:65]
	v_mfma_f32_32x32x16_bf16 v[2:17], v[172:175], v[176:179], v[2:17]
	v_mfma_f32_32x32x16_bf16 v[18:33], v[172:175], v[180:183], v[18:33]
	s_waitcnt lgkmcnt(1)
	v_mfma_f32_32x32x16_bf16 v[34:49], v[184:187], v[192:195], v[34:49]
	s_waitcnt lgkmcnt(0)
	v_mfma_f32_32x32x16_bf16 v[50:65], v[184:187], v[196:199], v[50:65]
	v_mfma_f32_32x32x16_bf16 v[2:17], v[188:191], v[192:195], v[2:17]
	v_mfma_f32_32x32x16_bf16 v[18:33], v[188:191], v[196:199], v[18:33]
	s_barrier
	s_nop 8
	ds_write2_b32 v100, v34, v50 offset1:32
	ds_write2_b32 v100, v35, v51 offset0:132 offset1:164
	v_add_u32_e32 v34, 0x400, v100
	ds_write2_b32 v34, v36, v52 offset0:8 offset1:40
	ds_write2_b32 v34, v37, v53 offset0:140 offset1:172
	v_add_u32_e32 v34, 0x1000, v100
	ds_write2_b32 v34, v38, v54 offset0:32 offset1:64
	ds_write2_b32 v34, v39, v55 offset0:164 offset1:196
	v_add_u32_e32 v34, 0x1400, v100
	ds_write2_b32 v34, v40, v56 offset0:40 offset1:72
	ds_write2_b32 v34, v41, v57 offset0:172 offset1:204
	v_add_u32_e32 v34, 0x2000, v100
	ds_write2_b32 v34, v42, v58 offset0:64 offset1:96
	ds_write2_b32 v34, v43, v59 offset0:196 offset1:228
	v_add_u32_e32 v34, 0x2400, v100
	ds_write2_b32 v34, v44, v60 offset0:72 offset1:104
	ds_write2_b32 v34, v45, v61 offset0:204 offset1:236
	v_add_u32_e32 v34, 0x3000, v100
	ds_write2_b32 v34, v46, v62 offset0:96 offset1:128
	v_add_u32_e32 v34, 0x3200, v100
	ds_write2_b32 v34, v47, v63 offset0:100 offset1:132
	v_add_u32_e32 v34, 0x3400, v100
	ds_write2_b32 v34, v48, v64 offset0:104 offset1:136
	v_add_u32_e32 v34, 0x3600, v100
	ds_write2_b32 v34, v49, v65 offset0:108 offset1:140
	v_add_u32_e32 v34, 0x4000, v100
	ds_write2_b32 v34, v2, v18 offset0:128 offset1:160
	v_add_u32_e32 v2, 0x4400, v100
	ds_write2_b32 v2, v3, v19 offset0:4 offset1:36
	ds_write2_b32 v2, v4, v20 offset0:136 offset1:168
	v_add_u32_e32 v2, 0x4800, v100
	ds_write2_b32 v2, v5, v21 offset0:12 offset1:44
	v_add_u32_e32 v2, 0x5000, v100
	ds_write2_b32 v2, v6, v22 offset0:160 offset1:192
	v_add_u32_e32 v2, 0x5400, v100
	ds_write2_b32 v2, v7, v23 offset0:36 offset1:68
	ds_write2_b32 v2, v8, v24 offset0:168 offset1:200
	v_add_u32_e32 v2, 0x5800, v100
	ds_write2_b32 v2, v9, v25 offset0:44 offset1:76
	v_add_u32_e32 v2, 0x6000, v100
	ds_write2_b32 v2, v10, v26 offset0:192 offset1:224
	v_add_u32_e32 v2, 0x6400, v100
	ds_write2_b32 v2, v11, v27 offset0:68 offset1:100
	ds_write2_b32 v2, v12, v28 offset0:200 offset1:232
	v_add_u32_e32 v2, 0x6800, v100
	ds_write2_b32 v2, v13, v29 offset0:76 offset1:108
	v_add_u32_e32 v2, 0x7200, v100
	ds_write2_b32 v2, v14, v30 offset0:96 offset1:128
	v_add_u32_e32 v2, 0x7400, v100
	ds_write2_b32 v2, v15, v31 offset0:100 offset1:132
	v_add_u32_e32 v2, 0x7600, v100
	ds_write2_b32 v2, v16, v32 offset0:104 offset1:136
	v_add_u32_e32 v2, 0x7800, v100
	s_cmp_lt_i32 s9, 0
	ds_write2_b32 v2, v17, v33 offset0:108 offset1:140
	s_waitcnt lgkmcnt(0)
	s_barrier
	s_cbranch_scc1 .LBB0_773
	v_add_u32_e32 v2, s9, v105
	v_ashrrev_i32_e32 v3, 31, v2
	v_lshlrev_b64 v[2:3], 11, v[2:3]
	v_lshl_add_u32 v4, s17, 7, v105
	v_lshl_add_u64 v[2:3], s[0:1], 0, v[2:3]
	v_ashrrev_i32_e32 v5, 31, v4
	v_lshl_add_u64 v[2:3], v[2:3], 0, v[0:1]
	v_lshl_add_u64 v[238:239], v[2:3], 0, s[56:57]
	v_lshl_add_u64 v[240:241], v[238:239], 0, s[56:57]
	v_lshl_add_u64 v[242:243], v[240:241], 0, s[56:57]
	global_load_dwordx4 v[66:69], v[242:243], off
	global_load_dwordx4 v[70:73], v[240:241], off
	global_load_dwordx4 v[74:77], v[238:239], off
	global_load_dwordx4 v[78:81], v[2:3], off
	v_lshlrev_b64 v[2:3], 11, v[4:5]
	v_lshl_add_u64 v[2:3], s[4:5], 0, v[2:3]
	v_lshl_add_u64 v[2:3], v[2:3], 0, v[0:1]
	v_lshl_add_u64 v[244:245], v[2:3], 0, s[56:57]
	v_lshl_add_u64 v[246:247], v[244:245], 0, s[56:57]
	v_lshl_add_u64 v[248:249], v[246:247], 0, s[56:57]
	global_load_dwordx4 v[82:85], v[248:249], off
	global_load_dwordx4 v[86:89], v[246:247], off
	global_load_dwordx4 v[90:93], v[244:245], off
	global_load_dwordx4 v[94:97], v[2:3], off
	s_branch .LBB0_773

.LBB0_866:
	v_fma_f32 v64, v64, s58, -v160
	v_fma_f32 v65, v65, s58, -v160
	v_exp_f32_e32 v64, v64
	v_exp_f32_e32 v65, v65
	v_fma_f32 v66, v66, s58, -v160
	v_fma_f32 v67, v67, s58, -v160
	v_add_f32_e32 v222, 0, v64
	v_add_f32_e32 v223, 0, v65
	v_exp_f32_e32 v66, v66
	v_exp_f32_e32 v67, v67
	v_fma_f32 v68, v68, s58, -v160
	v_fma_f32 v69, v69, s58, -v160
	v_add_f32_e32 v222, v66, v222
	v_add_f32_e32 v223, v67, v223
	v_exp_f32_e32 v68, v68
	v_exp_f32_e32 v69, v69
	v_fma_f32 v70, v70, s58, -v160
	v_fma_f32 v71, v71, s58, -v160
	v_add_f32_e32 v222, v68, v222
	v_add_f32_e32 v223, v69, v223
	v_exp_f32_e32 v70, v70
	v_exp_f32_e32 v71, v71
	v_fma_f32 v72, v72, s58, -v160
	v_fma_f32 v73, v73, s58, -v160
	v_add_f32_e32 v222, v70, v222
	v_add_f32_e32 v223, v71, v223
	v_exp_f32_e32 v72, v72
	v_exp_f32_e32 v73, v73
	v_fma_f32 v74, v74, s58, -v160
	v_fma_f32 v75, v75, s58, -v160
	v_add_f32_e32 v222, v72, v222
	v_add_f32_e32 v223, v73, v223
	v_exp_f32_e32 v74, v74
	v_exp_f32_e32 v75, v75
	v_fma_f32 v76, v76, s58, -v160
	v_fma_f32 v77, v77, s58, -v160
	v_add_f32_e32 v222, v74, v222
	v_add_f32_e32 v223, v75, v223
	v_exp_f32_e32 v76, v76
	v_exp_f32_e32 v77, v77
	v_fma_f32 v78, v78, s58, -v160
	v_fma_f32 v79, v79, s58, -v160
	v_add_f32_e32 v222, v76, v222
	v_add_f32_e32 v223, v77, v223
	v_exp_f32_e32 v78, v78
	v_exp_f32_e32 v79, v79
	v_fma_f32 v48, v48, s58, -v160
	v_fma_f32 v49, v49, s58, -v160
	v_add_f32_e32 v222, v78, v222
	v_add_f32_e32 v223, v79, v223
	v_exp_f32_e32 v164, v48
	v_exp_f32_e32 v165, v49
	v_fma_f32 v50, v50, s58, -v160
	v_fma_f32 v51, v51, s58, -v160
	v_add_f32_e32 v222, v164, v222
	v_add_f32_e32 v223, v165, v223
	v_exp_f32_e32 v166, v50
	v_exp_f32_e32 v167, v51
	v_fma_f32 v52, v52, s58, -v160
	v_fma_f32 v53, v53, s58, -v160
	v_add_f32_e32 v222, v166, v222
	v_add_f32_e32 v223, v167, v223
	v_exp_f32_e32 v168, v52
	v_exp_f32_e32 v169, v53
	v_fma_f32 v54, v54, s58, -v160
	v_fma_f32 v55, v55, s58, -v160
	v_add_f32_e32 v222, v168, v222
	v_add_f32_e32 v223, v169, v223
	v_exp_f32_e32 v170, v54
	v_exp_f32_e32 v171, v55
	v_fma_f32 v56, v56, s58, -v160
	v_fma_f32 v57, v57, s58, -v160
	v_add_f32_e32 v222, v170, v222
	v_add_f32_e32 v223, v171, v223
	v_exp_f32_e32 v162, v56
	v_exp_f32_e32 v163, v57
	v_fma_f32 v58, v58, s58, -v160
	v_fma_f32 v59, v59, s58, -v160
	v_add_f32_e32 v222, v162, v222
	v_add_f32_e32 v223, v163, v223
	v_exp_f32_e32 v172, v58
	v_exp_f32_e32 v173, v59
	v_fma_f32 v60, v60, s58, -v160
	v_fma_f32 v61, v61, s58, -v160
	v_add_f32_e32 v222, v172, v222
	v_add_f32_e32 v223, v173, v223
	v_exp_f32_e32 v174, v60
	v_exp_f32_e32 v175, v61
	v_fma_f32 v62, v62, s58, -v160
	v_fma_f32 v63, v63, s58, -v160
	v_add_f32_e32 v222, v174, v222
	v_add_f32_e32 v223, v175, v223
	v_exp_f32_e32 v176, v62
	v_exp_f32_e32 v177, v63
	s_add_i32 s7, s7, 1
	v_add_f32_e32 v222, v176, v222
	v_add_f32_e32 v223, v177, v223
	s_nop 0
	v_add_f32_e32 v15, v222, v223
	s_setprio 1
	ds_read2_b64 v[52:55], v14 offset0:132 offset1:134
	ds_read2_b64 v[56:59], v0 offset0:164 offset1:166
	v_cvt_pk_bf16_f32 v48, v64, v65
	v_cvt_pk_bf16_f32 v49, v66, v67
	v_cvt_pk_bf16_f32 v50, v68, v69
	v_cvt_pk_bf16_f32 v51, v70, v71
	s_waitcnt lgkmcnt(3)
	s_nop 0
	v_mfma_f32_32x32x16_bf16 v[32:47], v[100:103], v[48:51], v[32:47]
	s_waitcnt lgkmcnt(2)
	v_mfma_f32_32x32x16_bf16 v[16:31], v[104:107], v[48:51], v[16:31]
	ds_read2_b64 v[60:63], v14 offset0:136 offset1:138
	ds_read2_b64 v[64:67], v0 offset0:168 offset1:170
	v_cvt_pk_bf16_f32 v48, v72, v73
	v_cvt_pk_bf16_f32 v49, v74, v75
	v_cvt_pk_bf16_f32 v50, v76, v77
	v_cvt_pk_bf16_f32 v51, v78, v79
	s_waitcnt lgkmcnt(3)
	s_nop 0
	v_mfma_f32_32x32x16_bf16 v[32:47], v[52:55], v[48:51], v[32:47]
	s_waitcnt lgkmcnt(2)
	v_mfma_f32_32x32x16_bf16 v[16:31], v[56:59], v[48:51], v[16:31]
	ds_read2_b64 v[52:55], v14 offset0:140 offset1:142
	ds_read2_b64 v[56:59], v0 offset0:172 offset1:174
	v_cvt_pk_bf16_f32 v48, v164, v165
	v_cvt_pk_bf16_f32 v49, v166, v167
	v_cvt_pk_bf16_f32 v50, v168, v169
	v_cvt_pk_bf16_f32 v51, v170, v171
	s_waitcnt lgkmcnt(3)
	s_nop 0
	v_mfma_f32_32x32x16_bf16 v[32:47], v[60:63], v[48:51], v[32:47]
	s_waitcnt lgkmcnt(2)
	v_mfma_f32_32x32x16_bf16 v[16:31], v[64:67], v[48:51], v[16:31]
	v_cvt_pk_bf16_f32 v48, v162, v163
	v_cvt_pk_bf16_f32 v49, v172, v173
	v_cvt_pk_bf16_f32 v50, v174, v175
	v_cvt_pk_bf16_f32 v51, v176, v177
	s_waitcnt lgkmcnt(1)
	s_nop 0
	v_mfma_f32_32x32x16_bf16 v[32:47], v[52:55], v[48:51], v[32:47]
	s_waitcnt lgkmcnt(0)
	v_mfma_f32_32x32x16_bf16 v[16:31], v[56:59], v[48:51], v[16:31]
	v_add_f32_e32 v141, v141, v15
	s_setprio 0
	s_bitcmp1_b32 s7, 0
	s_cselect_b32 s0, 0x4600, 0
	v_add3_u32 v0, s0, v194, v195
	s_waitcnt vmcnt(3)
	ds_write_b128 v0, v[96:99]
	v_add3_u32 v0, s0, v196, v197
	s_waitcnt vmcnt(2)
	ds_write_b128 v0, v[10:13]
	v_or_b32_e32 v0, s0, v198
	v_add3_u32 v10, v0, v199, s33
	v_add3_u32 v0, v0, v200, s33
	v_lshl_add_u64 v[156:157], v[156:157], 0, s[52:53]
	v_lshl_add_u64 v[158:159], v[158:159], 0, s[52:53]
	v_lshl_add_u64 v[152:153], v[152:153], 0, s[60:61]
	s_cmp_eq_u32 s10, s7
	v_lshl_add_u64 v[154:155], v[154:155], 0, s[60:61]
	s_waitcnt vmcnt(1)
	ds_write2_b64 v10, v[2:3], v[4:5] offset1:1
	s_waitcnt vmcnt(0)
	ds_write2_b64 v0, v[6:7], v[8:9] offset1:1
	s_waitcnt lgkmcnt(0)
	s_barrier
	s_cbranch_scc1 .LBB0_788

.LBB0_871:
	s_andn2_b64 vcc, exec, s[0:1]
	s_cbranch_vccnz .LBB0_1316
	s_cmp_gt_i32 s96, 1
	s_mov_b64 s[0:1], -1
	s_cbranch_scc0 .LBB0_1128
	s_load_dword s0, s[46:47], 0x0
	v_readlane_b32 s4, v254, 12
	s_ashr_i32 s3, s4, 3
	s_waitcnt lgkmcnt(0)
	s_and_b32 s1, s0, -8
	s_cmp_ge_i32 s4, s1
	s_cselect_b64 s[4:5], -1, 0
	s_cmpk_gt_i32 s3, 0x1af
	s_cselect_b64 s[6:7], -1, 0
	s_or_b64 s[4:5], s[6:7], s[4:5]
	s_and_b64 vcc, exec, s[4:5]
	s_cbranch_vccnz .LBB0_1127
	v_ashrrev_i32_e32 v103, 7, v146
	v_and_b32_e32 v3, 31, v146
	v_bfe_u32 v4, v146, 5, 1
	s_waitcnt vmcnt(0)
	v_lshlrev_b32_e32 v0, 2, v146
	v_lshlrev_b32_e32 v6, 6, v103
	s_add_u32 s8, s62, 0x14f5000
	v_readlane_b32 s1, v254, 12
	v_bfe_u32 v2, v146, 6, 1
	v_and_b32_e32 v5, 4, v0
	s_movk_i32 s4, 0x90
	v_or_b32_e32 v7, v6, v3
	v_lshlrev_b32_e32 v0, 4, v4
	s_addc_u32 s9, s63, 0
	s_and_b32 s26, s1, 7
	s_lshr_b32 s27, s0, 3
	v_lshl_or_b32 v8, v2, 6, v3
	v_mad_u64_u32 v[98:99], s[0:1], v7, s4, v[0:1]
	v_ashrrev_i32_e32 v105, 1, v146
	v_mad_u32_u24 v99, v8, s4, v0
	v_lshlrev_b32_e32 v0, 2, v3
	v_ashrrev_i32_e32 v105, 3, v146
	v_lshlrev_b32_e32 v107, 7, v105
	v_lshl_or_b32 v0, v2, 8, v0
	v_lshl_or_b32 v2, v4, 2, v6
	s_movk_i32 s4, 0x210
	v_mad_u64_u32 v[100:101], s[0:1], v2, s4, v[0:1]
	v_lshlrev_b32_e32 v0, 3, v146
	v_mov_b32_e32 v2, 0x78
	v_and_b32_e32 v104, 56, v0
	v_bitop3_b32 v106, v0, 16, 56 bitop3:0x6c
	v_and_b32_e32 v101, 0x78, v0
	v_bitop3_b32 v2, v0, 16, v2 bitop3:0x6c
	v_and_b32_e32 v3, 4, v146
	v_and_b32_e32 v115, 8, v0
	v_and_b32_e32 v0, 2, v146
	v_ashrrev_i32_e32 v116, 4, v146
	v_cmp_eq_u32_e64 s[38:39], 0, v3
	v_cmp_eq_u32_e64 s[40:41], 0, v0
	v_mul_lo_u32 v3, v116, s4
	v_lshlrev_b32_e32 v0, 2, v101
	v_lshlrev_b32_e32 v2, 2, v2
	v_add_u32_e32 v117, v3, v0
	v_add_u32_e32 v118, v3, v2
	v_add_u32_e32 v3, 0x100, v146
	v_ashrrev_i32_e32 v119, 4, v3
	v_mul_lo_u32 v3, v119, s4
	v_add_u32_e32 v120, v3, v0
	v_add_u32_e32 v121, v3, v2
	v_add_u32_e32 v3, 0x200, v146
	v_ashrrev_i32_e32 v122, 4, v3
	v_mul_lo_u32 v3, v122, s4
	v_add_u32_e32 v123, v3, v0
	v_add_u32_e32 v124, v3, v2
	v_add_u32_e32 v3, 0x300, v146
	v_ashrrev_i32_e32 v125, 4, v3
	v_mul_lo_u32 v3, v125, s4
	v_add_u32_e32 v126, v3, v0
	v_add_u32_e32 v127, v3, v2
	v_add_u32_e32 v3, 0x400, v146
	v_ashrrev_i32_e32 v128, 4, v3
	v_mul_lo_u32 v3, v128, s4
	v_add_u32_e32 v129, v3, v0
	v_add_u32_e32 v130, v3, v2
	v_add_u32_e32 v3, 0x500, v146
	v_ashrrev_i32_e32 v131, 4, v3
	v_mul_lo_u32 v3, v131, s4
	v_add_u32_e32 v132, v3, v0
	v_add_u32_e32 v133, v3, v2
	v_add_u32_e32 v3, 0x600, v146
	v_ashrrev_i32_e32 v134, 4, v3
	v_mul_lo_u32 v3, v134, s4
	s_add_u32 s10, s62, 0x10d2000
	v_add_u32_e32 v135, v3, v0
	v_add_u32_e32 v136, v3, v2
	v_add_u32_e32 v3, 0x700, v146
	s_addc_u32 s11, s63, 0
	v_ashrrev_i32_e32 v137, 4, v3
	v_readlane_b32 s0, v254, 13
	s_add_u32 s12, s62, 0x10d3000
	v_mul_lo_u32 v3, v137, s4
	v_readlane_b32 s1, v254, 14
	v_and_b32_e32 v114, 7, v146
	v_lshlrev_b32_e32 v114, 4, v114
	s_addc_u32 s13, s63, 0
	v_add_u32_e32 v138, v3, v0
	v_add_u32_e32 v139, v3, v2
	v_lshl_add_u64 v[2:3], s[0:1], 0, v[0:1]
	s_mov_b64 s[0:1], 0x6400000
	v_and_b32_e32 v140, 0x7f, v146
	v_lshlrev_b32_e32 v0, 8, v103
	s_add_u32 s14, s62, 0x44f5000
	v_lshl_add_u64 v[108:109], v[2:3], 0, s[0:1]
	v_mad_u32_u24 v141, v140, s4, v0
	v_add_u32_e32 v0, 0x1000, v114
	v_add_u32_e32 v2, 0x2000, v114
	v_add_u32_e32 v3, 0x3000, v114
	v_bfe_u32 v102, v146, 4, 3
	v_lshlrev_b32_e32 v102, 4, v102
	v_xor_b32_e32 v102, v102, v114
	v_lshrrev_b32_e32 v102, 1, v102
	s_mov_b32 s28, 0
	s_addc_u32 s15, s63, 0
	s_mov_b32 s29, -1
	s_mov_b64 s[4:5], 0
	v_add_u32_e32 v142, v107, v0
	v_add_u32_e32 v143, v107, v2
	v_add_u32_e32 v144, v107, v3
	s_branch .LBB0_876

.LBB0_880:
	s_lshl_b32 s31, s30, 7
	v_add_u32_e32 v2, s31, v105
	s_lshl_b32 s24, s34, 7
	v_ashrrev_i32_e32 v3, 31, v2
	s_xor_b64 s[6:7], s[4:5], -1
	v_lshlrev_b64 v[2:3], 11, v[2:3]
	s_waitcnt vmcnt(0)
	v_add_u32_e32 v38, s24, v105
	s_lshl_b32 s98, s31, 11
	s_add_u32 s98, s8, s98
	s_addc_u32 s99, s9, 0
	s_lshl_b32 s100, s24, 11
	s_add_u32 s100, s62, s100
	s_addc_u32 s101, s63, 0
	s_mov_b64 s[4:5], -1
	s_andn2_b64 vcc, exec, s[6:7]
	v_lshl_add_u64 v[34:35], s[8:9], 0, v[2:3]
	v_ashrrev_i32_e32 v39, 31, v38
	v_lshlrev_b32_e32 v0, 1, v102
	s_cbranch_vccnz .LBB0_882
	v_lshlrev_b64 v[36:37], 11, v[38:39]
	v_lshl_add_u64 v[2:3], s[62:63], 0, v[36:37]
	v_lshl_add_u64 v[30:31], v[34:35], 0, v[0:1]
	v_lshl_add_u64 v[14:15], v[2:3], 0, v[0:1]
	v_lshl_add_u64 v[246:247], v[14:15], 0, s[56:57]
	v_lshl_add_u64 v[248:249], v[246:247], 0, s[56:57]
	v_lshl_add_u64 v[250:251], v[248:249], 0, s[56:57]
	v_lshl_add_u64 v[240:241], v[30:31], 0, s[56:57]
	v_lshl_add_u64 v[242:243], v[240:241], 0, s[56:57]
	v_lshl_add_u64 v[244:245], v[242:243], 0, s[56:57]
	global_load_dwordx4 v[2:5], v[250:251], off
	global_load_dwordx4 v[6:9], v[248:249], off
	global_load_dwordx4 v[10:13], v[246:247], off
	s_nop 0
	global_load_dwordx4 v[14:17], v[14:15], off
	s_nop 0
	global_load_dwordx4 v[18:21], v[244:245], off
	global_load_dwordx4 v[22:25], v[242:243], off
	global_load_dwordx4 v[26:29], v[240:241], off
	s_nop 0
	global_load_dwordx4 v[30:33], v[30:31], off
	s_mov_b64 s[4:5], 0

.LBB0_884:
	v_add_u32_e32 v145, v107, v114
	v_lshrrev_b32_e32 v160, 6, v146
	v_lshlrev_b32_e32 v160, 10, v160
	v_lshl_add_u32 v156, v105, 11, v0
	v_readfirstlane_b32 s32, v160
	v_add_u32_e32 v157, 0x10000, v156
	v_add_u32_e32 v158, 0x20000, v156
	v_add_u32_e32 v159, 0x30000, v156
	v_bfe_u32 v160, v146, 1, 3
	v_bfe_u32 v161, v146, 5, 1
	v_xor_b32_e32 v160, v160, v161
	v_lshlrev_b32_e32 v160, 4, v160
	v_and_b32_e32 v161, 31, v146
	v_lshrrev_b32_e32 v162, 7, v146
	v_lshl_add_u32 v162, v162, 6, v161
	v_lshl_add_u32 v148, v162, 7, v160
	v_bfe_u32 v162, v146, 6, 1
	v_lshl_add_u32 v162, v162, 6, v161
	v_lshl_add_u32 v152, v162, 7, v160
	v_xor_b32_e32 v149, 32, v148
	v_xor_b32_e32 v153, 32, v152
	v_xor_b32_e32 v150, 64, v148
	v_xor_b32_e32 v154, 64, v152
	v_xor_b32_e32 v151, 96, v148
	v_xor_b32_e32 v155, 96, v152
	s_add_u32 s98, s98, 0x80
	s_addc_u32 s99, s99, 0
	s_add_u32 s100, s100, 0x80
	s_addc_u32 s101, s101, 0
	s_add_u32 m0, s32, 0x8000
	s_nop 0
	global_load_lds_dwordx4 v156, s[98:99]
	s_add_u32 m0, s32, 0x9000
	s_nop 0
	global_load_lds_dwordx4 v157, s[98:99]
	s_add_u32 m0, s32, 0xa000
	s_nop 0
	global_load_lds_dwordx4 v158, s[98:99]
	s_add_u32 m0, s32, 0xb000
	s_nop 0
	global_load_lds_dwordx4 v159, s[98:99]
	s_add_u32 m0, s32, 0xc000
	s_nop 0
	global_load_lds_dwordx4 v156, s[100:101]
	s_add_u32 m0, s32, 0xd000
	s_nop 0
	global_load_lds_dwordx4 v157, s[100:101]
	s_add_u32 m0, s32, 0xe000
	s_nop 0
	global_load_lds_dwordx4 v158, s[100:101]
	s_add_u32 m0, s32, 0xf000
	s_nop 0
	global_load_lds_dwordx4 v159, s[100:101]
	s_add_u32 s98, s98, 0x80
	s_addc_u32 s99, s99, 0
	s_add_u32 s100, s100, 0x80
	s_addc_u32 s101, s101, 0
	s_waitcnt vmcnt(8)
	ds_write_b128 v145, v[30:33]
	ds_write_b128 v145, v[14:17] offset:16384
	ds_write_b128 v142, v[26:29]
	ds_write_b128 v142, v[10:13] offset:16384
	ds_write_b128 v143, v[22:25]
	ds_write_b128 v143, v[6:9] offset:16384
	ds_write_b128 v144, v[18:21]
	ds_write_b128 v144, v[2:5] offset:16384
	s_lshl_b32 s4, s29, 7
	s_and_b64 s[0:1], s[0:1], exec
	s_cselect_b32 s0, s4, -1
	s_waitcnt lgkmcnt(0)
	s_barrier
	ds_read_b128 v[180:183], v148
	ds_read_b128 v[184:187], v148 offset:4096
	ds_read_b128 v[188:191], v152 offset:16384
	ds_read_b128 v[192:195], v152 offset:20480
	ds_read_b128 v[196:199], v149
	ds_read_b128 v[200:203], v149 offset:4096
	ds_read_b128 v[232:235], v153 offset:16384
	ds_read_b128 v[236:239], v153 offset:20480
	s_waitcnt lgkmcnt(5)
	v_mfma_f32_32x32x16_bf16 v[34:49], v[180:183], v[188:191], 0
	s_waitcnt lgkmcnt(4)
	v_mfma_f32_32x32x16_bf16 v[50:65], v[180:183], v[192:195], 0
	v_mfma_f32_32x32x16_bf16 v[2:17], v[184:187], v[188:191], 0
	v_mfma_f32_32x32x16_bf16 v[18:33], v[184:187], v[192:195], 0
	ds_read_b128 v[180:183], v150
	ds_read_b128 v[184:187], v150 offset:4096
	ds_read_b128 v[188:191], v154 offset:16384
	ds_read_b128 v[192:195], v154 offset:20480
	s_waitcnt lgkmcnt(5)
	v_mfma_f32_32x32x16_bf16 v[34:49], v[196:199], v[232:235], v[34:49]
	s_waitcnt lgkmcnt(4)
	v_mfma_f32_32x32x16_bf16 v[50:65], v[196:199], v[236:239], v[50:65]
	v_mfma_f32_32x32x16_bf16 v[2:17], v[200:203], v[232:235], v[2:17]
	v_mfma_f32_32x32x16_bf16 v[18:33], v[200:203], v[236:239], v[18:33]
	ds_read_b128 v[196:199], v151
	ds_read_b128 v[200:203], v151 offset:4096
	ds_read_b128 v[232:235], v155 offset:16384
	ds_read_b128 v[236:239], v155 offset:20480
	s_waitcnt lgkmcnt(5)
	v_mfma_f32_32x32x16_bf16 v[34:49], v[180:183], v[188:191], v[34:49]
	s_waitcnt lgkmcnt(4)
	v_mfma_f32_32x32x16_bf16 v[50:65], v[180:183], v[192:195], v[50:65]
	v_mfma_f32_32x32x16_bf16 v[2:17], v[184:187], v[188:191], v[2:17]
	v_mfma_f32_32x32x16_bf16 v[18:33], v[184:187], v[192:195], v[18:33]
	s_waitcnt lgkmcnt(1)
	v_mfma_f32_32x32x16_bf16 v[34:49], v[196:199], v[232:235], v[34:49]
	s_waitcnt lgkmcnt(0)
	v_mfma_f32_32x32x16_bf16 v[50:65], v[196:199], v[236:239], v[50:65]
	v_mfma_f32_32x32x16_bf16 v[2:17], v[200:203], v[232:235], v[2:17]
	v_mfma_f32_32x32x16_bf16 v[18:33], v[200:203], v[236:239], v[18:33]
	s_waitcnt vmcnt(0) lgkmcnt(0)
	s_barrier
	ds_read_b128 v[180:183], v148 offset:32768
	ds_read_b128 v[184:187], v148 offset:36864
	ds_read_b128 v[188:191], v152 offset:49152
	ds_read_b128 v[192:195], v152 offset:53248
	ds_read_b128 v[196:199], v149 offset:32768
	ds_read_b128 v[200:203], v149 offset:36864
	ds_read_b128 v[232:235], v153 offset:49152
	ds_read_b128 v[236:239], v153 offset:53248
	s_mov_b32 m0, s32
	s_waitcnt lgkmcnt(5)
	v_mfma_f32_32x32x16_bf16 v[34:49], v[180:183], v[188:191], v[34:49]
	global_load_lds_dwordx4 v156, s[98:99]
	s_waitcnt lgkmcnt(4)
	v_mfma_f32_32x32x16_bf16 v[50:65], v[180:183], v[192:195], v[50:65]
	s_add_u32 m0, s32, 0x1000
	v_mfma_f32_32x32x16_bf16 v[2:17], v[184:187], v[188:191], v[2:17]
	global_load_lds_dwordx4 v157, s[98:99]
	v_mfma_f32_32x32x16_bf16 v[18:33], v[184:187], v[192:195], v[18:33]
	ds_read_b128 v[180:183], v150 offset:32768
	ds_read_b128 v[184:187], v150 offset:36864
	ds_read_b128 v[188:191], v154 offset:49152
	ds_read_b128 v[192:195], v154 offset:53248
	s_add_u32 m0, s32, 0x2000
	s_waitcnt lgkmcnt(5)
	v_mfma_f32_32x32x16_bf16 v[34:49], v[196:199], v[232:235], v[34:49]
	global_load_lds_dwordx4 v158, s[98:99]
	s_waitcnt lgkmcnt(4)
	v_mfma_f32_32x32x16_bf16 v[50:65], v[196:199], v[236:239], v[50:65]
	s_add_u32 m0, s32, 0x3000
	v_mfma_f32_32x32x16_bf16 v[2:17], v[200:203], v[232:235], v[2:17]
	global_load_lds_dwordx4 v159, s[98:99]
	v_mfma_f32_32x32x16_bf16 v[18:33], v[200:203], v[236:239], v[18:33]
	ds_read_b128 v[196:199], v151 offset:32768
	ds_read_b128 v[200:203], v151 offset:36864
	ds_read_b128 v[232:235], v155 offset:49152
	ds_read_b128 v[236:239], v155 offset:53248
	s_add_u32 m0, s32, 0x4000
	s_waitcnt lgkmcnt(5)
	v_mfma_f32_32x32x16_bf16 v[34:49], v[180:183], v[188:191], v[34:49]
	global_load_lds_dwordx4 v156, s[100:101]
	s_waitcnt lgkmcnt(4)
	v_mfma_f32_32x32x16_bf16 v[50:65], v[180:183], v[192:195], v[50:65]
	s_add_u32 m0, s32, 0x5000
	v_mfma_f32_32x32x16_bf16 v[2:17], v[184:187], v[188:191], v[2:17]
	global_load_lds_dwordx4 v157, s[100:101]
	v_mfma_f32_32x32x16_bf16 v[18:33], v[184:187], v[192:195], v[18:33]
	s_add_u32 m0, s32, 0x6000
	s_waitcnt lgkmcnt(1)
	v_mfma_f32_32x32x16_bf16 v[34:49], v[196:199], v[232:235], v[34:49]
	global_load_lds_dwordx4 v158, s[100:101]
	s_waitcnt lgkmcnt(0)
	v_mfma_f32_32x32x16_bf16 v[50:65], v[196:199], v[236:239], v[50:65]
	s_add_u32 m0, s32, 0x7000
	v_mfma_f32_32x32x16_bf16 v[2:17], v[200:203], v[232:235], v[2:17]
	global_load_lds_dwordx4 v159, s[100:101]
	v_mfma_f32_32x32x16_bf16 v[18:33], v[200:203], v[236:239], v[18:33]
	s_add_u32 s98, s98, 0x80
	s_addc_u32 s99, s99, 0
	s_add_u32 s100, s100, 0x80
	s_addc_u32 s101, s101, 0
	s_waitcnt vmcnt(0) lgkmcnt(0)
	s_barrier
	ds_read_b128 v[180:183], v148
	ds_read_b128 v[184:187], v148 offset:4096
	ds_read_b128 v[188:191], v152 offset:16384
	ds_read_b128 v[192:195], v152 offset:20480
	ds_read_b128 v[196:199], v149
	ds_read_b128 v[200:203], v149 offset:4096
	ds_read_b128 v[232:235], v153 offset:16384
	ds_read_b128 v[236:239], v153 offset:20480
	s_add_u32 m0, s32, 0x8000
	s_waitcnt lgkmcnt(5)
	v_mfma_f32_32x32x16_bf16 v[34:49], v[180:183], v[188:191], v[34:49]
	global_load_lds_dwordx4 v156, s[98:99]
	s_waitcnt lgkmcnt(4)
	v_mfma_f32_32x32x16_bf16 v[50:65], v[180:183], v[192:195], v[50:65]
	s_add_u32 m0, s32, 0x9000
	v_mfma_f32_32x32x16_bf16 v[2:17], v[184:187], v[188:191], v[2:17]
	global_load_lds_dwordx4 v157, s[98:99]
	v_mfma_f32_32x32x16_bf16 v[18:33], v[184:187], v[192:195], v[18:33]
	ds_read_b128 v[180:183], v150
	ds_read_b128 v[184:187], v150 offset:4096
	ds_read_b128 v[188:191], v154 offset:16384
	ds_read_b128 v[192:195], v154 offset:20480
	s_add_u32 m0, s32, 0xa000
	s_waitcnt lgkmcnt(5)
	v_mfma_f32_32x32x16_bf16 v[34:49], v[196:199], v[232:235], v[34:49]
	global_load_lds_dwordx4 v158, s[98:99]
	s_waitcnt lgkmcnt(4)
	v_mfma_f32_32x32x16_bf16 v[50:65], v[196:199], v[236:239], v[50:65]
	s_add_u32 m0, s32, 0xb000
	v_mfma_f32_32x32x16_bf16 v[2:17], v[200:203], v[232:235], v[2:17]
	global_load_lds_dwordx4 v159, s[98:99]
	v_mfma_f32_32x32x16_bf16 v[18:33], v[200:203], v[236:239], v[18:33]
	ds_read_b128 v[196:199], v151
	ds_read_b128 v[200:203], v151 offset:4096
	ds_read_b128 v[232:235], v155 offset:16384
	ds_read_b128 v[236:239], v155 offset:20480
	s_add_u32 m0, s32, 0xc000
	s_waitcnt lgkmcnt(5)
	v_mfma_f32_32x32x16_bf16 v[34:49], v[180:183], v[188:191], v[34:49]
	global_load_lds_dwordx4 v156, s[100:101]
	s_waitcnt lgkmcnt(4)
	v_mfma_f32_32x32x16_bf16 v[50:65], v[180:183], v[192:195], v[50:65]
	s_add_u32 m0, s32, 0xd000
	v_mfma_f32_32x32x16_bf16 v[2:17], v[184:187], v[188:191], v[2:17]
	global_load_lds_dwordx4 v157, s[100:101]
	v_mfma_f32_32x32x16_bf16 v[18:33], v[184:187], v[192:195], v[18:33]
	s_add_u32 m0, s32, 0xe000
	s_waitcnt lgkmcnt(1)
	v_mfma_f32_32x32x16_bf16 v[34:49], v[196:199], v[232:235], v[34:49]
	global_load_lds_dwordx4 v158, s[100:101]
	s_waitcnt lgkmcnt(0)
	v_mfma_f32_32x32x16_bf16 v[50:65], v[196:199], v[236:239], v[50:65]
	s_add_u32 m0, s32, 0xf000
	v_mfma_f32_32x32x16_bf16 v[2:17], v[200:203], v[232:235], v[2:17]
	global_load_lds_dwordx4 v159, s[100:101]
	v_mfma_f32_32x32x16_bf16 v[18:33], v[200:203], v[236:239], v[18:33]
	s_add_u32 s98, s98, 0x80
	s_addc_u32 s99, s99, 0
	s_add_u32 s100, s100, 0x80
	s_addc_u32 s101, s101, 0
	s_waitcnt vmcnt(0) lgkmcnt(0)
	s_barrier
	ds_read_b128 v[180:183], v148 offset:32768
	ds_read_b128 v[184:187], v148 offset:36864
	ds_read_b128 v[188:191], v152 offset:49152
	ds_read_b128 v[192:195], v152 offset:53248
	ds_read_b128 v[196:199], v149 offset:32768
	ds_read_b128 v[200:203], v149 offset:36864
	ds_read_b128 v[232:235], v153 offset:49152
	ds_read_b128 v[236:239], v153 offset:53248
	s_mov_b32 m0, s32
	s_waitcnt lgkmcnt(5)
	v_mfma_f32_32x32x16_bf16 v[34:49], v[180:183], v[188:191], v[34:49]
	global_load_lds_dwordx4 v156, s[98:99]
	s_waitcnt lgkmcnt(4)
	v_mfma_f32_32x32x16_bf16 v[50:65], v[180:183], v[192:195], v[50:65]
	s_add_u32 m0, s32, 0x1000
	v_mfma_f32_32x32x16_bf16 v[2:17], v[184:187], v[188:191], v[2:17]
	global_load_lds_dwordx4 v157, s[98:99]
	v_mfma_f32_32x32x16_bf16 v[18:33], v[184:187], v[192:195], v[18:33]
	ds_read_b128 v[180:183], v150 offset:32768
	ds_read_b128 v[184:187], v150 offset:36864
	ds_read_b128 v[188:191], v154 offset:49152
	ds_read_b128 v[192:195], v154 offset:53248
	s_add_u32 m0, s32, 0x2000
	s_waitcnt lgkmcnt(5)
	v_mfma_f32_32x32x16_bf16 v[34:49], v[196:199], v[232:235], v[34:49]
	global_load_lds_dwordx4 v158, s[98:99]
	s_waitcnt lgkmcnt(4)
	v_mfma_f32_32x32x16_bf16 v[50:65], v[196:199], v[236:239], v[50:65]
	s_add_u32 m0, s32, 0x3000
	v_mfma_f32_32x32x16_bf16 v[2:17], v[200:203], v[232:235], v[2:17]
	global_load_lds_dwordx4 v159, s[98:99]
	v_mfma_f32_32x32x16_bf16 v[18:33], v[200:203], v[236:239], v[18:33]
	ds_read_b128 v[196:199], v151 offset:32768
	ds_read_b128 v[200:203], v151 offset:36864
	ds_read_b128 v[232:235], v155 offset:49152
	ds_read_b128 v[236:239], v155 offset:53248
	s_add_u32 m0, s32, 0x4000
	s_waitcnt lgkmcnt(5)
	v_mfma_f32_32x32x16_bf16 v[34:49], v[180:183], v[188:191], v[34:49]
	global_load_lds_dwordx4 v156, s[100:101]
	s_waitcnt lgkmcnt(4)
	v_mfma_f32_32x32x16_bf16 v[50:65], v[180:183], v[192:195], v[50:65]
	s_add_u32 m0, s32, 0x5000
	v_mfma_f32_32x32x16_bf16 v[2:17], v[184:187], v[188:191], v[2:17]
	global_load_lds_dwordx4 v157, s[100:101]
	v_mfma_f32_32x32x16_bf16 v[18:33], v[184:187], v[192:195], v[18:33]
	s_add_u32 m0, s32, 0x6000
	s_waitcnt lgkmcnt(1)
	v_mfma_f32_32x32x16_bf16 v[34:49], v[196:199], v[232:235], v[34:49]
	global_load_lds_dwordx4 v158, s[100:101]
	s_waitcnt lgkmcnt(0)
	v_mfma_f32_32x32x16_bf16 v[50:65], v[196:199], v[236:239], v[50:65]
	s_add_u32 m0, s32, 0x7000
	v_mfma_f32_32x32x16_bf16 v[2:17], v[200:203], v[232:235], v[2:17]
	global_load_lds_dwordx4 v159, s[100:101]
	v_mfma_f32_32x32x16_bf16 v[18:33], v[200:203], v[236:239], v[18:33]
	s_add_u32 s98, s98, 0x80
	s_addc_u32 s99, s99, 0
	s_add_u32 s100, s100, 0x80
	s_addc_u32 s101, s101, 0
	s_waitcnt vmcnt(0) lgkmcnt(0)
	s_barrier
	ds_read_b128 v[180:183], v148
	ds_read_b128 v[184:187], v148 offset:4096
	ds_read_b128 v[188:191], v152 offset:16384
	ds_read_b128 v[192:195], v152 offset:20480
	ds_read_b128 v[196:199], v149
	ds_read_b128 v[200:203], v149 offset:4096
	ds_read_b128 v[232:235], v153 offset:16384
	ds_read_b128 v[236:239], v153 offset:20480
	s_add_u32 m0, s32, 0x8000
	s_waitcnt lgkmcnt(5)
	v_mfma_f32_32x32x16_bf16 v[34:49], v[180:183], v[188:191], v[34:49]
	global_load_lds_dwordx4 v156, s[98:99]
	s_waitcnt lgkmcnt(4)
	v_mfma_f32_32x32x16_bf16 v[50:65], v[180:183], v[192:195], v[50:65]
	s_add_u32 m0, s32, 0x9000
	v_mfma_f32_32x32x16_bf16 v[2:17], v[184:187], v[188:191], v[2:17]
	global_load_lds_dwordx4 v157, s[98:99]
	v_mfma_f32_32x32x16_bf16 v[18:33], v[184:187], v[192:195], v[18:33]
	ds_read_b128 v[180:183], v150
	ds_read_b128 v[184:187], v150 offset:4096
	ds_read_b128 v[188:191], v154 offset:16384
	ds_read_b128 v[192:195], v154 offset:20480
	s_add_u32 m0, s32, 0xa000
	s_waitcnt lgkmcnt(5)
	v_mfma_f32_32x32x16_bf16 v[34:49], v[196:199], v[232:235], v[34:49]
	global_load_lds_dwordx4 v158, s[98:99]
	s_waitcnt lgkmcnt(4)
	v_mfma_f32_32x32x16_bf16 v[50:65], v[196:199], v[236:239], v[50:65]
	s_add_u32 m0, s32, 0xb000
	v_mfma_f32_32x32x16_bf16 v[2:17], v[200:203], v[232:235], v[2:17]
	global_load_lds_dwordx4 v159, s[98:99]
	v_mfma_f32_32x32x16_bf16 v[18:33], v[200:203], v[236:239], v[18:33]
	ds_read_b128 v[196:199], v151
	ds_read_b128 v[200:203], v151 offset:4096
	ds_read_b128 v[232:235], v155 offset:16384
	ds_read_b128 v[236:239], v155 offset:20480
	s_add_u32 m0, s32, 0xc000
	s_waitcnt lgkmcnt(5)
	v_mfma_f32_32x32x16_bf16 v[34:49], v[180:183], v[188:191], v[34:49]
	global_load_lds_dwordx4 v156, s[100:101]
	s_waitcnt lgkmcnt(4)
	v_mfma_f32_32x32x16_bf16 v[50:65], v[180:183], v[192:195], v[50:65]
	s_add_u32 m0, s32, 0xd000
	v_mfma_f32_32x32x16_bf16 v[2:17], v[184:187], v[188:191], v[2:17]
	global_load_lds_dwordx4 v157, s[100:101]
	v_mfma_f32_32x32x16_bf16 v[18:33], v[184:187], v[192:195], v[18:33]
	s_add_u32 m0, s32, 0xe000
	s_waitcnt lgkmcnt(1)
	v_mfma_f32_32x32x16_bf16 v[34:49], v[196:199], v[232:235], v[34:49]
	global_load_lds_dwordx4 v158, s[100:101]
	s_waitcnt lgkmcnt(0)
	v_mfma_f32_32x32x16_bf16 v[50:65], v[196:199], v[236:239], v[50:65]
	s_add_u32 m0, s32, 0xf000
	v_mfma_f32_32x32x16_bf16 v[2:17], v[200:203], v[232:235], v[2:17]
	global_load_lds_dwordx4 v159, s[100:101]
	v_mfma_f32_32x32x16_bf16 v[18:33], v[200:203], v[236:239], v[18:33]
	s_add_u32 s98, s98, 0x80
	s_addc_u32 s99, s99, 0
	s_add_u32 s100, s100, 0x80
	s_addc_u32 s101, s101, 0
	s_waitcnt vmcnt(0) lgkmcnt(0)
	s_barrier
	ds_read_b128 v[180:183], v148 offset:32768
	ds_read_b128 v[184:187], v148 offset:36864
	ds_read_b128 v[188:191], v152 offset:49152
	ds_read_b128 v[192:195], v152 offset:53248
	ds_read_b128 v[196:199], v149 offset:32768
	ds_read_b128 v[200:203], v149 offset:36864
	ds_read_b128 v[232:235], v153 offset:49152
	ds_read_b128 v[236:239], v153 offset:53248
	s_mov_b32 m0, s32
	s_waitcnt lgkmcnt(5)
	v_mfma_f32_32x32x16_bf16 v[34:49], v[180:183], v[188:191], v[34:49]
	global_load_lds_dwordx4 v156, s[98:99]
	s_waitcnt lgkmcnt(4)
	v_mfma_f32_32x32x16_bf16 v[50:65], v[180:183], v[192:195], v[50:65]
	s_add_u32 m0, s32, 0x1000
	v_mfma_f32_32x32x16_bf16 v[2:17], v[184:187], v[188:191], v[2:17]
	global_load_lds_dwordx4 v157, s[98:99]
	v_mfma_f32_32x32x16_bf16 v[18:33], v[184:187], v[192:195], v[18:33]
	ds_read_b128 v[180:183], v150 offset:32768
	ds_read_b128 v[184:187], v150 offset:36864
	ds_read_b128 v[188:191], v154 offset:49152
	ds_read_b128 v[192:195], v154 offset:53248
	s_add_u32 m0, s32, 0x2000
	s_waitcnt lgkmcnt(5)
	v_mfma_f32_32x32x16_bf16 v[34:49], v[196:199], v[232:235], v[34:49]
	global_load_lds_dwordx4 v158, s[98:99]
	s_waitcnt lgkmcnt(4)
	v_mfma_f32_32x32x16_bf16 v[50:65], v[196:199], v[236:239], v[50:65]
	s_add_u32 m0, s32, 0x3000
	v_mfma_f32_32x32x16_bf16 v[2:17], v[200:203], v[232:235], v[2:17]
	global_load_lds_dwordx4 v159, s[98:99]
	v_mfma_f32_32x32x16_bf16 v[18:33], v[200:203], v[236:239], v[18:33]
	ds_read_b128 v[196:199], v151 offset:32768
	ds_read_b128 v[200:203], v151 offset:36864
	ds_read_b128 v[232:235], v155 offset:49152
	ds_read_b128 v[236:239], v155 offset:53248
	s_add_u32 m0, s32, 0x4000
	s_waitcnt lgkmcnt(5)
	v_mfma_f32_32x32x16_bf16 v[34:49], v[180:183], v[188:191], v[34:49]
	global_load_lds_dwordx4 v156, s[100:101]
	s_waitcnt lgkmcnt(4)
	v_mfma_f32_32x32x16_bf16 v[50:65], v[180:183], v[192:195], v[50:65]
	s_add_u32 m0, s32, 0x5000
	v_mfma_f32_32x32x16_bf16 v[2:17], v[184:187], v[188:191], v[2:17]
	global_load_lds_dwordx4 v157, s[100:101]
	v_mfma_f32_32x32x16_bf16 v[18:33], v[184:187], v[192:195], v[18:33]
	s_add_u32 m0, s32, 0x6000
	s_waitcnt lgkmcnt(1)
	v_mfma_f32_32x32x16_bf16 v[34:49], v[196:199], v[232:235], v[34:49]
	global_load_lds_dwordx4 v158, s[100:101]
	s_waitcnt lgkmcnt(0)
	v_mfma_f32_32x32x16_bf16 v[50:65], v[196:199], v[236:239], v[50:65]
	s_add_u32 m0, s32, 0x7000
	v_mfma_f32_32x32x16_bf16 v[2:17], v[200:203], v[232:235], v[2:17]
	global_load_lds_dwordx4 v159, s[100:101]
	v_mfma_f32_32x32x16_bf16 v[18:33], v[200:203], v[236:239], v[18:33]
	s_add_u32 s98, s98, 0x80
	s_addc_u32 s99, s99, 0
	s_add_u32 s100, s100, 0x80
	s_addc_u32 s101, s101, 0
	s_waitcnt vmcnt(0) lgkmcnt(0)
	s_barrier
	ds_read_b128 v[180:183], v148
	ds_read_b128 v[184:187], v148 offset:4096
	ds_read_b128 v[188:191], v152 offset:16384
	ds_read_b128 v[192:195], v152 offset:20480
	ds_read_b128 v[196:199], v149
	ds_read_b128 v[200:203], v149 offset:4096
	ds_read_b128 v[232:235], v153 offset:16384
	ds_read_b128 v[236:239], v153 offset:20480
	s_add_u32 m0, s32, 0x8000
	s_waitcnt lgkmcnt(5)
	v_mfma_f32_32x32x16_bf16 v[34:49], v[180:183], v[188:191], v[34:49]
	global_load_lds_dwordx4 v156, s[98:99]
	s_waitcnt lgkmcnt(4)
	v_mfma_f32_32x32x16_bf16 v[50:65], v[180:183], v[192:195], v[50:65]
	s_add_u32 m0, s32, 0x9000
	v_mfma_f32_32x32x16_bf16 v[2:17], v[184:187], v[188:191], v[2:17]
	global_load_lds_dwordx4 v157, s[98:99]
	v_mfma_f32_32x32x16_bf16 v[18:33], v[184:187], v[192:195], v[18:33]
	ds_read_b128 v[180:183], v150
	ds_read_b128 v[184:187], v150 offset:4096
	ds_read_b128 v[188:191], v154 offset:16384
	ds_read_b128 v[192:195], v154 offset:20480
	s_add_u32 m0, s32, 0xa000
	s_waitcnt lgkmcnt(5)
	v_mfma_f32_32x32x16_bf16 v[34:49], v[196:199], v[232:235], v[34:49]
	global_load_lds_dwordx4 v158, s[98:99]
	s_waitcnt lgkmcnt(4)
	v_mfma_f32_32x32x16_bf16 v[50:65], v[196:199], v[236:239], v[50:65]
	s_add_u32 m0, s32, 0xb000
	v_mfma_f32_32x32x16_bf16 v[2:17], v[200:203], v[232:235], v[2:17]
	global_load_lds_dwordx4 v159, s[98:99]
	v_mfma_f32_32x32x16_bf16 v[18:33], v[200:203], v[236:239], v[18:33]
	ds_read_b128 v[196:199], v151
	ds_read_b128 v[200:203], v151 offset:4096
	ds_read_b128 v[232:235], v155 offset:16384
	ds_read_b128 v[236:239], v155 offset:20480
	s_add_u32 m0, s32, 0xc000
	s_waitcnt lgkmcnt(5)
	v_mfma_f32_32x32x16_bf16 v[34:49], v[180:183], v[188:191], v[34:49]
	global_load_lds_dwordx4 v156, s[100:101]
	s_waitcnt lgkmcnt(4)
	v_mfma_f32_32x32x16_bf16 v[50:65], v[180:183], v[192:195], v[50:65]
	s_add_u32 m0, s32, 0xd000
	v_mfma_f32_32x32x16_bf16 v[2:17], v[184:187], v[188:191], v[2:17]
	global_load_lds_dwordx4 v157, s[100:101]
	v_mfma_f32_32x32x16_bf16 v[18:33], v[184:187], v[192:195], v[18:33]
	s_add_u32 m0, s32, 0xe000
	s_waitcnt lgkmcnt(1)
	v_mfma_f32_32x32x16_bf16 v[34:49], v[196:199], v[232:235], v[34:49]
	global_load_lds_dwordx4 v158, s[100:101]
	s_waitcnt lgkmcnt(0)
	v_mfma_f32_32x32x16_bf16 v[50:65], v[196:199], v[236:239], v[50:65]
	s_add_u32 m0, s32, 0xf000
	v_mfma_f32_32x32x16_bf16 v[2:17], v[200:203], v[232:235], v[2:17]
	global_load_lds_dwordx4 v159, s[100:101]
	v_mfma_f32_32x32x16_bf16 v[18:33], v[200:203], v[236:239], v[18:33]
	s_add_u32 s98, s98, 0x80
	s_addc_u32 s99, s99, 0
	s_add_u32 s100, s100, 0x80
	s_addc_u32 s101, s101, 0
	s_waitcnt vmcnt(0) lgkmcnt(0)
	s_barrier
	ds_read_b128 v[180:183], v148 offset:32768
	ds_read_b128 v[184:187], v148 offset:36864
	ds_read_b128 v[188:191], v152 offset:49152
	ds_read_b128 v[192:195], v152 offset:53248
	ds_read_b128 v[196:199], v149 offset:32768
	ds_read_b128 v[200:203], v149 offset:36864
	ds_read_b128 v[232:235], v153 offset:49152
	ds_read_b128 v[236:239], v153 offset:53248
	s_mov_b32 m0, s32
	s_waitcnt lgkmcnt(5)
	v_mfma_f32_32x32x16_bf16 v[34:49], v[180:183], v[188:191], v[34:49]
	global_load_lds_dwordx4 v156, s[98:99]
	s_waitcnt lgkmcnt(4)
	v_mfma_f32_32x32x16_bf16 v[50:65], v[180:183], v[192:195], v[50:65]
	s_add_u32 m0, s32, 0x1000
	v_mfma_f32_32x32x16_bf16 v[2:17], v[184:187], v[188:191], v[2:17]
	global_load_lds_dwordx4 v157, s[98:99]
	v_mfma_f32_32x32x16_bf16 v[18:33], v[184:187], v[192:195], v[18:33]
	ds_read_b128 v[180:183], v150 offset:32768
	ds_read_b128 v[184:187], v150 offset:36864
	ds_read_b128 v[188:191], v154 offset:49152
	ds_read_b128 v[192:195], v154 offset:53248
	s_add_u32 m0, s32, 0x2000
	s_waitcnt lgkmcnt(5)
	v_mfma_f32_32x32x16_bf16 v[34:49], v[196:199], v[232:235], v[34:49]
	global_load_lds_dwordx4 v158, s[98:99]
	s_waitcnt lgkmcnt(4)
	v_mfma_f32_32x32x16_bf16 v[50:65], v[196:199], v[236:239], v[50:65]
	s_add_u32 m0, s32, 0x3000
	v_mfma_f32_32x32x16_bf16 v[2:17], v[200:203], v[232:235], v[2:17]
	global_load_lds_dwordx4 v159, s[98:99]
	v_mfma_f32_32x32x16_bf16 v[18:33], v[200:203], v[236:239], v[18:33]
	ds_read_b128 v[196:199], v151 offset:32768
	ds_read_b128 v[200:203], v151 offset:36864
	ds_read_b128 v[232:235], v155 offset:49152
	ds_read_b128 v[236:239], v155 offset:53248
	s_add_u32 m0, s32, 0x4000
	s_waitcnt lgkmcnt(5)
	v_mfma_f32_32x32x16_bf16 v[34:49], v[180:183], v[188:191], v[34:49]
	global_load_lds_dwordx4 v156, s[100:101]
	s_waitcnt lgkmcnt(4)
	v_mfma_f32_32x32x16_bf16 v[50:65], v[180:183], v[192:195], v[50:65]
	s_add_u32 m0, s32, 0x5000
	v_mfma_f32_32x32x16_bf16 v[2:17], v[184:187], v[188:191], v[2:17]
	global_load_lds_dwordx4 v157, s[100:101]
	v_mfma_f32_32x32x16_bf16 v[18:33], v[184:187], v[192:195], v[18:33]
	s_add_u32 m0, s32, 0x6000
	s_waitcnt lgkmcnt(1)
	v_mfma_f32_32x32x16_bf16 v[34:49], v[196:199], v[232:235], v[34:49]
	global_load_lds_dwordx4 v158, s[100:101]
	s_waitcnt lgkmcnt(0)
	v_mfma_f32_32x32x16_bf16 v[50:65], v[196:199], v[236:239], v[50:65]
	s_add_u32 m0, s32, 0x7000
	v_mfma_f32_32x32x16_bf16 v[2:17], v[200:203], v[232:235], v[2:17]
	global_load_lds_dwordx4 v159, s[100:101]
	v_mfma_f32_32x32x16_bf16 v[18:33], v[200:203], v[236:239], v[18:33]
	s_add_u32 s98, s98, 0x80
	s_addc_u32 s99, s99, 0
	s_add_u32 s100, s100, 0x80
	s_addc_u32 s101, s101, 0
	s_waitcnt vmcnt(0) lgkmcnt(0)
	s_barrier
	ds_read_b128 v[180:183], v148
	ds_read_b128 v[184:187], v148 offset:4096
	ds_read_b128 v[188:191], v152 offset:16384
	ds_read_b128 v[192:195], v152 offset:20480
	ds_read_b128 v[196:199], v149
	ds_read_b128 v[200:203], v149 offset:4096
	ds_read_b128 v[232:235], v153 offset:16384
	ds_read_b128 v[236:239], v153 offset:20480
	s_add_u32 m0, s32, 0x8000
	s_waitcnt lgkmcnt(5)
	v_mfma_f32_32x32x16_bf16 v[34:49], v[180:183], v[188:191], v[34:49]
	global_load_lds_dwordx4 v156, s[98:99]
	s_waitcnt lgkmcnt(4)
	v_mfma_f32_32x32x16_bf16 v[50:65], v[180:183], v[192:195], v[50:65]
	s_add_u32 m0, s32, 0x9000
	v_mfma_f32_32x32x16_bf16 v[2:17], v[184:187], v[188:191], v[2:17]
	global_load_lds_dwordx4 v157, s[98:99]
	v_mfma_f32_32x32x16_bf16 v[18:33], v[184:187], v[192:195], v[18:33]
	ds_read_b128 v[180:183], v150
	ds_read_b128 v[184:187], v150 offset:4096
	ds_read_b128 v[188:191], v154 offset:16384
	ds_read_b128 v[192:195], v154 offset:20480
	s_add_u32 m0, s32, 0xa000
	s_waitcnt lgkmcnt(5)
	v_mfma_f32_32x32x16_bf16 v[34:49], v[196:199], v[232:235], v[34:49]
	global_load_lds_dwordx4 v158, s[98:99]
	s_waitcnt lgkmcnt(4)
	v_mfma_f32_32x32x16_bf16 v[50:65], v[196:199], v[236:239], v[50:65]
	s_add_u32 m0, s32, 0xb000
	v_mfma_f32_32x32x16_bf16 v[2:17], v[200:203], v[232:235], v[2:17]
	global_load_lds_dwordx4 v159, s[98:99]
	v_mfma_f32_32x32x16_bf16 v[18:33], v[200:203], v[236:239], v[18:33]
	ds_read_b128 v[196:199], v151
	ds_read_b128 v[200:203], v151 offset:4096
	ds_read_b128 v[232:235], v155 offset:16384
	ds_read_b128 v[236:239], v155 offset:20480
	s_add_u32 m0, s32, 0xc000
	s_waitcnt lgkmcnt(5)
	v_mfma_f32_32x32x16_bf16 v[34:49], v[180:183], v[188:191], v[34:49]
	global_load_lds_dwordx4 v156, s[100:101]
	s_waitcnt lgkmcnt(4)
	v_mfma_f32_32x32x16_bf16 v[50:65], v[180:183], v[192:195], v[50:65]
	s_add_u32 m0, s32, 0xd000
	v_mfma_f32_32x32x16_bf16 v[2:17], v[184:187], v[188:191], v[2:17]
	global_load_lds_dwordx4 v157, s[100:101]
	v_mfma_f32_32x32x16_bf16 v[18:33], v[184:187], v[192:195], v[18:33]
	s_add_u32 m0, s32, 0xe000
	s_waitcnt lgkmcnt(1)
	v_mfma_f32_32x32x16_bf16 v[34:49], v[196:199], v[232:235], v[34:49]
	global_load_lds_dwordx4 v158, s[100:101]
	s_waitcnt lgkmcnt(0)
	v_mfma_f32_32x32x16_bf16 v[50:65], v[196:199], v[236:239], v[50:65]
	s_add_u32 m0, s32, 0xf000
	v_mfma_f32_32x32x16_bf16 v[2:17], v[200:203], v[232:235], v[2:17]
	global_load_lds_dwordx4 v159, s[100:101]
	v_mfma_f32_32x32x16_bf16 v[18:33], v[200:203], v[236:239], v[18:33]
	s_add_u32 s98, s98, 0x80
	s_addc_u32 s99, s99, 0
	s_add_u32 s100, s100, 0x80
	s_addc_u32 s101, s101, 0
	s_waitcnt vmcnt(0) lgkmcnt(0)
	s_barrier
	ds_read_b128 v[180:183], v148 offset:32768
	ds_read_b128 v[184:187], v148 offset:36864
	ds_read_b128 v[188:191], v152 offset:49152
	ds_read_b128 v[192:195], v152 offset:53248
	ds_read_b128 v[196:199], v149 offset:32768
	ds_read_b128 v[200:203], v149 offset:36864
	ds_read_b128 v[232:235], v153 offset:49152
	ds_read_b128 v[236:239], v153 offset:53248
	s_mov_b32 m0, s32
	s_waitcnt lgkmcnt(5)
	v_mfma_f32_32x32x16_bf16 v[34:49], v[180:183], v[188:191], v[34:49]
	global_load_lds_dwordx4 v156, s[98:99]
	s_waitcnt lgkmcnt(4)
	v_mfma_f32_32x32x16_bf16 v[50:65], v[180:183], v[192:195], v[50:65]
	s_add_u32 m0, s32, 0x1000
	v_mfma_f32_32x32x16_bf16 v[2:17], v[184:187], v[188:191], v[2:17]
	global_load_lds_dwordx4 v157, s[98:99]
	v_mfma_f32_32x32x16_bf16 v[18:33], v[184:187], v[192:195], v[18:33]
	ds_read_b128 v[180:183], v150 offset:32768
	ds_read_b128 v[184:187], v150 offset:36864
	ds_read_b128 v[188:191], v154 offset:49152
	ds_read_b128 v[192:195], v154 offset:53248
	s_add_u32 m0, s32, 0x2000
	s_waitcnt lgkmcnt(5)
	v_mfma_f32_32x32x16_bf16 v[34:49], v[196:199], v[232:235], v[34:49]
	global_load_lds_dwordx4 v158, s[98:99]
	s_waitcnt lgkmcnt(4)
	v_mfma_f32_32x32x16_bf16 v[50:65], v[196:199], v[236:239], v[50:65]
	s_add_u32 m0, s32, 0x3000
	v_mfma_f32_32x32x16_bf16 v[2:17], v[200:203], v[232:235], v[2:17]
	global_load_lds_dwordx4 v159, s[98:99]
	v_mfma_f32_32x32x16_bf16 v[18:33], v[200:203], v[236:239], v[18:33]
	ds_read_b128 v[196:199], v151 offset:32768
	ds_read_b128 v[200:203], v151 offset:36864
	ds_read_b128 v[232:235], v155 offset:49152
	ds_read_b128 v[236:239], v155 offset:53248
	s_add_u32 m0, s32, 0x4000
	s_waitcnt lgkmcnt(5)
	v_mfma_f32_32x32x16_bf16 v[34:49], v[180:183], v[188:191], v[34:49]
	global_load_lds_dwordx4 v156, s[100:101]
	s_waitcnt lgkmcnt(4)
	v_mfma_f32_32x32x16_bf16 v[50:65], v[180:183], v[192:195], v[50:65]
	s_add_u32 m0, s32, 0x5000
	v_mfma_f32_32x32x16_bf16 v[2:17], v[184:187], v[188:191], v[2:17]
	global_load_lds_dwordx4 v157, s[100:101]
	v_mfma_f32_32x32x16_bf16 v[18:33], v[184:187], v[192:195], v[18:33]
	s_add_u32 m0, s32, 0x6000
	s_waitcnt lgkmcnt(1)
	v_mfma_f32_32x32x16_bf16 v[34:49], v[196:199], v[232:235], v[34:49]
	global_load_lds_dwordx4 v158, s[100:101]
	s_waitcnt lgkmcnt(0)
	v_mfma_f32_32x32x16_bf16 v[50:65], v[196:199], v[236:239], v[50:65]
	s_add_u32 m0, s32, 0x7000
	v_mfma_f32_32x32x16_bf16 v[2:17], v[200:203], v[232:235], v[2:17]
	global_load_lds_dwordx4 v159, s[100:101]
	v_mfma_f32_32x32x16_bf16 v[18:33], v[200:203], v[236:239], v[18:33]
	s_add_u32 s98, s98, 0x80
	s_addc_u32 s99, s99, 0
	s_add_u32 s100, s100, 0x80
	s_addc_u32 s101, s101, 0
	s_waitcnt vmcnt(0) lgkmcnt(0)
	s_barrier
	ds_read_b128 v[180:183], v148
	ds_read_b128 v[184:187], v148 offset:4096
	ds_read_b128 v[188:191], v152 offset:16384
	ds_read_b128 v[192:195], v152 offset:20480
	ds_read_b128 v[196:199], v149
	ds_read_b128 v[200:203], v149 offset:4096
	ds_read_b128 v[232:235], v153 offset:16384
	ds_read_b128 v[236:239], v153 offset:20480
	s_add_u32 m0, s32, 0x8000
	s_waitcnt lgkmcnt(5)
	v_mfma_f32_32x32x16_bf16 v[34:49], v[180:183], v[188:191], v[34:49]
	global_load_lds_dwordx4 v156, s[98:99]
	s_waitcnt lgkmcnt(4)
	v_mfma_f32_32x32x16_bf16 v[50:65], v[180:183], v[192:195], v[50:65]
	s_add_u32 m0, s32, 0x9000
	v_mfma_f32_32x32x16_bf16 v[2:17], v[184:187], v[188:191], v[2:17]
	global_load_lds_dwordx4 v157, s[98:99]
	v_mfma_f32_32x32x16_bf16 v[18:33], v[184:187], v[192:195], v[18:33]
	ds_read_b128 v[180:183], v150
	ds_read_b128 v[184:187], v150 offset:4096
	ds_read_b128 v[188:191], v154 offset:16384
	ds_read_b128 v[192:195], v154 offset:20480
	s_add_u32 m0, s32, 0xa000
	s_waitcnt lgkmcnt(5)
	v_mfma_f32_32x32x16_bf16 v[34:49], v[196:199], v[232:235], v[34:49]
	global_load_lds_dwordx4 v158, s[98:99]
	s_waitcnt lgkmcnt(4)
	v_mfma_f32_32x32x16_bf16 v[50:65], v[196:199], v[236:239], v[50:65]
	s_add_u32 m0, s32, 0xb000
	v_mfma_f32_32x32x16_bf16 v[2:17], v[200:203], v[232:235], v[2:17]
	global_load_lds_dwordx4 v159, s[98:99]
	v_mfma_f32_32x32x16_bf16 v[18:33], v[200:203], v[236:239], v[18:33]
	ds_read_b128 v[196:199], v151
	ds_read_b128 v[200:203], v151 offset:4096
	ds_read_b128 v[232:235], v155 offset:16384
	ds_read_b128 v[236:239], v155 offset:20480
	s_add_u32 m0, s32, 0xc000
	s_waitcnt lgkmcnt(5)
	v_mfma_f32_32x32x16_bf16 v[34:49], v[180:183], v[188:191], v[34:49]
	global_load_lds_dwordx4 v156, s[100:101]
	s_waitcnt lgkmcnt(4)
	v_mfma_f32_32x32x16_bf16 v[50:65], v[180:183], v[192:195], v[50:65]
	s_add_u32 m0, s32, 0xd000
	v_mfma_f32_32x32x16_bf16 v[2:17], v[184:187], v[188:191], v[2:17]
	global_load_lds_dwordx4 v157, s[100:101]
	v_mfma_f32_32x32x16_bf16 v[18:33], v[184:187], v[192:195], v[18:33]
	s_add_u32 m0, s32, 0xe000
	s_waitcnt lgkmcnt(1)
	v_mfma_f32_32x32x16_bf16 v[34:49], v[196:199], v[232:235], v[34:49]
	global_load_lds_dwordx4 v158, s[100:101]
	s_waitcnt lgkmcnt(0)
	v_mfma_f32_32x32x16_bf16 v[50:65], v[196:199], v[236:239], v[50:65]
	s_add_u32 m0, s32, 0xf000
	v_mfma_f32_32x32x16_bf16 v[2:17], v[200:203], v[232:235], v[2:17]
	global_load_lds_dwordx4 v159, s[100:101]
	v_mfma_f32_32x32x16_bf16 v[18:33], v[200:203], v[236:239], v[18:33]
	s_add_u32 s98, s98, 0x80
	s_addc_u32 s99, s99, 0
	s_add_u32 s100, s100, 0x80
	s_addc_u32 s101, s101, 0
	s_waitcnt vmcnt(0) lgkmcnt(0)
	s_barrier
	ds_read_b128 v[180:183], v148 offset:32768
	ds_read_b128 v[184:187], v148 offset:36864
	ds_read_b128 v[188:191], v152 offset:49152
	ds_read_b128 v[192:195], v152 offset:53248
	ds_read_b128 v[196:199], v149 offset:32768
	ds_read_b128 v[200:203], v149 offset:36864
	ds_read_b128 v[232:235], v153 offset:49152
	ds_read_b128 v[236:239], v153 offset:53248
	s_mov_b32 m0, s32
	s_waitcnt lgkmcnt(5)
	v_mfma_f32_32x32x16_bf16 v[34:49], v[180:183], v[188:191], v[34:49]
	global_load_lds_dwordx4 v156, s[98:99]
	s_waitcnt lgkmcnt(4)
	v_mfma_f32_32x32x16_bf16 v[50:65], v[180:183], v[192:195], v[50:65]
	s_add_u32 m0, s32, 0x1000
	v_mfma_f32_32x32x16_bf16 v[2:17], v[184:187], v[188:191], v[2:17]
	global_load_lds_dwordx4 v157, s[98:99]
	v_mfma_f32_32x32x16_bf16 v[18:33], v[184:187], v[192:195], v[18:33]
	ds_read_b128 v[180:183], v150 offset:32768
	ds_read_b128 v[184:187], v150 offset:36864
	ds_read_b128 v[188:191], v154 offset:49152
	ds_read_b128 v[192:195], v154 offset:53248
	s_add_u32 m0, s32, 0x2000
	s_waitcnt lgkmcnt(5)
	v_mfma_f32_32x32x16_bf16 v[34:49], v[196:199], v[232:235], v[34:49]
	global_load_lds_dwordx4 v158, s[98:99]
	s_waitcnt lgkmcnt(4)
	v_mfma_f32_32x32x16_bf16 v[50:65], v[196:199], v[236:239], v[50:65]
	s_add_u32 m0, s32, 0x3000
	v_mfma_f32_32x32x16_bf16 v[2:17], v[200:203], v[232:235], v[2:17]
	global_load_lds_dwordx4 v159, s[98:99]
	v_mfma_f32_32x32x16_bf16 v[18:33], v[200:203], v[236:239], v[18:33]
	ds_read_b128 v[196:199], v151 offset:32768
	ds_read_b128 v[200:203], v151 offset:36864
	ds_read_b128 v[232:235], v155 offset:49152
	ds_read_b128 v[236:239], v155 offset:53248
	s_add_u32 m0, s32, 0x4000
	s_waitcnt lgkmcnt(5)
	v_mfma_f32_32x32x16_bf16 v[34:49], v[180:183], v[188:191], v[34:49]
	global_load_lds_dwordx4 v156, s[100:101]
	s_waitcnt lgkmcnt(4)
	v_mfma_f32_32x32x16_bf16 v[50:65], v[180:183], v[192:195], v[50:65]
	s_add_u32 m0, s32, 0x5000
	v_mfma_f32_32x32x16_bf16 v[2:17], v[184:187], v[188:191], v[2:17]
	global_load_lds_dwordx4 v157, s[100:101]
	v_mfma_f32_32x32x16_bf16 v[18:33], v[184:187], v[192:195], v[18:33]
	s_add_u32 m0, s32, 0x6000
	s_waitcnt lgkmcnt(1)
	v_mfma_f32_32x32x16_bf16 v[34:49], v[196:199], v[232:235], v[34:49]
	global_load_lds_dwordx4 v158, s[100:101]
	s_waitcnt lgkmcnt(0)
	v_mfma_f32_32x32x16_bf16 v[50:65], v[196:199], v[236:239], v[50:65]
	s_add_u32 m0, s32, 0x7000
	v_mfma_f32_32x32x16_bf16 v[2:17], v[200:203], v[232:235], v[2:17]
	global_load_lds_dwordx4 v159, s[100:101]
	v_mfma_f32_32x32x16_bf16 v[18:33], v[200:203], v[236:239], v[18:33]
	s_add_u32 s98, s98, 0x80
	s_addc_u32 s99, s99, 0
	s_add_u32 s100, s100, 0x80
	s_addc_u32 s101, s101, 0
	s_waitcnt vmcnt(0) lgkmcnt(0)
	s_barrier
	ds_read_b128 v[180:183], v148
	ds_read_b128 v[184:187], v148 offset:4096
	ds_read_b128 v[188:191], v152 offset:16384
	ds_read_b128 v[192:195], v152 offset:20480
	ds_read_b128 v[196:199], v149
	ds_read_b128 v[200:203], v149 offset:4096
	ds_read_b128 v[232:235], v153 offset:16384
	ds_read_b128 v[236:239], v153 offset:20480
	s_add_u32 m0, s32, 0x8000
	s_waitcnt lgkmcnt(5)
	v_mfma_f32_32x32x16_bf16 v[34:49], v[180:183], v[188:191], v[34:49]
	global_load_lds_dwordx4 v156, s[98:99]
	s_waitcnt lgkmcnt(4)
	v_mfma_f32_32x32x16_bf16 v[50:65], v[180:183], v[192:195], v[50:65]
	s_add_u32 m0, s32, 0x9000
	v_mfma_f32_32x32x16_bf16 v[2:17], v[184:187], v[188:191], v[2:17]
	global_load_lds_dwordx4 v157, s[98:99]
	v_mfma_f32_32x32x16_bf16 v[18:33], v[184:187], v[192:195], v[18:33]
	ds_read_b128 v[180:183], v150
	ds_read_b128 v[184:187], v150 offset:4096
	ds_read_b128 v[188:191], v154 offset:16384
	ds_read_b128 v[192:195], v154 offset:20480
	s_add_u32 m0, s32, 0xa000
	s_waitcnt lgkmcnt(5)
	v_mfma_f32_32x32x16_bf16 v[34:49], v[196:199], v[232:235], v[34:49]
	global_load_lds_dwordx4 v158, s[98:99]
	s_waitcnt lgkmcnt(4)
	v_mfma_f32_32x32x16_bf16 v[50:65], v[196:199], v[236:239], v[50:65]
	s_add_u32 m0, s32, 0xb000
	v_mfma_f32_32x32x16_bf16 v[2:17], v[200:203], v[232:235], v[2:17]
	global_load_lds_dwordx4 v159, s[98:99]
	v_mfma_f32_32x32x16_bf16 v[18:33], v[200:203], v[236:239], v[18:33]
	ds_read_b128 v[196:199], v151
	ds_read_b128 v[200:203], v151 offset:4096
	ds_read_b128 v[232:235], v155 offset:16384
	ds_read_b128 v[236:239], v155 offset:20480
	s_add_u32 m0, s32, 0xc000
	s_waitcnt lgkmcnt(5)
	v_mfma_f32_32x32x16_bf16 v[34:49], v[180:183], v[188:191], v[34:49]
	global_load_lds_dwordx4 v156, s[100:101]
	s_waitcnt lgkmcnt(4)
	v_mfma_f32_32x32x16_bf16 v[50:65], v[180:183], v[192:195], v[50:65]
	s_add_u32 m0, s32, 0xd000
	v_mfma_f32_32x32x16_bf16 v[2:17], v[184:187], v[188:191], v[2:17]
	global_load_lds_dwordx4 v157, s[100:101]
	v_mfma_f32_32x32x16_bf16 v[18:33], v[184:187], v[192:195], v[18:33]
	s_add_u32 m0, s32, 0xe000
	s_waitcnt lgkmcnt(1)
	v_mfma_f32_32x32x16_bf16 v[34:49], v[196:199], v[232:235], v[34:49]
	global_load_lds_dwordx4 v158, s[100:101]
	s_waitcnt lgkmcnt(0)
	v_mfma_f32_32x32x16_bf16 v[50:65], v[196:199], v[236:239], v[50:65]
	s_add_u32 m0, s32, 0xf000
	v_mfma_f32_32x32x16_bf16 v[2:17], v[200:203], v[232:235], v[2:17]
	global_load_lds_dwordx4 v159, s[100:101]
	v_mfma_f32_32x32x16_bf16 v[18:33], v[200:203], v[236:239], v[18:33]
	s_add_u32 s98, s98, 0x80
	s_addc_u32 s99, s99, 0
	s_add_u32 s100, s100, 0x80
	s_addc_u32 s101, s101, 0
	s_waitcnt vmcnt(0) lgkmcnt(0)
	s_barrier
	ds_read_b128 v[180:183], v148 offset:32768
	ds_read_b128 v[184:187], v148 offset:36864
	ds_read_b128 v[188:191], v152 offset:49152
	ds_read_b128 v[192:195], v152 offset:53248
	ds_read_b128 v[196:199], v149 offset:32768
	ds_read_b128 v[200:203], v149 offset:36864
	ds_read_b128 v[232:235], v153 offset:49152
	ds_read_b128 v[236:239], v153 offset:53248
	s_mov_b32 m0, s32
	s_waitcnt lgkmcnt(5)
	v_mfma_f32_32x32x16_bf16 v[34:49], v[180:183], v[188:191], v[34:49]
	global_load_lds_dwordx4 v156, s[98:99]
	s_waitcnt lgkmcnt(4)
	v_mfma_f32_32x32x16_bf16 v[50:65], v[180:183], v[192:195], v[50:65]
	s_add_u32 m0, s32, 0x1000
	v_mfma_f32_32x32x16_bf16 v[2:17], v[184:187], v[188:191], v[2:17]
	global_load_lds_dwordx4 v157, s[98:99]
	v_mfma_f32_32x32x16_bf16 v[18:33], v[184:187], v[192:195], v[18:33]
	ds_read_b128 v[180:183], v150 offset:32768
	ds_read_b128 v[184:187], v150 offset:36864
	ds_read_b128 v[188:191], v154 offset:49152
	ds_read_b128 v[192:195], v154 offset:53248
	s_add_u32 m0, s32, 0x2000
	s_waitcnt lgkmcnt(5)
	v_mfma_f32_32x32x16_bf16 v[34:49], v[196:199], v[232:235], v[34:49]
	global_load_lds_dwordx4 v158, s[98:99]
	s_waitcnt lgkmcnt(4)
	v_mfma_f32_32x32x16_bf16 v[50:65], v[196:199], v[236:239], v[50:65]
	s_add_u32 m0, s32, 0x3000
	v_mfma_f32_32x32x16_bf16 v[2:17], v[200:203], v[232:235], v[2:17]
	global_load_lds_dwordx4 v159, s[98:99]
	v_mfma_f32_32x32x16_bf16 v[18:33], v[200:203], v[236:239], v[18:33]
	ds_read_b128 v[196:199], v151 offset:32768
	ds_read_b128 v[200:203], v151 offset:36864
	ds_read_b128 v[232:235], v155 offset:49152
	ds_read_b128 v[236:239], v155 offset:53248
	s_add_u32 m0, s32, 0x4000
	s_waitcnt lgkmcnt(5)
	v_mfma_f32_32x32x16_bf16 v[34:49], v[180:183], v[188:191], v[34:49]
	global_load_lds_dwordx4 v156, s[100:101]
	s_waitcnt lgkmcnt(4)
	v_mfma_f32_32x32x16_bf16 v[50:65], v[180:183], v[192:195], v[50:65]
	s_add_u32 m0, s32, 0x5000
	v_mfma_f32_32x32x16_bf16 v[2:17], v[184:187], v[188:191], v[2:17]
	global_load_lds_dwordx4 v157, s[100:101]
	v_mfma_f32_32x32x16_bf16 v[18:33], v[184:187], v[192:195], v[18:33]
	s_add_u32 m0, s32, 0x6000
	s_waitcnt lgkmcnt(1)
	v_mfma_f32_32x32x16_bf16 v[34:49], v[196:199], v[232:235], v[34:49]
	global_load_lds_dwordx4 v158, s[100:101]
	s_waitcnt lgkmcnt(0)
	v_mfma_f32_32x32x16_bf16 v[50:65], v[196:199], v[236:239], v[50:65]
	s_add_u32 m0, s32, 0x7000
	v_mfma_f32_32x32x16_bf16 v[2:17], v[200:203], v[232:235], v[2:17]
	global_load_lds_dwordx4 v159, s[100:101]
	v_mfma_f32_32x32x16_bf16 v[18:33], v[200:203], v[236:239], v[18:33]
	s_add_u32 s98, s98, 0x80
	s_addc_u32 s99, s99, 0
	s_add_u32 s100, s100, 0x80
	s_addc_u32 s101, s101, 0
	s_waitcnt vmcnt(0) lgkmcnt(0)
	s_barrier
	ds_read_b128 v[180:183], v148
	ds_read_b128 v[184:187], v148 offset:4096
	ds_read_b128 v[188:191], v152 offset:16384
	ds_read_b128 v[192:195], v152 offset:20480
	ds_read_b128 v[196:199], v149
	ds_read_b128 v[200:203], v149 offset:4096
	ds_read_b128 v[232:235], v153 offset:16384
	ds_read_b128 v[236:239], v153 offset:20480
	s_add_u32 m0, s32, 0x8000
	s_waitcnt lgkmcnt(5)
	v_mfma_f32_32x32x16_bf16 v[34:49], v[180:183], v[188:191], v[34:49]
	global_load_lds_dwordx4 v156, s[98:99]
	s_waitcnt lgkmcnt(4)
	v_mfma_f32_32x32x16_bf16 v[50:65], v[180:183], v[192:195], v[50:65]
	s_add_u32 m0, s32, 0x9000
	v_mfma_f32_32x32x16_bf16 v[2:17], v[184:187], v[188:191], v[2:17]
	global_load_lds_dwordx4 v157, s[98:99]
	v_mfma_f32_32x32x16_bf16 v[18:33], v[184:187], v[192:195], v[18:33]
	ds_read_b128 v[180:183], v150
	ds_read_b128 v[184:187], v150 offset:4096
	ds_read_b128 v[188:191], v154 offset:16384
	ds_read_b128 v[192:195], v154 offset:20480
	s_add_u32 m0, s32, 0xa000
	s_waitcnt lgkmcnt(5)
	v_mfma_f32_32x32x16_bf16 v[34:49], v[196:199], v[232:235], v[34:49]
	global_load_lds_dwordx4 v158, s[98:99]
	s_waitcnt lgkmcnt(4)
	v_mfma_f32_32x32x16_bf16 v[50:65], v[196:199], v[236:239], v[50:65]
	s_add_u32 m0, s32, 0xb000
	v_mfma_f32_32x32x16_bf16 v[2:17], v[200:203], v[232:235], v[2:17]
	global_load_lds_dwordx4 v159, s[98:99]
	v_mfma_f32_32x32x16_bf16 v[18:33], v[200:203], v[236:239], v[18:33]
	ds_read_b128 v[196:199], v151
	ds_read_b128 v[200:203], v151 offset:4096
	ds_read_b128 v[232:235], v155 offset:16384
	ds_read_b128 v[236:239], v155 offset:20480
	s_add_u32 m0, s32, 0xc000
	s_waitcnt lgkmcnt(5)
	v_mfma_f32_32x32x16_bf16 v[34:49], v[180:183], v[188:191], v[34:49]
	global_load_lds_dwordx4 v156, s[100:101]
	s_waitcnt lgkmcnt(4)
	v_mfma_f32_32x32x16_bf16 v[50:65], v[180:183], v[192:195], v[50:65]
	s_add_u32 m0, s32, 0xd000
	v_mfma_f32_32x32x16_bf16 v[2:17], v[184:187], v[188:191], v[2:17]
	global_load_lds_dwordx4 v157, s[100:101]
	v_mfma_f32_32x32x16_bf16 v[18:33], v[184:187], v[192:195], v[18:33]
	s_add_u32 m0, s32, 0xe000
	s_waitcnt lgkmcnt(1)
	v_mfma_f32_32x32x16_bf16 v[34:49], v[196:199], v[232:235], v[34:49]
	global_load_lds_dwordx4 v158, s[100:101]
	s_waitcnt lgkmcnt(0)
	v_mfma_f32_32x32x16_bf16 v[50:65], v[196:199], v[236:239], v[50:65]
	s_add_u32 m0, s32, 0xf000
	v_mfma_f32_32x32x16_bf16 v[2:17], v[200:203], v[232:235], v[2:17]
	global_load_lds_dwordx4 v159, s[100:101]
	v_mfma_f32_32x32x16_bf16 v[18:33], v[200:203], v[236:239], v[18:33]
	s_add_u32 s98, s98, 0x80
	s_addc_u32 s99, s99, 0
	s_add_u32 s100, s100, 0x80
	s_addc_u32 s101, s101, 0
	s_waitcnt vmcnt(0) lgkmcnt(0)
	s_barrier
	ds_read_b128 v[180:183], v148 offset:32768
	ds_read_b128 v[184:187], v148 offset:36864
	ds_read_b128 v[188:191], v152 offset:49152
	ds_read_b128 v[192:195], v152 offset:53248
	ds_read_b128 v[196:199], v149 offset:32768
	ds_read_b128 v[200:203], v149 offset:36864
	ds_read_b128 v[232:235], v153 offset:49152
	ds_read_b128 v[236:239], v153 offset:53248
	s_waitcnt lgkmcnt(5)
	v_mfma_f32_32x32x16_bf16 v[34:49], v[180:183], v[188:191], v[34:49]
	s_waitcnt lgkmcnt(4)
	v_mfma_f32_32x32x16_bf16 v[50:65], v[180:183], v[192:195], v[50:65]
	v_mfma_f32_32x32x16_bf16 v[2:17], v[184:187], v[188:191], v[2:17]
	v_mfma_f32_32x32x16_bf16 v[18:33], v[184:187], v[192:195], v[18:33]
	ds_read_b128 v[180:183], v150 offset:32768
	ds_read_b128 v[184:187], v150 offset:36864
	ds_read_b128 v[188:191], v154 offset:49152
	ds_read_b128 v[192:195], v154 offset:53248
	s_waitcnt lgkmcnt(5)
	v_mfma_f32_32x32x16_bf16 v[34:49], v[196:199], v[232:235], v[34:49]
	s_waitcnt lgkmcnt(4)
	v_mfma_f32_32x32x16_bf16 v[50:65], v[196:199], v[236:239], v[50:65]
	v_mfma_f32_32x32x16_bf16 v[2:17], v[200:203], v[232:235], v[2:17]
	v_mfma_f32_32x32x16_bf16 v[18:33], v[200:203], v[236:239], v[18:33]
	ds_read_b128 v[196:199], v151 offset:32768
	ds_read_b128 v[200:203], v151 offset:36864
	ds_read_b128 v[232:235], v155 offset:49152
	ds_read_b128 v[236:239], v155 offset:53248
	s_waitcnt lgkmcnt(5)
	v_mfma_f32_32x32x16_bf16 v[34:49], v[180:183], v[188:191], v[34:49]
	s_waitcnt lgkmcnt(4)
	v_mfma_f32_32x32x16_bf16 v[50:65], v[180:183], v[192:195], v[50:65]
	v_mfma_f32_32x32x16_bf16 v[2:17], v[184:187], v[188:191], v[2:17]
	v_mfma_f32_32x32x16_bf16 v[18:33], v[184:187], v[192:195], v[18:33]
	s_waitcnt lgkmcnt(1)
	v_mfma_f32_32x32x16_bf16 v[34:49], v[196:199], v[232:235], v[34:49]
	s_waitcnt lgkmcnt(0)
	v_mfma_f32_32x32x16_bf16 v[50:65], v[196:199], v[236:239], v[50:65]
	v_mfma_f32_32x32x16_bf16 v[2:17], v[200:203], v[232:235], v[2:17]
	v_mfma_f32_32x32x16_bf16 v[18:33], v[200:203], v[236:239], v[18:33]
	s_barrier
	s_nop 8
	ds_write2_b32 v100, v34, v50 offset1:32
	ds_write2_b32 v100, v35, v51 offset0:132 offset1:164
	v_add_u32_e32 v34, 0x400, v100
	ds_write2_b32 v34, v36, v52 offset0:8 offset1:40
	ds_write2_b32 v34, v37, v53 offset0:140 offset1:172
	v_add_u32_e32 v34, 0x1000, v100
	ds_write2_b32 v34, v38, v54 offset0:32 offset1:64
	ds_write2_b32 v34, v39, v55 offset0:164 offset1:196
	v_add_u32_e32 v34, 0x1400, v100
	ds_write2_b32 v34, v40, v56 offset0:40 offset1:72
	ds_write2_b32 v34, v41, v57 offset0:172 offset1:204
	v_add_u32_e32 v34, 0x2000, v100
	ds_write2_b32 v34, v42, v58 offset0:64 offset1:96
	ds_write2_b32 v34, v43, v59 offset0:196 offset1:228
	v_add_u32_e32 v34, 0x2400, v100
	ds_write2_b32 v34, v44, v60 offset0:72 offset1:104
	ds_write2_b32 v34, v45, v61 offset0:204 offset1:236
	v_add_u32_e32 v34, 0x3000, v100
	ds_write2_b32 v34, v46, v62 offset0:96 offset1:128
	v_add_u32_e32 v34, 0x3200, v100
	ds_write2_b32 v34, v47, v63 offset0:100 offset1:132
	v_add_u32_e32 v34, 0x3400, v100
	ds_write2_b32 v34, v48, v64 offset0:104 offset1:136
	v_add_u32_e32 v34, 0x3600, v100
	ds_write2_b32 v34, v49, v65 offset0:108 offset1:140
	v_add_u32_e32 v34, 0x4000, v100
	ds_write2_b32 v34, v2, v18 offset0:128 offset1:160
	v_add_u32_e32 v2, 0x4400, v100
	ds_write2_b32 v2, v3, v19 offset0:4 offset1:36
	ds_write2_b32 v2, v4, v20 offset0:136 offset1:168
	v_add_u32_e32 v2, 0x4800, v100
	ds_write2_b32 v2, v5, v21 offset0:12 offset1:44
	v_add_u32_e32 v2, 0x5000, v100
	ds_write2_b32 v2, v6, v22 offset0:160 offset1:192
	v_add_u32_e32 v2, 0x5400, v100
	ds_write2_b32 v2, v7, v23 offset0:36 offset1:68
	ds_write2_b32 v2, v8, v24 offset0:168 offset1:200
	v_add_u32_e32 v2, 0x5800, v100
	ds_write2_b32 v2, v9, v25 offset0:44 offset1:76
	v_add_u32_e32 v2, 0x6000, v100
	ds_write2_b32 v2, v10, v26 offset0:192 offset1:224
	v_add_u32_e32 v2, 0x6400, v100
	ds_write2_b32 v2, v11, v27 offset0:68 offset1:100
	ds_write2_b32 v2, v12, v28 offset0:200 offset1:232
	v_add_u32_e32 v2, 0x6800, v100
	ds_write2_b32 v2, v13, v29 offset0:76 offset1:108
	v_add_u32_e32 v2, 0x7200, v100
	ds_write2_b32 v2, v14, v30 offset0:96 offset1:128
	v_add_u32_e32 v2, 0x7400, v100
	ds_write2_b32 v2, v15, v31 offset0:100 offset1:132
	v_add_u32_e32 v2, 0x7600, v100
	ds_write2_b32 v2, v16, v32 offset0:104 offset1:136
	v_add_u32_e32 v2, 0x7800, v100
	s_cmp_lt_i32 s0, 0
	ds_write2_b32 v2, v17, v33 offset0:108 offset1:140
	s_waitcnt lgkmcnt(0)
	s_barrier
	s_cbranch_scc1 .LBB0_886
	v_add_u32_e32 v2, s0, v105
	v_ashrrev_i32_e32 v3, 31, v2
	v_lshlrev_b64 v[2:3], 11, v[2:3]
	v_lshl_add_u32 v4, s28, 7, v105
	v_lshl_add_u64 v[2:3], s[8:9], 0, v[2:3]
	v_ashrrev_i32_e32 v5, 31, v4
	v_lshl_add_u64 v[2:3], v[2:3], 0, v[0:1]
	v_lshl_add_u64 v[240:241], v[2:3], 0, s[56:57]
	v_lshl_add_u64 v[242:243], v[240:241], 0, s[56:57]
	v_lshl_add_u64 v[244:245], v[242:243], 0, s[56:57]
	global_load_dwordx4 v[66:69], v[244:245], off
	global_load_dwordx4 v[70:73], v[242:243], off
	global_load_dwordx4 v[74:77], v[240:241], off
	global_load_dwordx4 v[78:81], v[2:3], off
	v_lshlrev_b64 v[2:3], 11, v[4:5]
	v_lshl_add_u64 v[2:3], s[62:63], 0, v[2:3]
	v_lshl_add_u64 v[2:3], v[2:3], 0, v[0:1]
	v_lshl_add_u64 v[246:247], v[2:3], 0, s[56:57]
	v_lshl_add_u64 v[248:249], v[246:247], 0, s[56:57]
	v_lshl_add_u64 v[250:251], v[248:249], 0, s[56:57]
	global_load_dwordx4 v[82:85], v[250:251], off
	global_load_dwordx4 v[86:89], v[248:249], off
	global_load_dwordx4 v[90:93], v[246:247], off
	global_load_dwordx4 v[94:97], v[2:3], off

	.amdhsa_kernel _Z4mega6Paramsii
		.amdhsa_group_segment_fixed_size 73744
		.amdhsa_private_segment_fixed_size 0
		.amdhsa_kernarg_size 504
		.amdhsa_user_sgpr_count 2
		.amdhsa_user_sgpr_dispatch_ptr 0
		.amdhsa_user_sgpr_queue_ptr 0
		.amdhsa_user_sgpr_kernarg_segment_ptr 1
		.amdhsa_user_sgpr_dispatch_id 0
		.amdhsa_user_sgpr_kernarg_preload_length 0
		.amdhsa_user_sgpr_kernarg_preload_offset 0
		.amdhsa_user_sgpr_private_segment_size 0
		.amdhsa_uses_dynamic_stack 0
		.amdhsa_enable_private_segment 0
		.amdhsa_system_sgpr_workgroup_id_x 1
		.amdhsa_system_sgpr_workgroup_id_y 0
		.amdhsa_system_sgpr_workgroup_id_z 0
		.amdhsa_system_sgpr_workgroup_info 0
		.amdhsa_system_vgpr_workitem_id 2
		.amdhsa_next_free_vgpr 256
		.amdhsa_next_free_sgpr 102
		.amdhsa_accum_offset 256
		.amdhsa_reserve_vcc 1
		.amdhsa_float_round_mode_32 0
		.amdhsa_float_round_mode_16_64 0
		.amdhsa_float_denorm_mode_32 3
		.amdhsa_float_denorm_mode_16_64 3
		.amdhsa_dx10_clamp 1
		.amdhsa_ieee_mode 1
		.amdhsa_fp16_overflow 0
		.amdhsa_tg_split 0
		.amdhsa_exception_fp_ieee_invalid_op 0
		.amdhsa_exception_fp_denorm_src 0
		.amdhsa_exception_fp_ieee_div_zero 0
		.amdhsa_exception_fp_ieee_overflow 0
		.amdhsa_exception_fp_ieee_underflow 0
		.amdhsa_exception_fp_ieee_inexact 0
		.amdhsa_exception_int_div_zero 0
	.end_amdhsa_kernel

amdhsa.kernels:
  - .agpr_count:     0
    .args:
      - .offset:         0
        .size:           240
        .value_kind:     by_value
      - .offset:         240
        .size:           4
        .value_kind:     by_value
      - .offset:         244
        .size:           4
        .value_kind:     by_value
      - .offset:         248
        .size:           4
        .value_kind:     hidden_block_count_x
      - .offset:         252
        .size:           4
        .value_kind:     hidden_block_count_y
      - .offset:         256
        .size:           4
        .value_kind:     hidden_block_count_z
      - .offset:         260
        .size:           2
        .value_kind:     hidden_group_size_x
      - .offset:         262
        .size:           2
        .value_kind:     hidden_group_size_y
      - .offset:         264
        .size:           2
        .value_kind:     hidden_group_size_z
      - .offset:         266
        .size:           2
        .value_kind:     hidden_remainder_x
      - .offset:         268
        .size:           2
        .value_kind:     hidden_remainder_y
      - .offset:         270
        .size:           2
        .value_kind:     hidden_remainder_z
      - .offset:         288
        .size:           8
        .value_kind:     hidden_global_offset_x
      - .offset:         296
        .size:           8
        .value_kind:     hidden_global_offset_y
      - .offset:         304
        .size:           8
        .value_kind:     hidden_global_offset_z
      - .offset:         312
        .size:           2
        .value_kind:     hidden_grid_dims
      - .offset:         336
        .size:           8
        .value_kind:     hidden_multigrid_sync_arg
    .group_segment_fixed_size: 73744
    .kernarg_segment_align: 8
    .kernarg_segment_size: 504
    .language:       OpenCL C
    .language_version:
      - 2
      - 0
    .max_flat_workgroup_size: 256
    .name:           _Z4mega6Paramsii
    .private_segment_fixed_size: 0
    .sgpr_count:     108
    .sgpr_spill_count: 221
    .symbol:         _Z4mega6Paramsii.kd
    .uniform_work_group_size: 1
    .uses_dynamic_stack: false
    .vgpr_count:     256
    .vgpr_spill_count: 0
    .wavefront_size: 64
